# kernel-argument scalar loads batched: one s_waitcnt per run of lazily fetched pointers instead of one per load (171 waits dropped)
# baseline (speedup 1.0000x reference)
;     int tid_ = threadIdx.x; asm volatile("" : "+v"(tid_));
;     const int tid = tid_, ntn = N / 64, ntiles = (K / 64) * ntn, nwg = wgn > 0 ? wgn : (int)gridDim.x - wg0;
;     if ((int)blockIdx.x < wg0 || (int)blockIdx.x >= wg0 + nwg) return;
;     const int r = tid >> 4, c4 = (tid & 15) * 4, n = tid >> 3, k8 = (tid & 7) * 8;
;     int t = (int)blockIdx.x - wg0;
;     f32x4 v0, v1; float g0 = 1.f, g1 = 1.f;
;     if (t < ntiles) { const int k0 = (t / ntn) * 64, n0 = (t % ntn) * 64;
;         v0 = *(const f32x4*)(src + (size_t)(k0 + r) * N + n0 + c4); v1 = *(const f32x4*)(src + (size_t)(k0 + r + 32) * N + n0 + c4);
;         if (gain) { g0 = gain[k0 + r]; g1 = gain[k0 + r + 32]; } }
.LBB0_5:
	s_or_b64 exec, exec, s[6:7]
	s_mov_b32 s6, s2
	s_mov_b32 s7, s46
	s_cmp_gt_i32 s2, -1
	s_cselect_b64 s[6:7], -1, 0
	s_cmp_lt_i32 s2, s46
	s_load_dwordx2 s[10:11], s[0:1], 48
	s_cselect_b64 s[8:9], -1, 0
	s_load_dwordx2 s[14:15], s[0:1], 40
	v_writelane_b32 v230, s8, 0
	s_and_b64 s[6:7], s[6:7], s[8:9]
	s_load_dwordx2 s[16:17], s[0:1], 0xe0
	s_waitcnt lgkmcnt(0)
	v_cndmask_b32_e64 v1, 0, 1, s[6:7]
	v_writelane_b32 v230, s9, 1
	v_cmp_ne_u32_e64 s[8:9], 1, v1
	v_mov_b32_e32 v15, v166
	s_andn2_b64 vcc, exec, s[6:7]
	v_writelane_b32 v230, s8, 2
	s_nop 1
	v_writelane_b32 v230, s9, 3
	s_cbranch_vccnz .LBB0_39
	s_cmpk_gt_u32 s2, 0x43f
	s_cbranch_scc1 .LBB0_16
	s_mul_i32 s6, s2, 0xf0f1
	s_lshr_b32 s7, s6, 22
	s_lshr_b32 s6, s6, 16
	v_ashrrev_i32_e32 v1, 4, v15
	v_lshlrev_b32_e32 v2, 2, v15
	s_and_b32 s6, s6, 0xffc0
	s_mulk_i32 s7, 0x44
	v_and_b32_e32 v6, 60, v2
	s_sub_i32 s7, s2, s7
	v_add_u32_e32 v16, s6, v1
	s_movk_i32 s6, 0x4400
	v_mov_b64_e32 v[2:3], s[10:11]
	v_mad_i64_i32 v[4:5], s[8:9], v16, s6, v[2:3]
	s_lshl_b32 s7, s7, 8
	s_and_b32 s8, s7, 0x3ff00
	s_mov_b32 s9, 0
	v_lshl_add_u64 v[4:5], v[4:5], 0, s[8:9]
	v_mov_b32_e32 v11, 0
	v_lshlrev_b32_e32 v10, 2, v6
	v_lshl_add_u64 v[12:13], v[4:5], 0, v[10:11]
	v_add_u32_e32 v4, 32, v16
	v_mad_i64_i32 v[2:3], s[18:19], v4, s6, v[2:3]
	v_lshl_add_u64 v[2:3], v[2:3], 0, s[8:9]
	v_lshl_add_u64 v[18:19], v[2:3], 0, v[10:11]
	global_load_dwordx4 v[2:5], v[12:13], off
	global_load_dwordx4 v[6:9], v[18:19], off
	s_cmp_lg_u64 s[14:15], 0
	v_mov_b32_e32 v12, 1.0
	s_cselect_b64 s[8:9], -1, 0
	s_cmp_eq_u64 s[14:15], 0
	v_mov_b32_e32 v14, 1.0
	s_cbranch_scc1 .LBB0_9
	v_ashrrev_i32_e32 v17, 31, v16
	v_lshl_add_u64 v[16:17], v[16:17], 2, s[14:15]
	global_load_dword v14, v[16:17], off
	global_load_dword v12, v[16:17], off offset:128

; __device__ __forceinline__ bf16_t f2bf(float f) { return (bf16_t)(pk2(f, 0.f) & 0xffffu); }
; #define KP(f) ((decltype(Params::f))karg_ptr<(int)offsetof(Params, f)>())
;     const int nwg_ = wgn > 0 ? wgn : (int)gridDim.x - wg0;
;     if ((int)blockIdx.x < wg0 || (int)blockIdx.x >= wg0 + nwg_) return;
;     const int gtid = ((int)blockIdx.x - wg0) * 512 + threadIdx.x, nth = nwg_ * 512;
;     { const float* wd = KP(w_decay2) + (size_t)l * 64 * 512; const float* wa = KP(w_a2) + (size_t)l * 64 * 512; const float* wg = KP(w_g2) + (size_t)l * 128 * 512;
;       bf16_t* LoraT = KP(LoraT);
;       for (int i = gtid; i < 1536 * 256; i += nth) { const int n = i >> 8, k = i & 255; float v = 0.f;
;         if (n < 512) { if (k < 64) v = wd[k * 512 + n]; }
;         else if (n < 1024) { if (k >= 64 && k < 128) v = wa[(k - 64) * 512 + (n - 512)]; }
;         else { if (k >= 128) v = wg[(k - 128) * 512 + (n - 1024)]; }
;         LoraT[i] = f2bf(v); } }
.LBB0_16:
	s_load_dwordx2 s[10:11], s[0:1], 0x48
	s_load_dwordx2 s[14:15], s[0:1], 0x58
	s_load_dwordx2 s[16:17], s[0:1], 0x60
	s_load_dwordx2 s[24:25], s[0:1], 0xe8
	s_waitcnt lgkmcnt(0)
	s_waitcnt vmcnt(2)
	v_lshl_add_u32 v2, s2, 9, v166
	s_mov_b32 s6, 0x60000
	s_lshl_b32 s8, s46, 9
	v_cmp_gt_i32_e32 vcc, s6, v2
	v_ashrrev_i32_e32 v3, 31, v2
	s_and_saveexec_b64 s[18:19], vcc
	s_cbranch_execz .LBB0_33
	s_movk_i32 s6, 0x7f
	v_mov_b32_e32 v1, 9
	v_mov_b32_e32 v4, 64
	s_ashr_i32 s9, s8, 31
	v_cmp_gt_u32_sdwa s[20:21], v166, s6 src0_sel:BYTE_0 src1_sel:DWORD
	v_lshlrev_b32_sdwa v1, v1, v166 dst_sel:DWORD dst_unused:UNUSED_PAD src0_sel:DWORD src1_sel:BYTE_0
	v_cmp_lt_u32_sdwa s[22:23], v166, v4 src0_sel:BYTE_0 src1_sel:DWORD
	v_lshl_add_u64 v[4:5], v[2:3], 1, s[24:25]
	s_lshl_b64 s[24:25], s[8:9], 1
	s_mov_b64 s[26:27], 0
	s_movk_i32 s6, 0x1ff
	s_movk_i32 s7, 0x3ff
	s_waitcnt vmcnt(1)
	v_mov_b32_e32 v7, 0
	s_mov_b32 s9, 0x5ffff
	v_mov_b32_e32 v8, v2
	s_branch .LBB0_20

; __device__ __forceinline__ bf16_t f2bf(float f) { return (bf16_t)(pk2(f, 0.f) & 0xffffu); }
; #define KP(f) ((decltype(Params::f))karg_ptr<(int)offsetof(Params, f)>())
;     ...
;     { const float* wp = KP(w_pool) + (size_t)l * 4 * 128 * 128; bf16_t* PoolT = KP(PoolT);
;       for (int i = gtid; i < 512 * 512; i += nth) { const int n = i >> 9, k = i & 511; const int g = n >> 7, d = n & 127; float v = 0.f;
;         if ((k >> 7) == g) v = wp[(g * 128 + (k & 127)) * 128 + d];
;         PoolT[i] = f2bf(v); } }
.LBB0_33:
	s_or_b64 exec, exec, s[18:19]
	s_load_dwordx2 s[10:11], s[0:1], 0x98
	s_load_dwordx2 s[16:17], s[0:1], 0xf0
	s_waitcnt lgkmcnt(0)
	s_mov_b32 s6, 0x40000
	v_cmp_gt_i32_e32 vcc, s6, v2
	s_and_saveexec_b64 s[14:15], vcc
	s_cbranch_execz .LBB0_38
	v_lshlrev_b32_e32 v1, 7, v166
	s_ashr_i32 s9, s8, 31
	v_lshl_add_u32 v1, s2, 16, v1
	s_lshl_b32 s6, s46, 16
	v_lshl_add_u64 v[4:5], v[2:3], 1, s[16:17]
	s_lshl_b64 s[16:17], s[8:9], 1
	s_mov_b64 s[18:19], 0
	s_waitcnt vmcnt(1)
	v_mov_b32_e32 v7, 0
	s_mov_b32 s7, 0x3ffff
	v_mov_b32_e32 v3, 14
	s_branch .LBB0_36

; __device__ __forceinline__ unsigned pk2(float lo, float hi) { unsigned r; asm volatile("v_cvt_pk_bf16_f32 %0, %1, %2" : "=v"(r) : "v"(lo), "v"(hi)); return r; }
; #define KP(f) ((decltype(Params::f))karg_ptr<(int)offsetof(Params, f)>())
; __device__ void phase_prologue(float* tile) {
;     ...
;     const float* x_prompt = KP(x_prompt); const float* x_sample = KP(x_sample); bf16_t* xb = KP(xb); float* ssq = KP(ssq);
;     const int lane = threadIdx.x & 63, gw = blockIdx.x * 8 + (threadIdx.x >> 6), nw = gridDim.x * 8;
;     for (int row = gw; row < T_ALL; row += nw) {
;         const float* xr = row < T_P ? x_prompt + (size_t)row * DM : x_sample + (size_t)(row - T_P) * DM;
;         float s = 0.f;
; #pragma unroll
;         for (int i = 0; i < 4; ++i) { const int c = i * 256 + lane * 4; const f32x4 v = *(const f32x4*)(xr + c);
;             s += (v[0] * v[0] + v[1] * v[1]) + (v[2] * v[2] + v[3] * v[3]);
;             u32x2 w; w.x = pk2(v[0], v[1]); w.y = pk2(v[2], v[3]); *(u32x2*)(xb + (size_t)row * DM + c) = w; }
; #pragma unroll
;         for (int o = 32; o >= 1; o >>= 1) s += __shfl_xor(s, o);
;         if (lane < 16) ssq[(size_t)row * 16 + lane] = lane == 0 ? s : 0.f;
;     }
.LBB0_39:
	s_load_dwordx2 s[10:11], s[0:1], 0
	s_load_dwordx2 s[14:15], s[0:1], 8
	s_load_dwordx2 s[18:19], s[0:1], 0x120
	s_load_dwordx2 s[8:9], s[0:1], 0x128
	s_waitcnt lgkmcnt(0)
	v_lshrrev_b32_e32 v1, 6, v166
	v_lshl_add_u32 v144, s2, 3, v1
	s_lshl_b32 s50, s46, 3
	s_movk_i32 s6, 0x4400
	v_ashrrev_i32_e32 v145, 31, v144
	v_and_b32_e32 v167, 63, v166
	v_mbcnt_lo_u32_b32 v168, -1, 0
	v_cmp_gt_i32_e64 s[6:7], s6, v144
	s_mov_b64 s[16:17], exec
	s_nop 0
	v_writelane_b32 v230, s6, 4
	s_nop 1
	v_writelane_b32 v230, s7, 5
	s_and_b64 s[6:7], s[16:17], s[6:7]
	s_mov_b64 exec, s[6:7]
	s_cbranch_execz .LBB0_46
	v_lshlrev_b32_e32 v2, 2, v167
	v_mov_b32_e32 v3, 0
	v_mbcnt_hi_u32_b32 v1, -1, v168
	v_lshl_add_u64 v[4:5], s[8:9], 0, v[2:3]
	s_waitcnt vmcnt(1)
	v_lshlrev_b32_e32 v6, 3, v167
	v_mov_b32_e32 v7, v3
	s_ashr_i32 s51, s50, 31
	v_lshlrev_b64 v[8:9], 12, v[144:145]
	v_lshlrev_b32_e32 v10, 2, v2
	v_and_b32_e32 v2, 64, v1
	v_cmp_gt_u32_e32 vcc, 16, v167
	v_cmp_eq_u32_e64 s[8:9], 0, v167
	v_lshl_add_u64 v[6:7], s[18:19], 0, v[6:7]
	v_lshl_add_u64 v[8:9], s[10:11], 0, v[8:9]
	s_lshl_b64 s[18:19], s[50:51], 12
	s_mov_b64 s[20:21], 0
	s_movk_i32 s6, 0x3fff
	v_mov_b32_e32 v11, v3
	v_add_u32_e32 v18, 64, v2
	v_xor_b32_e32 v19, 32, v1
	v_xor_b32_e32 v20, 16, v1
	v_xor_b32_e32 v21, 8, v1
	v_xor_b32_e32 v22, 4, v1
	v_xor_b32_e32 v23, 2, v1
	v_xor_b32_e32 v24, 1, v1
	s_movk_i32 s7, 0x43ff
	v_mov_b64_e32 v[12:13], v[144:145]
	s_branch .LBB0_42

; #define KP(f) ((decltype(Params::f))karg_ptr<(int)offsetof(Params, f)>())
;     __device__ bool next(int i, Unit& u) const {
;         const long L = (long)i * G + c; if (L >= nwg) return false;
;         int wgid = (int)L; { const int q = nwg / NXCD, r = nwg % NXCD, xcd = wgid % NXCD, off = wgid / NXCD; wgid = (xcd < r ? xcd * (q + 1) : r * (q + 1) + (xcd - r) * q) + off; }
;         const int nig = WGM * nN, gid = wgid / nig, fm = gid * WGM, gsz = (nM - fm) < WGM ? (nM - fm) : WGM;
;         u.pm = fm + ((wgid % nig) % gsz); u.pn = (wgid % nig) / gsz; return true;
; __device__ __forceinline__ void run_phase(int type, int l, unsigned char* shm) {
;     ...
;         pg8::Gemm g{KP(xb), KP(WinT), T_ALL, DIN, DM, DM, DM}; S.init(T_ALL, DIN, G, c);
;         EpiNormBf16<0> E{KP(z), DIN, KP(ssq)}; pg8::gemm_phase(lds, g, S, E);
.LBB0_110:
	s_mov_b32 s38, s46
	s_mov_b32 s39, s2
	s_load_dwordx2 s[10:11], s[0:1], 0x120
	s_load_dwordx2 s[12:13], s[0:1], 0xe0
	s_load_dwordx2 s[14:15], s[0:1], 0x130
	s_load_dwordx2 s[16:17], s[0:1], 0x128
	s_waitcnt lgkmcnt(0)
	s_waitcnt vmcnt(1)
	v_mov_b32_e32 v8, v166
	s_cmpk_gt_i32 s39, 0x483
	v_readfirstlane_b32 s40, v8
	s_cbranch_scc1 .LBB0_130
	s_ashr_i32 s41, s39, 31
	s_lshr_b32 s6, s41, 29
	s_add_i32 s7, s39, s6
	s_and_b32 s6, s7, -8
	s_sub_i32 s6, s39, s6
	s_cmp_gt_i32 s6, 3
	s_cbranch_scc0 .LBB0_113
	s_mul_i32 s8, s6, 0x90
	s_or_b32 s18, s8, 4
	s_ashr_i32 s8, s7, 3
	s_cbranch_execz .LBB0_114
	s_branch .LBB0_115

; #define KP(f) ((decltype(Params::f))karg_ptr<(int)offsetof(Params, f)>())
;     int tid_ = threadIdx.x; asm volatile("" : "+v"(tid_));
;     const int tid = tid_, ntn = N / 64, ntiles = (K / 64) * ntn, nwg = wgn > 0 ? wgn : (int)gridDim.x - wg0;
;     if ((int)blockIdx.x < wg0 || (int)blockIdx.x >= wg0 + nwg) return;
;     const int r = tid >> 4, c4 = (tid & 15) * 4, n = tid >> 3, k8 = (tid & 7) * 8;
;     int t = (int)blockIdx.x - wg0;
;     f32x4 v0, v1; float g0 = 1.f, g1 = 1.f;
;     if (t < ntiles) { const int k0 = (t / ntn) * 64, n0 = (t % ntn) * 64;
;         v0 = *(const f32x4*)(src + (size_t)(k0 + r) * N + n0 + c4); v1 = *(const f32x4*)(src + (size_t)(k0 + r + 32) * N + n0 + c4);
;         if (gain) { g0 = gain[k0 + r]; g1 = gain[k0 + r + 32]; } }
; __device__ __forceinline__ void run_phase(int type, int l, unsigned char* shm) {
;     ...
;         { const int w0 = (68 * 17) % G;
;           if (l == 1) transpose_convert(KP(w_ff2) + (size_t)DFF * DM, DFF, DM, nullptr, KP(Wff2T), (float*)shm, w0);
;           else { transpose_convert(KP(w_b_up), 512, DM, nullptr, KP(BupT), (float*)shm, w0);
.LBB0_130:
	s_abs_i32 s6, s38
	v_cvt_f32_u32_e32 v0, s6
	s_sub_i32 s7, 0, s6
	v_readlane_b32 s14, v230, 0
	s_load_dwordx2 s[10:11], s[0:1], 0xa8
	v_rcp_iflag_f32_e32 v0, v0
	v_readlane_b32 s15, v230, 1
	s_load_dwordx2 s[12:13], s[0:1], 0xf8
	s_waitcnt lgkmcnt(0)
	v_mov_b32_e32 v10, v166
	v_mul_f32_e32 v0, 0x4f7ffffe, v0
	v_cvt_u32_f32_e32 v0, v0
	s_nop 0
	v_readfirstlane_b32 s8, v0
	s_mul_i32 s7, s7, s8
	s_mul_hi_u32 s7, s8, s7
	s_add_i32 s8, s8, s7
	s_mul_hi_u32 s7, s8, 0x484
	s_mul_i32 s7, s7, s6
	s_sub_i32 s7, 0x484, s7
	s_sub_i32 s8, s7, s6
	s_cmp_ge_u32 s7, s6
	s_cselect_b32 s7, s8, s7
	s_sub_i32 s8, s7, s6
	s_cmp_ge_u32 s7, s6
	s_cselect_b32 s7, s8, s7
	s_sub_i32 s6, s46, s7
	s_cmp_ge_i32 s2, s7
	s_cselect_b64 s[8:9], -1, 0
	s_and_b64 s[14:15], s[8:9], s[14:15]
	v_cndmask_b32_e64 v0, 0, 1, s[14:15]
	v_cmp_ne_u32_e64 s[8:9], 1, v0
	s_andn2_b64 vcc, exec, s[14:15]
	s_cbranch_vccnz .LBB0_138
	s_sub_i32 s18, s2, s7
	s_cmpk_gt_i32 s18, 0x7f
	s_cbranch_scc1 .LBB0_138
	s_sext_i32_i16 s14, s18
	s_bfe_u32 s14, s14, 0x4001b
	s_add_i32 s14, s18, s14
	s_sext_i32_i16 s15, s14
	s_lshl_b32 s15, s15, 2
	v_ashrrev_i32_e32 v12, 4, v10
	v_lshlrev_b32_e32 v0, 2, v10
	s_andn2_b32 s15, s15, 63
	s_and_b32 s14, s14, 0xfff0
	v_and_b32_e32 v20, 60, v0
	s_sub_i32 s14, s18, s14
	v_add_u32_e32 v0, s15, v12
	s_sext_i32_i16 s14, s14
	v_ashrrev_i32_e32 v1, 31, v0
	s_lshl_b32 s14, s14, 6
	v_lshlrev_b64 v[0:1], 12, v[0:1]
	v_lshl_add_u64 v[0:1], s[10:11], 0, v[0:1]
	s_ashr_i32 s15, s14, 31
	v_lshl_add_u64 v[0:1], s[14:15], 2, v[0:1]
	v_mov_b32_e32 v9, 0
	v_lshlrev_b32_e32 v8, 2, v20
	v_lshl_add_u64 v[14:15], v[0:1], 0, v[8:9]
	s_mov_b32 s14, 0x20000
	v_add_co_u32_e32 v16, vcc, s14, v14
	v_ashrrev_i32_e32 v13, 3, v10
	s_nop 0
	v_addc_co_u32_e32 v17, vcc, 0, v15, vcc
	global_load_dwordx4 v[0:3], v[14:15], off
	global_load_dwordx4 v[4:7], v[16:17], off
	v_lshlrev_b32_e32 v10, 3, v10
	s_movk_i32 s14, 0x104
	v_and_b32_e32 v10, 56, v10
	v_mul_lo_u32 v15, v12, s14
	v_add3_u32 v14, 0, v8, v15
	v_add3_u32 v8, 0, v15, v8
	v_mul_u32_u24_e32 v15, 0x41, v10
	v_lshlrev_b32_e32 v11, 2, v13
	v_lshlrev_b32_e32 v16, 2, v15
	v_add3_u32 v15, 0, v11, v16
	v_add3_u32 v16, 0, v16, v11
	s_lshl_b32 s21, s18, 6
	s_lshl_b32 s19, s6, 6
	v_add_u32_e32 v17, 0x2080, v8
	v_add_u32_e32 v18, 0x2088, v8
	v_lshlrev_b32_e32 v8, 2, v20
	v_lshlrev_b32_e32 v10, 1, v10
	v_add_u32_e32 v19, 0x400, v16
	v_mov_b32_e32 v11, v9
	s_branch .LBB0_134

; #define KP(f) ((decltype(Params::f))karg_ptr<(int)offsetof(Params, f)>())
;     int tid_ = threadIdx.x; asm volatile("" : "+v"(tid_));
;     const int tid = tid_, ntn = N / 64, ntiles = (K / 64) * ntn, nwg = wgn > 0 ? wgn : (int)gridDim.x - wg0;
;     if ((int)blockIdx.x < wg0 || (int)blockIdx.x >= wg0 + nwg) return;
;     const int r = tid >> 4, c4 = (tid & 15) * 4, n = tid >> 3, k8 = (tid & 7) * 8;
;     int t = (int)blockIdx.x - wg0;
;     f32x4 v0, v1; float g0 = 1.f, g1 = 1.f;
;     if (t < ntiles) { const int k0 = (t / ntn) * 64, n0 = (t % ntn) * 64;
;         v0 = *(const f32x4*)(src + (size_t)(k0 + r) * N + n0 + c4); v1 = *(const f32x4*)(src + (size_t)(k0 + r + 32) * N + n0 + c4);
;         if (gain) { g0 = gain[k0 + r]; g1 = gain[k0 + r + 32]; } }
; __device__ __forceinline__ void run_phase(int type, int l, unsigned char* shm) {
;     ...
;                  transpose_convert(KP(w_a_up), 512, DM, nullptr, KP(AupT), (float*)shm, w0);
.LBB0_138:
	s_load_dwordx2 s[10:11], s[0:1], 0x90
	s_load_dwordx2 s[12:13], s[0:1], 0x100
	s_waitcnt lgkmcnt(0)
	v_mov_b32_e32 v10, v166
	s_and_b64 vcc, exec, s[8:9]
	s_cbranch_vccnz .LBB0_146
	s_sub_i32 s18, s2, s7
	s_cmpk_gt_i32 s18, 0x7f
	s_cbranch_scc1 .LBB0_146
	s_sext_i32_i16 s14, s18
	s_bfe_u32 s14, s14, 0x4001b
	s_add_i32 s14, s18, s14
	s_sext_i32_i16 s15, s14
	s_lshl_b32 s15, s15, 2
	v_ashrrev_i32_e32 v12, 4, v10
	s_waitcnt vmcnt(0)
	v_lshlrev_b32_e32 v0, 2, v10
	s_andn2_b32 s15, s15, 63
	s_and_b32 s14, s14, 0xfff0
	v_and_b32_e32 v20, 60, v0
	s_sub_i32 s14, s18, s14
	v_add_u32_e32 v0, s15, v12
	s_sext_i32_i16 s14, s14
	v_ashrrev_i32_e32 v1, 31, v0
	s_lshl_b32 s14, s14, 6
	v_lshlrev_b64 v[0:1], 12, v[0:1]
	v_lshl_add_u64 v[0:1], s[10:11], 0, v[0:1]
	s_ashr_i32 s15, s14, 31
	v_lshl_add_u64 v[0:1], s[14:15], 2, v[0:1]
	v_mov_b32_e32 v9, 0
	v_lshlrev_b32_e32 v8, 2, v20
	v_lshl_add_u64 v[14:15], v[0:1], 0, v[8:9]
	s_mov_b32 s14, 0x20000
	v_add_co_u32_e32 v16, vcc, s14, v14
	v_ashrrev_i32_e32 v13, 3, v10
	s_nop 0
	v_addc_co_u32_e32 v17, vcc, 0, v15, vcc
	global_load_dwordx4 v[0:3], v[14:15], off
	global_load_dwordx4 v[4:7], v[16:17], off
	v_lshlrev_b32_e32 v10, 3, v10
	s_movk_i32 s14, 0x104
	v_and_b32_e32 v10, 56, v10
	v_mul_lo_u32 v15, v12, s14
	v_add3_u32 v14, 0, v8, v15
	v_add3_u32 v8, 0, v15, v8
	v_mul_u32_u24_e32 v15, 0x41, v10
	v_lshlrev_b32_e32 v11, 2, v13
	v_lshlrev_b32_e32 v16, 2, v15
	v_add3_u32 v15, 0, v11, v16
	v_add3_u32 v16, 0, v16, v11
	s_lshl_b32 s21, s18, 6
	s_lshl_b32 s19, s6, 6
	v_add_u32_e32 v17, 0x2080, v8
	v_add_u32_e32 v18, 0x2088, v8
	v_lshlrev_b32_e32 v8, 2, v20
	v_lshlrev_b32_e32 v10, 1, v10
	v_add_u32_e32 v19, 0x400, v16
	v_mov_b32_e32 v11, v9
	s_branch .LBB0_142

; #define KP(f) ((decltype(Params::f))karg_ptr<(int)offsetof(Params, f)>())
;     int tid_ = threadIdx.x; asm volatile("" : "+v"(tid_));
;     const int tid = tid_, ntn = N / 64, ntiles = (K / 64) * ntn, nwg = wgn > 0 ? wgn : (int)gridDim.x - wg0;
;     if ((int)blockIdx.x < wg0 || (int)blockIdx.x >= wg0 + nwg) return;
;     const int r = tid >> 4, c4 = (tid & 15) * 4, n = tid >> 3, k8 = (tid & 7) * 8;
;     int t = (int)blockIdx.x - wg0;
;     f32x4 v0, v1; float g0 = 1.f, g1 = 1.f;
;     if (t < ntiles) { const int k0 = (t / ntn) * 64, n0 = (t % ntn) * 64;
;         v0 = *(const f32x4*)(src + (size_t)(k0 + r) * N + n0 + c4); v1 = *(const f32x4*)(src + (size_t)(k0 + r + 32) * N + n0 + c4);
;         if (gain) { g0 = gain[k0 + r]; g1 = gain[k0 + r + 32]; } }
; __device__ __forceinline__ void run_phase(int type, int l, unsigned char* shm) {
;     ...
;                  transpose_convert(KP(w_o), DM, DM, nullptr, KP(WoT), (float*)shm, w0);
.LBB0_146:
	s_load_dwordx2 s[10:11], s[0:1], 0xb0
	s_load_dwordx2 s[12:13], s[0:1], 0x108
	s_waitcnt lgkmcnt(0)
	v_mov_b32_e32 v10, v166
	s_and_b64 vcc, exec, s[8:9]
	s_cbranch_vccnz .LBB0_154
	s_sub_i32 s18, s2, s7
	s_cmpk_gt_i32 s18, 0xff
	s_cbranch_scc1 .LBB0_154
	s_sext_i32_i16 s14, s18
	s_bfe_u32 s14, s14, 0x4001b
	s_add_i32 s14, s18, s14
	s_sext_i32_i16 s15, s14
	s_lshl_b32 s15, s15, 2
	v_ashrrev_i32_e32 v12, 4, v10
	s_waitcnt vmcnt(0)
	v_lshlrev_b32_e32 v0, 2, v10
	s_andn2_b32 s15, s15, 63
	s_and_b32 s14, s14, 0xfff0
	v_and_b32_e32 v20, 60, v0
	s_sub_i32 s14, s18, s14
	v_add_u32_e32 v0, s15, v12
	s_sext_i32_i16 s14, s14
	v_ashrrev_i32_e32 v1, 31, v0
	s_lshl_b32 s14, s14, 6
	v_lshlrev_b64 v[0:1], 12, v[0:1]
	v_lshl_add_u64 v[0:1], s[10:11], 0, v[0:1]
	s_ashr_i32 s15, s14, 31
	v_lshl_add_u64 v[0:1], s[14:15], 2, v[0:1]
	v_mov_b32_e32 v9, 0
	v_lshlrev_b32_e32 v8, 2, v20
	v_lshl_add_u64 v[14:15], v[0:1], 0, v[8:9]
	s_mov_b32 s14, 0x20000
	v_add_co_u32_e32 v16, vcc, s14, v14
	v_ashrrev_i32_e32 v13, 3, v10
	s_nop 0
	v_addc_co_u32_e32 v17, vcc, 0, v15, vcc
	global_load_dwordx4 v[0:3], v[14:15], off
	global_load_dwordx4 v[4:7], v[16:17], off
	v_lshlrev_b32_e32 v10, 3, v10
	s_movk_i32 s14, 0x104
	v_and_b32_e32 v10, 56, v10
	v_mul_lo_u32 v15, v12, s14
	v_add3_u32 v14, 0, v8, v15
	v_add3_u32 v8, 0, v15, v8
	v_mul_u32_u24_e32 v15, 0x41, v10
	v_lshlrev_b32_e32 v11, 2, v13
	v_lshlrev_b32_e32 v16, 2, v15
	v_add3_u32 v15, 0, v11, v16
	v_add3_u32 v16, 0, v16, v11
	s_lshl_b32 s21, s18, 6
	s_lshl_b32 s19, s6, 6
	v_add_u32_e32 v17, 0x2080, v8
	v_add_u32_e32 v18, 0x2088, v8
	v_lshlrev_b32_e32 v8, 2, v20
	v_lshlrev_b32_e32 v10, 1, v10
	v_add_u32_e32 v19, 0x400, v16
	v_mov_b32_e32 v11, v9
	s_branch .LBB0_150

; #define KP(f) ((decltype(Params::f))karg_ptr<(int)offsetof(Params, f)>())
;     int tid_ = threadIdx.x; asm volatile("" : "+v"(tid_));
;     const int tid = tid_, ntn = N / 64, ntiles = (K / 64) * ntn, nwg = wgn > 0 ? wgn : (int)gridDim.x - wg0;
;     if ((int)blockIdx.x < wg0 || (int)blockIdx.x >= wg0 + nwg) return;
;     const int r = tid >> 4, c4 = (tid & 15) * 4, n = tid >> 3, k8 = (tid & 7) * 8;
;     int t = (int)blockIdx.x - wg0;
;     f32x4 v0, v1; float g0 = 1.f, g1 = 1.f;
;     if (t < ntiles) { const int k0 = (t / ntn) * 64, n0 = (t % ntn) * 64;
;         v0 = *(const f32x4*)(src + (size_t)(k0 + r) * N + n0 + c4); v1 = *(const f32x4*)(src + (size_t)(k0 + r + 32) * N + n0 + c4);
;         if (gain) { g0 = gain[k0 + r]; g1 = gain[k0 + r + 32]; } }
; __device__ __forceinline__ void run_phase(int type, int l, unsigned char* shm) {
;     ...
;                  transpose_convert(KP(w_ff1), DM, DFF, KP(norm2_g), KP(Wff1T), (float*)shm, w0); } }
.LBB0_154:
	s_load_dwordx2 s[10:11], s[0:1], 0xc0
	s_load_dwordx2 s[12:13], s[0:1], 0xb8
	s_load_dwordx2 s[14:15], s[0:1], 0x110
	s_waitcnt lgkmcnt(0)
	v_mov_b32_e32 v16, v166
	s_and_b64 vcc, exec, s[8:9]
	s_cbranch_vccnz .LBB0_165
	s_sub_i32 s7, s2, s7
	s_cmpk_gt_i32 s7, 0x3ff
	s_cbranch_scc1 .LBB0_165
	s_sext_i32_i16 s8, s7
	s_bfe_u32 s8, s8, 0x60019
	s_add_i32 s8, s7, s8
	s_sext_i32_i16 s9, s8
	v_ashrrev_i32_e32 v11, 4, v16
	s_andn2_b32 s9, s9, 63
	s_and_b32 s8, s8, 0xffc0
	s_sub_i32 s8, s7, s8
	v_add_u32_e32 v14, s9, v11
	s_waitcnt vmcnt(0)
	v_lshlrev_b32_e32 v0, 2, v16
	s_sext_i32_i16 s8, s8
	v_ashrrev_i32_e32 v15, 31, v14
	v_and_b32_e32 v2, 60, v0
	s_lshl_b32 s8, s8, 6
	v_lshlrev_b64 v[0:1], 14, v[14:15]
	v_lshl_add_u64 v[0:1], s[10:11], 0, v[0:1]
	s_ashr_i32 s9, s8, 31
	v_lshl_add_u64 v[0:1], s[8:9], 2, v[0:1]
	v_mov_b32_e32 v9, 0
	v_lshlrev_b32_e32 v8, 2, v2
	v_lshl_add_u64 v[12:13], v[0:1], 0, v[8:9]
	v_add_co_u32_e32 v18, vcc, 0x80000, v12
	s_cmp_lg_u64 s[12:13], 0
	s_nop 0
	v_addc_co_u32_e32 v19, vcc, 0, v13, vcc
	global_load_dwordx4 v[0:3], v[12:13], off
	global_load_dwordx4 v[4:7], v[18:19], off
	v_mov_b32_e32 v10, 1.0
	s_cselect_b64 s[8:9], -1, 0
	s_cmp_eq_u64 s[12:13], 0
	v_mov_b32_e32 v12, 1.0
	s_cbranch_scc1 .LBB0_158
	v_lshl_add_u64 v[14:15], v[14:15], 2, s[12:13]
	global_load_dword v12, v[14:15], off
	global_load_dword v10, v[14:15], off offset:128

; #define KP(f) ((decltype(Params::f))karg_ptr<(int)offsetof(Params, f)>())
; __device__ __forceinline__ void unpack8(const u32x4 w, f32x4& v0, f32x4& v1) { v0 = (f32x4){bflo(w.x), bfhi(w.x), bflo(w.y), bfhi(w.y)}; v1 = (f32x4){bflo(w.z), bfhi(w.z), bflo(w.w), bfhi(w.w)}; }
; __device__ __forceinline__ Tok tok_decode(int tok) { Tok r; if (tok < T_P) { r.is_s = 0; r.seq = tok >> 11; r.t = tok & 2047; } else { r.is_s = 1; r.seq = (tok - T_P) >> 3; r.t = (tok - T_P) & 7; } return r; }
; __device__ void phase_e1(int l) {
;     ...
;     const bf16_t* z = KP(z); bf16_t* pbuf = KP(xb);
;     bf16_t* Lb = KP(L);
;     const float* mu = KP(mu_shift) + (size_t)l * DSH;
;     const float* st_shift = KP(state_shift) + (size_t)l * NSB * DSH;
;     const float* st_pool = KP(state_pool) + (size_t)l * NSB * 15 * 512;
;     float* out = KP(out);
;     for (int it = gtid; it < T_ALL * 32; it += nth) {
;         const int tok = it >> 5, v = it & 31; const Tok tk = tok_decode(tok);
;         const int c = O_LORA + v * 8; const bf16_t* zr = z + (size_t)tok * DIN + c;
;         f32x4 x0, x1, p0, p1; unpack8(*(const u32x4*)zr, x0, x1);
;         if (tk.t > 0) unpack8(*(const u32x4*)(zr - DIN), p0, p1);
;         else if (tk.is_s) { const float* sp = st_shift + (size_t)tk.seq * DSH + c; p0 = *(const f32x4*)sp; p1 = *(const f32x4*)(sp + 4); }
;         else { p0 = (f32x4){0.f, 0.f, 0.f, 0.f}; p1 = p0; }
;         const f32x4 m0 = *(const f32x4*)(mu + c), m1 = *(const f32x4*)(mu + c + 4);
;         x0 = x0 + (p0 - x0) * m0; x1 = x1 + (p1 - x1) * m1;
.LBB0_219:
	s_load_dwordx2 s[58:59], s[0:1], 0x130
	s_load_dwordx2 s[62:63], s[0:1], 0x120
	s_load_dwordx2 s[12:13], s[0:1], 0x138
	s_load_dwordx2 s[8:9], s[0:1], 56
	s_load_dwordx2 s[10:11], s[0:1], 16
	s_load_dwordx2 s[60:61], s[0:1], 24
	s_load_dwordx2 s[56:57], s[0:1], 0xd8
	s_waitcnt lgkmcnt(0)
	v_lshl_add_u32 v34, s6, 9, v166
	s_mov_b32 s6, 0x88000
	s_lshl_b32 s52, s46, 9
	v_cmp_gt_i32_e32 vcc, s6, v34
	v_and_b32_e32 v169, 31, v166
	s_and_saveexec_b64 s[14:15], vcc
	s_cbranch_execz .LBB0_234
	s_waitcnt vmcnt(2)
	v_mov_b32_e32 v1, 0
	v_mov_b32_e32 v2, 0x1800
	v_lshlrev_b32_e32 v0, 4, v169
	v_lshl_or_b32 v2, v169, 5, v2
	v_mov_b32_e32 v3, v1
	v_lshl_add_u64 v[12:13], s[58:59], 0, v[0:1]
	v_lshl_add_u64 v[14:15], s[10:11], 0, v[2:3]
	v_lshl_add_u64 v[16:17], s[8:9], 0, v[2:3]
	v_cmp_lt_u32_e64 s[8:9], 7, v169
	v_cmp_lt_u32_e64 s[10:11], 15, v169
	v_lshl_add_u64 v[18:19], s[12:13], 0, v[0:1]
	s_mov_b64 s[16:17], 0
	s_movk_i32 s6, 0x3fff
	s_movk_i32 s7, 0x4000
	v_mov_b32_e32 v22, 0x7ff
	s_movk_i32 s24, 0x2200
	s_mov_b64 s[18:19], 0xc00
	s_movk_i32 s25, 0x1c00
	s_mov_b32 s26, 0x87fff
	v_mov_b32_e32 v23, v34
	s_branch .LBB0_222

; #define KP(f) ((decltype(Params::f))karg_ptr<(int)offsetof(Params, f)>())
; #define PG8_WAIT_V(n) asm volatile("s_waitcnt vmcnt(" #n ")" ::: "memory")
; #define PG8_BAR __builtin_amdgcn_s_barrier()
;     ...
;     const int tid = tid_, wid = __builtin_amdgcn_readfirstlane(tid >> 6), lane = tid & 63, wr = wid >> 2, wc = wid & 3, fr = lane & 15, fq = lane >> 4;
;     const int K = g.K, nt = K / BK, lda = g.lda, ldb = g.ldb;
;     unsigned voffA[2], voffB[2];
; #pragma unroll
;     for (int i = 0; i < 2; ++i) { int R, C; stage_rc(tid * 16 + i * 8192, R, C); const int Rb = Epi::PERM ? ((R & ~31) + perm32(R & 31)) : R;
;         voffA[i] = (unsigned)(R * lda + C) * 2u; voffB[i] = (unsigned)(Rb * ldb + C) * 2u; }
;     const size_t kstep = (size_t)(BK * 2);
;     const size_t hA = (size_t)HALF * lda * 2, hB = (size_t)HALF * ldb * 2;
;     const size_t tA = 2 * hA, tB = 2 * hB;
;     const unsigned ldsw = (unsigned)wid * 1024u;
;     const int aoff = lds_byte(wr * 64 + fr, fq * 8), boff = lds_byte(wc * 32 + fr, fq * 8);
;     ...
;     Unit cur, nxt; int ui = 0;
;     if (!S.next(0, cur)) return;
;     ...
;     f32x4 acc[2][2][4][2];
; #pragma unroll
;     for (int a = 0; a < 2; ++a)
; #pragma unroll
;         for (int b = 0; b < 2; ++b)
; #pragma unroll
;             for (int m = 0; m < 4; ++m)
; #pragma unroll
;                 for (int n = 0; n < 2; ++n) acc[a][b][m][n] = (f32x4){0.f, 0.f, 0.f, 0.f};
;     bf16x8 At[4][2], B0[2][2], B1[2][2];
;     const char* cA = (const char*)g.A + (size_t)cur.pm * tA; const char* cB = (const char*)g.Bt + (size_t)cur.pn * tB;
;     PG8_A_READY(cur);
;     PG8_STAGE(PG8_SB(0, 0), cB, voffB); PG8_STAGE(PG8_SA(0, 0), cA, voffA); PG8_STAGE(PG8_SB(0, 1), cB + hB, voffB); PG8_STAGE(PG8_SA(0, 1), cA + hA, voffA);
;     if (wr == 1) PG8_BAR;
;     PG8_WAIT_V(4); PG8_BAR;
;     PG8_STAGE(PG8_SB(1, 0), cB + kstep, voffB); PG8_STAGE(PG8_SA(1, 0), cA + kstep, voffA); PG8_STAGE(PG8_SB(1, 1), cB + hB + kstep, voffB);
;     PG8_WAIT_V(6); PG8_BAR;
; __device__ __forceinline__ void run_phase(int type, int l, unsigned char* shm) {
;     ...
;         { pg8::Gemm g{KP(L), KP(LoraT), T_ALL, 1536, 256, 256, 256}; S.init(T_ALL, 1536, G, c);
;           EpiLora E{KP(xb) + (size_t)T_ALL * 512, KP(sc_a), KP(sc_g)}; pg8::gemm_phase(lds, g, S, E); }
.LBB0_325:
	s_or_b64 exec, exec, s[8:9]
	s_mov_b32 s53, s2
	s_mov_b32 s51, s46
	s_waitcnt lgkmcnt(0)
	s_barrier
	s_load_dwordx2 s[10:11], s[0:1], 0x138
	s_load_dwordx2 s[12:13], s[0:1], 0xe8
	s_load_dwordx2 s[8:9], s[0:1], 0x120
	s_load_dwordx2 s[14:15], s[0:1], 0x140
	s_load_dwordx2 s[16:17], s[0:1], 0x148
	s_waitcnt lgkmcnt(0)
	v_mov_b32_e32 v8, v166
	s_cmpk_gt_i32 s53, 0x197
	v_readfirstlane_b32 s70, v8
	s_cbranch_scc1 .LBB0_337
	s_waitcnt vmcnt(2)
	v_lshlrev_b32_e32 v0, 4, v8
	v_add_u32_e32 v1, 0x2000, v0
	v_ashrrev_i32_e32 v2, 31, v1
	v_lshrrev_b32_e32 v2, 22, v2
	v_add_u32_e32 v2, v1, v2
	v_ashrrev_i32_e32 v2, 10, v2
	v_mul_i32_i24_e32 v3, 0x400, v2
	v_sub_u32_e32 v1, v1, v3
	v_lshrrev_b32_e32 v3, 4, v1
	v_bitop3_b32 v1, v3, v1, 32 bitop3:0x6c
	v_ashrrev_i32_e32 v3, 31, v1
	v_lshrrev_b32_e32 v3, 26, v3
	v_add_u32_e32 v3, v1, v3
	s_waitcnt vmcnt(1)
	v_lshlrev_b32_e32 v5, 3, v2
	v_ashrrev_i32_e32 v4, 6, v3
	v_and_b32_e32 v5, -16, v5
	v_and_b32_e32 v3, 0xc0, v3
	v_add_u32_e32 v5, v4, v5
	v_sub_u32_e32 v1, v1, v3
	v_mov_b32_e32 v3, 1
	v_and_b32_e32 v4, 3, v4
	s_mov_b32 s18, 0x7fffe0
	v_lshrrev_b32_e32 v6, 2, v5
	v_lshlrev_b32_e32 v7, 1, v5
	v_lshlrev_b32_e32 v2, 5, v2
	v_ashrrev_i16_sdwa v1, v3, sext(v1) dst_sel:DWORD dst_unused:UNUSED_PAD src0_sel:DWORD src1_sel:BYTE_0
	v_and_or_b32 v4, v5, s18, v4
	v_and_b32_e32 v6, 4, v6
	v_and_b32_e32 v7, 24, v7
	v_and_b32_e32 v2, 32, v2
	v_bfe_i32 v1, v1, 0, 16
	v_or3_b32 v4, v4, v6, v7
	v_add_lshl_u32 v1, v2, v1, 1
	v_lshl_add_u32 v128, v4, 9, v1
	v_lshl_add_u32 v130, v5, 9, v1
	v_bfe_i32 v1, v8, 27, 1
	v_lshrrev_b32_e32 v1, 22, v1
	v_add_u32_e32 v1, v0, v1
	v_and_b32_e32 v1, 0xfffffc00, v1
	v_sub_u32_e32 v0, v0, v1
	v_lshrrev_b32_e32 v1, 4, v0
	v_ashrrev_i32_e32 v4, 31, v8
	v_bitop3_b32 v0, v1, v0, 32 bitop3:0x6c
	v_lshrrev_b32_e32 v4, 26, v4
	v_ashrrev_i32_e32 v1, 31, v0
	v_add_u32_e32 v4, v8, v4
	v_lshrrev_b32_e32 v1, 26, v1
	v_ashrrev_i32_e32 v4, 6, v4
	v_add_u32_e32 v1, v0, v1
	v_lshlrev_b32_e32 v5, 3, v4
	v_ashrrev_i32_e32 v2, 6, v1
	v_and_b32_e32 v5, -16, v5
	v_add_u32_e32 v5, v2, v5
	v_and_b32_e32 v2, 3, v2
	s_ashr_i32 s72, s53, 31
	v_and_or_b32 v2, v5, s18, v2
	s_lshr_b32 s18, s72, 29
	s_add_i32 s18, s53, s18
	s_ashr_i32 s6, s70, 6
	s_ashr_i32 s19, s18, 3
	s_and_b32 s18, s18, -8
	s_ashr_i32 s7, s70, 8
	s_lshl_b32 s71, s6, 10
	s_sub_i32 s18, s53, s18
	s_cmp_lt_i32 s18, 0
	s_cselect_b32 s20, 52, 51
	s_mul_i32 s18, s20, s18
	s_add_i32 s18, s18, s19
	s_mul_hi_i32 s19, s18, 0x2aaaaaab
	v_and_b32_e32 v1, 0xc0, v1
	s_lshr_b32 s20, s19, 31
	s_ashr_i32 s19, s19, 3
	v_sub_u32_e32 v0, v0, v1
	s_add_i32 s19, s19, s20
	v_lshrrev_b32_e32 v6, 2, v5
	v_lshlrev_b32_e32 v7, 1, v5
	v_lshlrev_b32_e32 v4, 5, v4
	v_ashrrev_i16_sdwa v0, v3, sext(v0) dst_sel:DWORD dst_unused:UNUSED_PAD src0_sel:DWORD src1_sel:BYTE_0
	s_lshl_b32 s21, s19, 3
	v_and_b32_e32 v6, 4, v6
	v_and_b32_e32 v7, 24, v7
	v_and_b32_e32 v4, 32, v4
	v_bfe_i32 v0, v0, 0, 16
	s_sub_i32 s20, 0x44, s21
	v_or3_b32 v2, v2, v6, v7
	v_add_lshl_u32 v0, v4, v0, 1
	s_min_u32 s22, s20, 8
	s_mul_i32 s19, s19, 48
	v_lshl_add_u32 v132, v2, 9, v0
	s_sub_i32 s23, s18, s19
	v_cvt_f32_ubyte0_e32 v2, s22
	v_cvt_f32_i32_e32 v1, s23
	v_rcp_iflag_f32_e32 v3, v2
	v_lshl_add_u32 v134, v5, 9, v0
	s_ashr_i32 s18, s23, 30
	s_or_b32 s20, s18, 1
	v_mul_f32_e32 v0, v1, v3
	v_trunc_f32_e32 v0, v0
	v_fma_f32 v1, -v0, v2, v1
	v_cvt_i32_f32_e32 v0, v0
	v_cmp_ge_f32_e64 s[18:19], |v1|, v2
	s_and_b64 s[18:19], s[18:19], exec
	s_cselect_b32 s18, s20, 0
	v_readfirstlane_b32 s19, v0
	s_add_i32 s20, s19, s18
	s_mul_i32 s18, s20, s22
	s_sub_i32 s18, s23, s18
	s_sext_i32_i8 s18, s18
	s_add_i32 s36, s21, s18
	s_ashr_i32 s37, s36, 31
	s_bfe_i64 s[22:23], s[20:21], 0x80000
	s_lshl_b64 s[18:19], s[36:37], 17
	s_lshl_b64 s[22:23], s[22:23], 17
	s_add_u32 s38, s12, s22
	s_addc_u32 s39, s13, s23
	s_add_i32 s37, s71, 0
	s_add_i32 m0, s37, 0x10000
	v_mov_b32_e32 v137, 0
	global_load_lds_dwordx4 v132, s[38:39]
	s_add_i32 m0, s37, 0x12000
	s_add_u32 s40, s10, s18
	global_load_lds_dwordx4 v128, s[38:39]
	s_addc_u32 s41, s11, s19
	s_mov_b32 m0, s37
	s_add_i32 s73, s37, 0x2000
	global_load_lds_dwordx4 v134, s[40:41]
	s_mov_b32 m0, s73
	s_add_u32 s18, s38, 0x10000
	global_load_lds_dwordx4 v130, s[40:41]
	s_addc_u32 s19, s39, 0
	s_add_i32 m0, s37, 0x14000
	v_mov_b32_e32 v133, v137
	global_load_lds_dwordx4 v132, s[18:19]
	s_add_i32 m0, s37, 0x16000
	v_mov_b32_e32 v129, v137
	global_load_lds_dwordx4 v128, s[18:19]
	s_add_u32 s18, s40, 0x10000
	s_addc_u32 s19, s41, 0
	s_add_i32 s74, s37, 0x4000
	s_mov_b32 m0, s74
	s_add_i32 s75, s37, 0x6000
	global_load_lds_dwordx4 v134, s[18:19]
	s_mov_b32 m0, s75
	v_mov_b32_e32 v135, v137
	global_load_lds_dwordx4 v130, s[18:19]
	v_mov_b32_e32 v131, v137
	s_mov_b32 s76, 0
	v_lshl_add_u64 v[6:7], s[38:39], 0, v[132:133]
	v_lshl_add_u64 v[4:5], s[38:39], 0, v[128:129]
	v_lshl_add_u64 v[2:3], s[40:41], 0, v[134:135]
	s_cmp_lg_u32 s7, 1
	v_lshl_add_u64 v[0:1], s[40:41], 0, v[130:131]
	s_cbranch_scc1 .LBB0_328
	s_barrier

; #define KP(f) ((decltype(Params::f))karg_ptr<(int)offsetof(Params, f)>())
; #define PG8_WAIT_V(n) asm volatile("s_waitcnt vmcnt(" #n ")" ::: "memory")
; #define PG8_BAR __builtin_amdgcn_s_barrier()
;     ...
;     const int tid = tid_, wid = __builtin_amdgcn_readfirstlane(tid >> 6), lane = tid & 63, wr = wid >> 2, wc = wid & 3, fr = lane & 15, fq = lane >> 4;
;     const int K = g.K, nt = K / BK, lda = g.lda, ldb = g.ldb;
;     unsigned voffA[2], voffB[2];
; #pragma unroll
;     for (int i = 0; i < 2; ++i) { int R, C; stage_rc(tid * 16 + i * 8192, R, C); const int Rb = Epi::PERM ? ((R & ~31) + perm32(R & 31)) : R;
;         voffA[i] = (unsigned)(R * lda + C) * 2u; voffB[i] = (unsigned)(Rb * ldb + C) * 2u; }
;     const size_t kstep = (size_t)(BK * 2);
;     const size_t hA = (size_t)HALF * lda * 2, hB = (size_t)HALF * ldb * 2;
;     const size_t tA = 2 * hA, tB = 2 * hB;
;     const unsigned ldsw = (unsigned)wid * 1024u;
;     const int aoff = lds_byte(wr * 64 + fr, fq * 8), boff = lds_byte(wc * 32 + fr, fq * 8);
;     ...
;     Unit cur, nxt; int ui = 0;
;     if (!S.next(0, cur)) return;
;     ...
;     f32x4 acc[2][2][4][2];
; #pragma unroll
;     for (int a = 0; a < 2; ++a)
; #pragma unroll
;         for (int b = 0; b < 2; ++b)
; #pragma unroll
;             for (int m = 0; m < 4; ++m)
; #pragma unroll
;                 for (int n = 0; n < 2; ++n) acc[a][b][m][n] = (f32x4){0.f, 0.f, 0.f, 0.f};
;     bf16x8 At[4][2], B0[2][2], B1[2][2];
;     const char* cA = (const char*)g.A + (size_t)cur.pm * tA; const char* cB = (const char*)g.Bt + (size_t)cur.pn * tB;
;     PG8_A_READY(cur);
;     PG8_STAGE(PG8_SB(0, 0), cB, voffB); PG8_STAGE(PG8_SA(0, 0), cA, voffA); PG8_STAGE(PG8_SB(0, 1), cB + hB, voffB); PG8_STAGE(PG8_SA(0, 1), cA + hA, voffA);
;     if (wr == 1) PG8_BAR;
;     PG8_WAIT_V(4); PG8_BAR;
;     PG8_STAGE(PG8_SB(1, 0), cB + kstep, voffB); PG8_STAGE(PG8_SA(1, 0), cA + kstep, voffA); PG8_STAGE(PG8_SB(1, 1), cB + hB + kstep, voffB);
;     PG8_WAIT_V(6); PG8_BAR;
; __device__ __forceinline__ void run_phase(int type, int l, unsigned char* shm) {
;     ...
;         { pg8::Gemm g{KP(xb), KP(PoolT), T_ALL, 512, 512, 512, 512}; S.init(T_ALL, 512, G, (c + 136) % G);
;           EpiPool E{KP(z), KP(pool_scale) + (size_t)l * 512}; pg8::gemm_phase(lds, g, S, E); }
.LBB0_337:
	s_abs_i32 s6, s51
	s_waitcnt vmcnt(0)
	v_cvt_f32_u32_e32 v0, s6
	s_sub_i32 s9, 0, s6
	s_add_i32 s7, s53, 0x88
	s_ashr_i32 s8, s7, 31
	v_rcp_iflag_f32_e32 v0, v0
	s_abs_i32 s7, s7
	s_load_dwordx2 s[10:11], s[0:1], 0x120
	s_load_dwordx2 s[12:13], s[0:1], 0xf0
	v_mul_f32_e32 v0, 0x4f7ffffe, v0
	v_cvt_u32_f32_e32 v0, v0
	s_load_dwordx2 s[14:15], s[0:1], 0x130
	s_load_dwordx2 s[16:17], s[0:1], 0xa0
	s_waitcnt lgkmcnt(0)
	v_mov_b32_e32 v8, v166
	v_readfirstlane_b32 s18, v0
	s_mul_i32 s9, s9, s18
	s_mul_hi_u32 s9, s18, s9
	s_add_i32 s18, s18, s9
	s_mul_hi_u32 s9, s7, s18
	s_mul_i32 s9, s9, s6
	s_sub_i32 s7, s7, s9
	s_sub_i32 s9, s7, s6
	s_cmp_ge_u32 s7, s6
	s_cselect_b32 s7, s9, s7
	s_sub_i32 s9, s7, s6
	s_cmp_ge_u32 s7, s6
	s_cselect_b32 s6, s9, s7
	s_xor_b32 s6, s6, s8
	s_sub_i32 s38, s6, s8
	s_cmpk_gt_i32 s38, 0x87
	v_readfirstlane_b32 s39, v8
	s_cbranch_scc1 .LBB0_349
	v_lshlrev_b32_e32 v0, 4, v8
	v_add_u32_e32 v1, 0x2000, v0
	v_ashrrev_i32_e32 v2, 31, v1
	v_lshrrev_b32_e32 v2, 22, v2
	v_add_u32_e32 v2, v1, v2
	v_ashrrev_i32_e32 v9, 10, v2
	v_mul_i32_i24_e32 v2, 0x400, v9
	v_sub_u32_e32 v1, v1, v2
	v_lshrrev_b32_e32 v2, 4, v1
	v_bitop3_b32 v1, v2, v1, 32 bitop3:0x6c
	v_ashrrev_i32_e32 v2, 31, v1
	v_lshrrev_b32_e32 v2, 26, v2
	v_add_u32_e32 v2, v1, v2
	v_lshlrev_b32_e32 v3, 3, v9
	v_ashrrev_i32_e32 v10, 6, v2
	v_and_b32_e32 v3, -16, v3
	v_add_u32_e32 v3, v10, v3
	v_and_b32_e32 v4, 3, v10
	s_mov_b32 s8, 0x3fffe0
	v_lshrrev_b32_e32 v5, 2, v3
	v_lshlrev_b32_e32 v6, 1, v3
	v_and_b32_e32 v2, 0xc0, v2
	v_and_or_b32 v4, v3, s8, v4
	v_and_b32_e32 v5, 4, v5
	v_and_b32_e32 v6, 24, v6
	v_sub_u32_e32 v1, v1, v2
	v_mov_b32_e32 v2, 1
	v_or3_b32 v4, v4, v5, v6
	v_lshlrev_b32_e32 v5, 5, v9
	v_ashrrev_i16_sdwa v1, v2, sext(v1) dst_sel:DWORD dst_unused:UNUSED_PAD src0_sel:DWORD src1_sel:BYTE_0
	v_and_b32_e32 v5, 32, v5
	v_bfe_i32 v11, v1, 0, 16
	v_add_lshl_u32 v1, v5, v11, 1
	v_lshl_add_u32 v146, v4, 10, v1
	v_lshl_add_u32 v148, v3, 10, v1
	v_bfe_i32 v1, v8, 27, 1
	v_lshrrev_b32_e32 v1, 22, v1
	v_add_u32_e32 v1, v0, v1
	v_and_b32_e32 v1, 0xfffffc00, v1
	v_sub_u32_e32 v0, v0, v1
	v_lshrrev_b32_e32 v1, 4, v0
	v_ashrrev_i32_e32 v3, 31, v8
	v_bitop3_b32 v0, v1, v0, 32 bitop3:0x6c
	v_lshrrev_b32_e32 v3, 26, v3
	v_ashrrev_i32_e32 v1, 31, v0
	v_add_u32_e32 v3, v8, v3
	v_lshrrev_b32_e32 v1, 26, v1
	v_ashrrev_i32_e32 v13, 6, v3
	v_add_u32_e32 v1, v0, v1
	v_lshlrev_b32_e32 v3, 3, v13
	v_ashrrev_i32_e32 v12, 6, v1
	v_and_b32_e32 v3, -16, v3
	v_add_u32_e32 v3, v12, v3
	v_and_b32_e32 v4, 3, v12
	s_ashr_i32 s41, s38, 31
	v_and_or_b32 v4, v3, s8, v4
	s_lshr_b32 s8, s41, 29
	s_add_i32 s8, s38, s8
	s_ashr_i32 s6, s39, 6
	s_ashr_i32 s9, s8, 3
	s_and_b32 s8, s8, -8
	s_ashr_i32 s7, s39, 8
	s_lshl_b32 s40, s6, 10
	s_sub_i32 s8, s38, s8
	s_cmp_lt_i32 s8, 0
	s_cselect_b32 s18, 18, 17
	s_mul_i32 s8, s18, s8
	s_add_i32 s8, s8, s9
	s_ashr_i32 s9, s8, 31
	s_lshr_b32 s9, s9, 28
	s_add_i32 s9, s8, s9
	v_lshrrev_b32_e32 v5, 2, v3
	v_lshlrev_b32_e32 v6, 1, v3
	v_and_b32_e32 v1, 0xc0, v1
	s_ashr_i32 s18, s9, 4
	v_and_b32_e32 v5, 4, v5
	v_and_b32_e32 v6, 24, v6
	v_sub_u32_e32 v0, v0, v1
	s_lshl_b32 s18, s18, 3
	v_or3_b32 v4, v4, v5, v6
	v_lshlrev_b32_e32 v5, 5, v13
	v_ashrrev_i16_sdwa v0, v2, sext(v0) dst_sel:DWORD dst_unused:UNUSED_PAD src0_sel:DWORD src1_sel:BYTE_0
	s_sub_i32 s19, 0x44, s18
	v_and_b32_e32 v5, 32, v5
	v_bfe_i32 v14, v0, 0, 16
	s_min_u32 s19, s19, 8
	s_and_b32 s9, s9, -16
	v_add_lshl_u32 v0, v5, v14, 1
	s_sub_i32 s20, s8, s9
	v_cvt_f32_ubyte0_e32 v2, s19
	v_lshl_add_u32 v150, v4, 10, v0
	v_cvt_f32_i32_e32 v1, s20
	v_rcp_iflag_f32_e32 v4, v2
	v_lshl_add_u32 v152, v3, 10, v0
	s_ashr_i32 s8, s20, 30
	s_or_b32 s21, s8, 1
	v_mul_f32_e32 v0, v1, v4
	v_trunc_f32_e32 v0, v0
	v_fma_f32 v1, -v0, v2, v1
	v_cvt_i32_f32_e32 v0, v0
	v_cmp_ge_f32_e64 s[8:9], |v1|, v2
	s_and_b64 s[8:9], s[8:9], exec
	s_cselect_b32 s8, s21, 0
	v_readfirstlane_b32 s9, v0
	s_add_i32 s8, s9, s8
	s_mul_i32 s9, s8, s19
	s_sub_i32 s9, s20, s9
	s_sext_i32_i8 s9, s9
	s_add_i32 s28, s18, s9
	s_ashr_i32 s29, s28, 31
	s_bfe_i64 s[20:21], s[8:9], 0x80000
	s_lshl_b64 s[18:19], s[28:29], 18
	s_lshl_b64 s[20:21], s[20:21], 18
	s_add_u32 s30, s12, s20
	s_addc_u32 s31, s13, s21
	s_add_i32 s29, s40, 0
	s_add_i32 m0, s29, 0x10000
	v_mov_b32_e32 v151, 0
	global_load_lds_dwordx4 v150, s[30:31]
	s_add_i32 m0, s29, 0x12000
	s_add_u32 s34, s10, s18
	global_load_lds_dwordx4 v146, s[30:31]
	s_addc_u32 s35, s11, s19
	s_mov_b32 m0, s29
	s_add_i32 s53, s29, 0x2000
	global_load_lds_dwordx4 v152, s[34:35]
	s_mov_b32 m0, s53
	s_add_u32 s18, s30, 0x20000
	global_load_lds_dwordx4 v148, s[34:35]
	s_addc_u32 s19, s31, 0
	s_add_i32 m0, s29, 0x14000
	v_mov_b32_e32 v147, v151
	global_load_lds_dwordx4 v150, s[18:19]
	s_add_i32 m0, s29, 0x16000
	v_mov_b32_e32 v153, v151
	global_load_lds_dwordx4 v146, s[18:19]
	s_add_u32 s18, s34, 0x20000
	s_addc_u32 s19, s35, 0
	s_add_i32 s56, s29, 0x4000
	s_mov_b32 m0, s56
	s_add_i32 s57, s29, 0x6000
	global_load_lds_dwordx4 v152, s[18:19]
	s_mov_b32 m0, s57
	v_mov_b32_e32 v149, v151
	global_load_lds_dwordx4 v148, s[18:19]
	v_lshl_add_u64 v[6:7], s[30:31], 0, v[150:151]
	v_lshl_add_u64 v[4:5], s[30:31], 0, v[146:147]
	v_lshl_add_u64 v[2:3], s[34:35], 0, v[152:153]
	s_cmp_lg_u32 s7, 1
	v_lshl_add_u64 v[0:1], s[34:35], 0, v[148:149]
	s_cbranch_scc1 .LBB0_340
	s_barrier

; #define KP(f) ((decltype(Params::f))karg_ptr<(int)offsetof(Params, f)>())
; __device__ void phase_scan(int l, unsigned char* lds) {
;     int tid_ = threadIdx.x; asm volatile("" : "+v"(tid_));
;     const int tid = tid_, wid = tid >> 6, lane = tid & 63, G = gridDim.x;
;     const bool loader = wid >= 4;
;     if (!loader) __builtin_amdgcn_s_setprio(3);
;     ScanPtrs Q;
;     Q.z = KP(z); Q.sw = KP(xb) + (size_t)T_ALL * 512; Q.sa = KP(sc_a); Q.st_shift = KP(state_shift) + (size_t)l * NSB * DSH; Q.mu = KP(mu_shift) + (size_t)l * DSH;
;     Q.k_k = KP(k_k) + (size_t)l * 512; Q.k_a = KP(k_a) + (size_t)l * 512; Q.r_k = KP(r_k) + (size_t)l * 512; Q.decay0 = KP(decay0) + (size_t)l * 512; Q.a0 = KP(a0) + (size_t)l * 512; Q.rk = KP(rk);
;     bf16_t* ybuf = KP(xb);
;     const float* st_wkv = KP(state_wkv); float* out = KP(out);
;     int J = (G % 8 == 0) ? (int)(blockIdx.x % 8) * (G / 8) + (int)(blockIdx.x / 8) : (int)blockIdx.x, ci = 0, it = 0;
;     int Ji = J, cis = 0;
;     int Jg = J, cg_ = 0;
;     LStage L, L2;
;     f32x2 s01 = (f32x2){0.f, 0.f}, s23 = s01;
;     f32x4 s_pref = (f32x4){0.f, 0.f, 0.f, 0.f};
;     if (!loader && J >= 256 && J < NJOBS) { const Job j0 = job_decode(J, 0); s_pref = *(const f32x4*)(st_wkv + (((((size_t)l * NSB + j0.seq) * 8 + j0.h) * 64 + j0.rs * 16 + (wid * 4 + (lane >> 4))) * 64 + (lane & 15) * 4)); }
.LBB0_401:
	s_or_b64 exec, exec, s[8:9]
	s_mov_b32 s6, s46
	s_mov_b32 s7, s2
	v_mov_b32_e32 v53, v166
	s_waitcnt lgkmcnt(0)
	s_barrier
	s_nop 0
	v_ashrrev_i32_e32 v52, 6, v53
	s_mov_b32 s98, -1
	v_mov_b32_e32 v252, 0xbfb8aa3b
	v_mov_b32_e32 v254, 0xbf1b4598
	v_mov_b32_e32 v226, 0x3fb8aa3b
	v_cmp_lt_i32_e64 s[10:11], 3, v52
	v_cmp_gt_i32_e64 s[12:13], 4, v52
	s_and_saveexec_b64 s[8:9], s[12:13]
	s_setprio 3
	s_or_b64 exec, exec, s[8:9]
	s_load_dwordx2 s[24:25], s[0:1], 0x130
	s_load_dwordx2 s[14:15], s[0:1], 0x120
	s_load_dwordx2 s[26:27], s[0:1], 0x140
	s_load_dwordx2 s[28:29], s[0:1], 16
	s_load_dwordx2 s[30:31], s[0:1], 56
	s_load_dwordx2 s[34:35], s[0:1], 0x68
	s_load_dwordx2 s[36:37], s[0:1], 0x70
	s_load_dwordx2 s[38:39], s[0:1], 0x78
	s_load_dwordx2 s[40:41], s[0:1], 64
	s_load_dwordx2 s[56:57], s[0:1], 0x50
	s_load_dwordx2 s[58:59], s[0:1], 0x150
	s_load_dwordx2 s[60:61], s[0:1], 0x120
	s_load_dwordx2 s[22:23], s[0:1], 32
	s_load_dwordx2 s[62:63], s[0:1], 0xd8
	s_waitcnt lgkmcnt(0)
	v_cndmask_b32_e64 v0, 0, 1, s[54:55]
	v_cmp_ne_u32_e64 s[6:7], 1, v0
	s_andn2_b64 vcc, exec, s[54:55]
	s_mov_b32 s51, s2
	v_writelane_b32 v230, s6, 6
	s_nop 1
	v_writelane_b32 v230, s7, 7
	s_cbranch_vccnz .LBB0_405
	s_and_b32 s6, s2, 7
	s_ashr_i32 s7, s46, 3
	s_mul_i32 s6, s7, s6
	s_lshr_b32 s7, s2, 3
	s_add_i32 s51, s6, s7

; #define KP(f) ((decltype(Params::f))karg_ptr<(int)offsetof(Params, f)>())
; __device__ __forceinline__ Tok tok_decode(int tok) { Tok r; if (tok < T_P) { r.is_s = 0; r.seq = tok >> 11; r.t = tok & 2047; } else { r.is_s = 1; r.seq = (tok - T_P) >> 3; r.t = (tok - T_P) & 7; } return r; }
; __device__ void phase_e2(int l, int wg0) {
;     if ((int)blockIdx.x < wg0) return;
;     const int gtid = ((int)blockIdx.x - wg0) * 512 + threadIdx.x, nth = ((int)gridDim.x - wg0) * 512;
;     const bf16_t* ybuf = KP(xb); bf16_t* ya = KP(xb) + (size_t)T_ALL * 512;
;     const bf16_t* z = KP(z); const bf16_t* sc_g = KP(sc_g); const float* rkb = KP(rk);
;     const float* mu = KP(mu_shift) + (size_t)l * DSH + 1024;
;     const float* st_shift = KP(state_shift) + (size_t)l * NSB * DSH;
;     const float* lng = KP(ln_x_g) + (size_t)l * 512; const float* lnb = KP(ln_x_b) + (size_t)l * 512;
;     for (int it0 = gtid; it0 < T_ALL * 128; it0 += 2 * nth) {
;         f32x4 y[2], v[2], vp[2], g[2], m4[2], lg[2], lb[2]; float rk[2]; int tokv[2], cv[2]; bool ok[2];
; #pragma unroll
;         for (int q = 0; q < 2; ++q) {
;             const int it = it0 + q * nth; ok[q] = it < T_ALL * 128; const int itc = ok[q] ? it : it0;
;             const int tok = itc >> 7, c = (itc & 127) * 4, h = c >> 6; const Tok tk = tok_decode(tok); tokv[q] = tok; cv[q] = c;
.LBB0_595:
	s_or_b64 exec, exec, s[10:11]
	s_mov_b32 s40, s46
	s_mov_b32 s41, s2
	s_waitcnt lgkmcnt(0)
	s_barrier
	s_abs_i32 s6, s40
	v_cvt_f32_u32_e32 v0, s6
	s_sub_i32 s7, 0, s6
	v_rcp_iflag_f32_e32 v0, v0
	s_nop 0
	v_mul_f32_e32 v0, 0x4f7ffffe, v0
	v_cvt_u32_f32_e32 v0, v0
	s_nop 0
	v_readfirstlane_b32 s8, v0
	s_mul_i32 s7, s7, s8
	s_mul_hi_u32 s7, s8, s7
	s_add_i32 s8, s8, s7
	s_mul_hi_u32 s7, s8, 0x110
	s_mul_i32 s7, s7, s6
	s_sub_i32 s7, 0x110, s7
	s_sub_i32 s8, s7, s6
	s_cmp_ge_u32 s7, s6
	s_cselect_b32 s7, s8, s7
	s_sub_i32 s8, s7, s6
	s_cmp_ge_u32 s7, s6
	s_cselect_b32 s33, s8, s7
	s_cmp_lt_i32 s2, s33
	s_cbranch_scc1 .LBB0_618
	s_load_dwordx2 s[14:15], s[0:1], 0x120
	s_load_dwordx2 s[12:13], s[0:1], 0x120
	s_load_dwordx2 s[10:11], s[0:1], 0x130
	s_load_dwordx2 s[16:17], s[0:1], 0x148
	s_load_dwordx2 s[18:19], s[0:1], 0x150
	s_load_dwordx2 s[30:31], s[0:1], 56
	s_load_dwordx2 s[20:21], s[0:1], 16
	s_load_dwordx2 s[22:23], s[0:1], 0x80
	s_sub_i32 s6, s2, s33
	s_load_dwordx2 s[24:25], s[0:1], 0x88
	s_waitcnt lgkmcnt(0)
	v_lshl_add_u32 v0, s6, 9, v166
	s_mov_b32 s6, 0x220000
	v_cmp_gt_i32_e32 vcc, s6, v0
	s_and_saveexec_b64 s[26:27], vcc
	s_cbranch_execz .LBB0_617
	s_add_u32 s28, s12, 0x1100000
	s_addc_u32 s29, s13, 0
	s_add_u32 s30, s30, 0x1000
	s_addc_u32 s31, s31, 0
	s_lshl_b32 s7, s33, 9
	s_lshl_b32 s8, s46, 10
	s_lshl_b32 s9, s33, 10
	s_lshl_b32 s12, s46, 12
	s_lshl_b32 s13, s33, 12
	s_sub_i32 s7, 0, s7
	v_lshl_add_u32 v35, s2, 9, v166
	s_sub_i32 s8, s8, s9
	s_sub_i32 s9, s52, s9
	v_lshlrev_b32_e32 v44, 2, v0
	s_sub_i32 s33, s12, s13
	s_mov_b64 s[34:35], 0
	s_movk_i32 s42, 0x3fff
	s_movk_i32 s43, 0x4000
	v_mov_b32_e32 v45, 0x7ff
	v_mov_b32_e32 v21, 0
	s_movk_i32 s44, 0x2200
	v_mov_b64_e32 v[22:23], s[10:11]
	s_mov_b64 s[36:37], 0x800
	s_movk_i32 s45, 0x1c00
	v_mov_b32_e32 v46, 0x3a27c5ac
	s_mov_b32 s51, 0x800000
	s_mov_b32 s53, 0x21ffff
	s_branch .LBB0_599

; #define KP(f) ((decltype(Params::f))karg_ptr<(int)offsetof(Params, f)>())
; #define PG8_STAGE(bufoff, gbase, voff) do { _Pragma("unroll") for (int _i = 0; _i < 2; ++_i) \
;         __builtin_amdgcn_global_load_lds((const unsigned*)((const char*)(gbase) + (voff)[_i]), (LAS unsigned*)(lds + (bufoff) + ldsw + _i * 8192), 16, 0, 0); } while (0)
;     ...
;     const int tid = tid_, wid = __builtin_amdgcn_readfirstlane(tid >> 6), lane = tid & 63, wr = wid >> 2, wc = wid & 3, fr = lane & 15, fq = lane >> 4;
;     const int K = g.K, nt = K / BK, lda = g.lda, ldb = g.ldb;
;     unsigned voffA[2], voffB[2];
; #pragma unroll
;     for (int i = 0; i < 2; ++i) { int R, C; stage_rc(tid * 16 + i * 8192, R, C); const int Rb = Epi::PERM ? ((R & ~31) + perm32(R & 31)) : R;
;         voffA[i] = (unsigned)(R * lda + C) * 2u; voffB[i] = (unsigned)(Rb * ldb + C) * 2u; }
;     const size_t kstep = (size_t)(BK * 2);
;     const size_t hA = (size_t)HALF * lda * 2, hB = (size_t)HALF * ldb * 2;
;     const size_t tA = 2 * hA, tB = 2 * hB;
;     const unsigned ldsw = (unsigned)wid * 1024u;
;     const int aoff = lds_byte(wr * 64 + fr, fq * 8), boff = lds_byte(wc * 32 + fr, fq * 8);
;     ...
;     Unit cur, nxt; int ui = 0;
;     if (!S.next(0, cur)) return;
;     ...
;     f32x4 acc[2][2][4][2];
; #pragma unroll
;     for (int a = 0; a < 2; ++a)
; #pragma unroll
;         for (int b = 0; b < 2; ++b)
; #pragma unroll
;             for (int m = 0; m < 4; ++m)
; #pragma unroll
;                 for (int n = 0; n < 2; ++n) acc[a][b][m][n] = (f32x4){0.f, 0.f, 0.f, 0.f};
;     bf16x8 At[4][2], B0[2][2], B1[2][2];
;     const char* cA = (const char*)g.A + (size_t)cur.pm * tA; const char* cB = (const char*)g.Bt + (size_t)cur.pn * tB;
;     PG8_A_READY(cur);
;     PG8_STAGE(PG8_SB(0, 0), cB, voffB); PG8_STAGE(PG8_SA(0, 0), cA, voffA); PG8_STAGE(PG8_SB(0, 1), cB + hB, voffB); PG8_STAGE(PG8_SA(0, 1), cA + hA, voffA);
;     if (wr == 1) PG8_BAR;
;     PG8_WAIT_V(4); PG8_BAR;
;     PG8_STAGE(PG8_SB(1, 0), cB + kstep, voffB); PG8_STAGE(PG8_SA(1, 0), cA + kstep, voffA); PG8_STAGE(PG8_SB(1, 1), cB + hB + kstep, voffB);
;     PG8_WAIT_V(6); PG8_BAR;
; __device__ __forceinline__ void run_phase(int type, int l, unsigned char* shm) {
;     ...
;         pg8::Gemm g{KP(z) + O_U, KP(BupT), T_ALL, DM, 512, DIN, 512}; S.init(T_ALL, DM, G, c);
;         EpiGate<0> E{KP(z)}; pg8::gemm_phase(lds, g, S, E);
.LBB0_618:
	s_load_dwordx2 s[20:21], s[0:1], 0x130
	s_load_dwordx2 s[22:23], s[0:1], 0xf8
	s_load_dwordx2 s[24:25], s[0:1], 0x130
	s_waitcnt lgkmcnt(0)
	s_waitcnt vmcnt(4)
	v_mov_b32_e32 v8, v166
	s_cmpk_gt_i32 s41, 0x10f
	v_readfirstlane_b32 s36, v8
	s_cbranch_scc1 .LBB0_632
	v_lshlrev_b32_e32 v0, 4, v8
	v_add_u32_e32 v1, 0x2000, v0
	s_waitcnt vmcnt(0)
	v_ashrrev_i32_e32 v2, 31, v1
	v_lshrrev_b32_e32 v2, 22, v2
	v_add_u32_e32 v2, v1, v2
	v_ashrrev_i32_e32 v9, 10, v2
	v_mul_i32_i24_e32 v2, 0x400, v9
	v_sub_u32_e32 v1, v1, v2
	v_lshrrev_b32_e32 v2, 4, v1
	v_bitop3_b32 v1, v2, v1, 32 bitop3:0x6c
	v_ashrrev_i32_e32 v2, 31, v1
	v_lshrrev_b32_e32 v2, 26, v2
	v_add_u32_e32 v2, v1, v2
	v_lshlrev_b32_e32 v3, 3, v9
	v_ashrrev_i32_e32 v10, 6, v2
	v_and_b32_e32 v3, -16, v3
	v_add_u32_e32 v3, v10, v3
	v_and_b32_e32 v4, 3, v10
	s_mov_b32 s6, 0x3fffe0
	v_lshrrev_b32_e32 v5, 2, v3
	v_lshlrev_b32_e32 v6, 1, v3
	v_and_b32_e32 v2, 0xc0, v2
	v_and_or_b32 v4, v3, s6, v4
	v_and_b32_e32 v5, 4, v5
	v_and_b32_e32 v6, 24, v6
	v_sub_u32_e32 v1, v1, v2
	v_mov_b32_e32 v2, 1
	v_or3_b32 v4, v4, v5, v6
	v_lshlrev_b32_e32 v5, 5, v9
	v_ashrrev_i16_sdwa v1, v2, sext(v1) dst_sel:DWORD dst_unused:UNUSED_PAD src0_sel:DWORD src1_sel:BYTE_0
	v_and_b32_e32 v11, 32, v5
	v_bfe_i32 v12, v1, 0, 16
	s_movk_i32 s9, 0x1100
	v_add_u32_e32 v1, v11, v12
	v_mul_lo_u32 v3, v3, s9
	v_lshlrev_b32_e32 v5, 1, v1
	v_add_lshl_u32 v130, v1, v3, 1
	v_bfe_i32 v1, v8, 27, 1
	v_lshrrev_b32_e32 v1, 22, v1
	v_add_u32_e32 v1, v0, v1
	v_and_b32_e32 v1, 0xfffffc00, v1
	v_sub_u32_e32 v0, v0, v1
	v_lshrrev_b32_e32 v1, 4, v0
	v_ashrrev_i32_e32 v3, 31, v8
	v_bitop3_b32 v0, v1, v0, 32 bitop3:0x6c
	v_lshrrev_b32_e32 v3, 26, v3
	v_ashrrev_i32_e32 v1, 31, v0
	v_add_u32_e32 v3, v8, v3
	v_lshrrev_b32_e32 v1, 26, v1
	v_ashrrev_i32_e32 v14, 6, v3
	v_add_u32_e32 v1, v0, v1
	v_lshlrev_b32_e32 v3, 3, v14
	v_ashrrev_i32_e32 v13, 6, v1
	v_and_b32_e32 v3, -16, v3
	v_lshl_add_u32 v128, v4, 10, v5
	v_add_u32_e32 v3, v13, v3
	v_and_b32_e32 v4, 3, v13
	s_ashr_i32 s38, s41, 31
	v_and_or_b32 v4, v3, s6, v4
	s_lshr_b32 s6, s38, 29
	s_add_i32 s6, s41, s6
	s_ashr_i32 s7, s36, 6
	s_ashr_i32 s10, s6, 3
	s_and_b32 s6, s6, -8
	s_ashr_i32 s8, s36, 8
	s_lshl_b32 s37, s7, 10
	s_sub_i32 s6, s41, s6
	s_cmp_lt_i32 s6, 0
	s_cselect_b32 s11, 35, 34
	s_mul_i32 s6, s11, s6
	s_add_i32 s6, s6, s10
	s_ashr_i32 s10, s6, 31
	v_lshrrev_b32_e32 v5, 2, v3
	v_lshlrev_b32_e32 v6, 1, v3
	v_and_b32_e32 v1, 0xc0, v1
	s_lshr_b32 s10, s10, 27
	v_and_b32_e32 v5, 4, v5
	v_and_b32_e32 v6, 24, v6
	v_sub_u32_e32 v0, v0, v1
	s_add_i32 s10, s6, s10
	v_or3_b32 v4, v4, v5, v6
	v_lshlrev_b32_e32 v5, 5, v14
	v_ashrrev_i16_sdwa v0, v2, sext(v0) dst_sel:DWORD dst_unused:UNUSED_PAD src0_sel:DWORD src1_sel:BYTE_0
	s_ashr_i32 s11, s10, 5
	v_and_b32_e32 v15, 32, v5
	v_bfe_i32 v16, v0, 0, 16
	s_lshl_b32 s12, s11, 3
	v_add_u32_e32 v0, v15, v16
	s_sub_i32 s11, 0x44, s12
	v_lshlrev_b32_e32 v1, 1, v0
	s_min_u32 s13, s11, 8
	s_andn2_b32 s10, s10, 31
	v_lshl_add_u32 v132, v4, 10, v1
	v_mul_lo_u32 v1, v3, s9
	s_sub_i32 s6, s6, s10
	v_cvt_f32_ubyte0_e32 v3, s13
	v_cvt_f32_i32_e32 v2, s6
	v_rcp_iflag_f32_e32 v4, v3
	v_add_lshl_u32 v134, v0, v1, 1
	s_ashr_i32 s10, s6, 30
	s_or_b32 s14, s10, 1
	v_mul_f32_e32 v0, v2, v4
	v_trunc_f32_e32 v0, v0
	v_fma_f32 v1, -v0, v3, v2
	v_cvt_i32_f32_e32 v0, v0
	v_cmp_ge_f32_e64 s[10:11], |v1|, v3
	s_and_b64 s[10:11], s[10:11], exec
	s_cselect_b32 s10, s14, 0
	v_readfirstlane_b32 s11, v0
	s_add_i32 s10, s11, s10
	s_mul_i32 s11, s10, s13
	s_sub_i32 s6, s6, s11
	s_sext_i32_i8 s6, s6
	s_add_i32 s6, s12, s6
	s_mul_hi_i32 s11, s6, 0x220000
	s_bfe_i64 s[12:13], s[10:11], 0x80000
	s_lshl_b64 s[12:13], s[12:13], 18
	s_add_u32 s16, s22, s12
	s_addc_u32 s17, s23, s13
	s_add_i32 s39, s37, 0
	s_add_i32 m0, s39, 0x10000
	s_mul_i32 s14, s6, 0x220000
	global_load_lds_dwordx4 v132, s[16:17]
	s_add_i32 m0, s39, 0x12000
	v_mov_b32_e32 v133, 0
	s_add_u32 s12, s20, s14
	s_addc_u32 s13, s21, s11
	v_mov_b32_e32 v135, v133
	s_mov_b64 s[18:19], 0xe00
	v_lshl_add_u64 v[0:1], s[12:13], 0, v[134:135]
	global_load_lds_dwordx4 v128, s[16:17]
	s_add_u32 s14, s12, 0xe00
	v_lshl_add_u64 v[2:3], v[0:1], 0, s[18:19]
	s_mov_b32 m0, s39
	v_mov_b32_e32 v131, v133
	s_addc_u32 s15, s13, 0
	global_load_lds_dwordx4 v[2:3], off
	v_lshl_add_u64 v[2:3], s[12:13], 0, v[130:131]
	s_add_i32 s51, s39, 0x2000
	v_lshl_add_u64 v[4:5], v[2:3], 0, s[18:19]
	s_mov_b32 m0, s51
	s_add_u32 s18, s16, 0x20000
	global_load_lds_dwordx4 v[4:5], off
	s_addc_u32 s19, s17, 0
	s_add_i32 m0, s39, 0x14000
	v_mov_b32_e32 v129, v133
	global_load_lds_dwordx4 v132, s[18:19]
	s_add_i32 m0, s39, 0x16000
	s_add_u32 s12, s12, 0x110e00
	s_addc_u32 s13, s13, 0
	s_add_i32 s53, s39, 0x4000
	global_load_lds_dwordx4 v128, s[18:19]
	s_mov_b32 m0, s53
	s_add_i32 s54, s39, 0x6000
	global_load_lds_dwordx4 v134, s[12:13]
	s_mov_b32 m0, s54
	s_mov_b32 s55, 0
	global_load_lds_dwordx4 v130, s[12:13]
	v_lshl_add_u64 v[4:5], s[16:17], 0, v[132:133]
	s_cmp_lg_u32 s8, 1
	v_lshl_add_u64 v[6:7], s[16:17], 0, v[128:129]
	s_cbranch_scc1 .LBB0_621
	s_barrier

; #define KP(f) ((decltype(Params::f))karg_ptr<(int)offsetof(Params, f)>())
;     __device__ bool next(int i, Unit& u) const {
;         const long L = (long)i * G + c; if (L >= nwg) return false;
;         int wgid = (int)L; { const int q = nwg / NXCD, r = nwg % NXCD, xcd = wgid % NXCD, off = wgid / NXCD; wgid = (xcd < r ? xcd * (q + 1) : r * (q + 1) + (xcd - r) * q) + off; }
;         const int nig = WGM * nN, gid = wgid / nig, fm = gid * WGM, gsz = (nM - fm) < WGM ? (nM - fm) : WGM;
;         u.pm = fm + ((wgid % nig) % gsz); u.pn = (wgid % nig) / gsz; return true;
; __device__ __forceinline__ void run_phase(int type, int l, unsigned char* shm) {
;     ...
;         unsigned* rdy = KP(bar) + XCD_BAR_WORDS + 1024 + (2 + l) * (68 * 64); float* out = KP(out);
;         { pg8::Gemm g{KP(xb) + (size_t)T_ALL * 512, KP(AupT), T_P, DM, 512, 512, 512}; S.init(T_P, DM, G, c);
;           EpiMergePub E{KP(z), rdy, 0, 0}; pg8::gemm_phase(lds, g, S, E); }
.LBB0_684:
	s_or_b64 exec, exec, s[10:11]
	s_mov_b32 s51, s2
	s_mov_b32 s53, s46
	s_waitcnt lgkmcnt(0)
	s_barrier
	s_load_dwordx2 s[30:31], s[0:1], 0x158
	s_load_dwordx2 s[28:29], s[0:1], 0xd8
	s_load_dwordx2 s[10:11], s[0:1], 0x120
	s_waitcnt lgkmcnt(0)
	s_add_u32 s34, s30, 0xce00
	s_load_dwordx2 s[22:23], s[0:1], 0x100
	s_addc_u32 s35, s31, 0
	s_load_dwordx2 s[38:39], s[0:1], 0x130
	s_waitcnt lgkmcnt(0)
	v_mov_b32_e32 v8, v166
	s_cmpk_lt_i32 s51, 0x100
	s_cselect_b64 s[36:37], -1, 0
	s_cmpk_gt_i32 s51, 0xff
	v_readfirstlane_b32 s62, v8
	s_cbranch_scc1 .LBB0_707
	s_ashr_i32 s63, s51, 31
	s_lshr_b32 s6, s63, 29
	s_add_i32 s6, s51, s6
	s_and_b32 s7, s6, -8
	s_sub_i32 s7, s51, s7
	s_cmp_gt_i32 s7, -1
	s_cbranch_scc0 .LBB0_687
	s_lshl_b32 s8, s7, 5
	s_cbranch_execz .LBB0_688
	s_branch .LBB0_689

; #define KP(f) ((decltype(Params::f))karg_ptr<(int)offsetof(Params, f)>())
;     __device__ bool next(int i, Unit& u) const {
;         const long L = (long)i * G + c; if (L >= nwg) return false;
;         int wgid = (int)L; { const int q = nwg / NXCD, r = nwg % NXCD, xcd = wgid % NXCD, off = wgid / NXCD; wgid = (xcd < r ? xcd * (q + 1) : r * (q + 1) + (xcd - r) * q) + off; }
;         const int nig = WGM * nN, gid = wgid / nig, fm = gid * WGM, gsz = (nM - fm) < WGM ? (nM - fm) : WGM;
;         u.pm = fm + ((wgid % nig) % gsz); u.pn = (wgid % nig) / gsz; return true;
; __device__ __forceinline__ void run_phase(int type, int l, unsigned char* shm) {
;     ...
;         { pg8::Gemm g{KP(xb) + (size_t)T_ALL * 512 + (size_t)T_P * 512, KP(AupT), T_ALL - T_P, DM, 512, 512, 512}; S.init(T_ALL - T_P, DM, G, c);
;           EpiMergePub E{KP(z), rdy, T_P, 64}; pg8::gemm_phase(lds, g, S, E); }
.LBB0_707:
	s_load_dwordx2 s[10:11], s[0:1], 0x120
	s_load_dwordx2 s[24:25], s[0:1], 0x100
	s_load_dwordx2 s[26:27], s[0:1], 0x130
	s_waitcnt lgkmcnt(0)
	v_mov_b32_e32 v8, v166
	s_cmp_gt_i32 s51, 15
	v_readfirstlane_b32 s62, v8
	s_cbranch_scc1 .LBB0_730
	s_ashr_i32 s63, s51, 31
	s_lshr_b32 s6, s63, 29
	s_add_i32 s6, s51, s6
	s_and_b32 s7, s6, -8
	s_sub_i32 s7, s51, s7
	s_cmp_gt_i32 s7, -1
	s_cbranch_scc0 .LBB0_710
	s_lshl_b32 s8, s7, 1
	s_cbranch_execz .LBB0_711
	s_branch .LBB0_712

; #define KP(f) ((decltype(Params::f))karg_ptr<(int)offsetof(Params, f)>())
;     __device__ bool next(int i, Unit& u) const {
;         const long L = (long)i * G + c; if (L >= nwg) return false;
;         int wgid = (int)L; { const int q = nwg / NXCD, r = nwg % NXCD, xcd = wgid % NXCD, off = wgid / NXCD; wgid = (xcd < r ? xcd * (q + 1) : r * (q + 1) + (xcd - r) * q) + off; }
;         const int nig = WGM * nN, gid = wgid / nig, fm = gid * WGM, gsz = (nM - fm) < WGM ? (nM - fm) : WGM;
;         u.pm = fm + ((wgid % nig) % gsz); u.pn = (wgid % nig) / gsz; return true;
; __device__ __forceinline__ void run_phase(int type, int l, unsigned char* shm) {
;     ...
;         { pg8::Gemm g{KP(z), KP(WoT), T_P, DM, DM, DIN, DM}; S.init(T_P, DM, G, c);
;           EpiRes E{l == 0 ? KP(x_prompt) : out, nullptr, out, KP(xb), KP(ssq)}; pg8::gemm_phase(lds, g, S, E, rdy, 32u, 64); }
.LBB0_730:
	s_load_dwordx2 s[18:19], s[0:1], 0x130
	s_load_dwordx2 s[20:21], s[0:1], 0x108
	s_load_dwordx2 s[22:23], s[0:1], 0
	s_load_dwordx2 s[24:25], s[0:1], 0x120
	s_load_dwordx2 s[26:27], s[0:1], 0x128
	s_waitcnt lgkmcnt(0)
	s_waitcnt vmcnt(0)
	v_mov_b32_e32 v10, v166
	v_cndmask_b32_e64 v0, 0, 1, s[36:37]
	v_cmp_ne_u32_e64 s[10:11], 1, v0
	s_andn2_b64 vcc, exec, s[36:37]
	v_readfirstlane_b32 s68, v10
	s_cbranch_vccnz .LBB0_736
	s_ashr_i32 s6, s51, 31
	s_lshr_b32 s6, s6, 29
	s_add_i32 s8, s51, s6
	s_and_b32 s6, s8, -8
	s_sub_i32 s6, s51, s6
	s_cmp_gt_i32 s6, -1
	s_cbranch_scc0 .LBB0_733
	s_lshl_b32 s7, s6, 5
	s_ashr_i32 s8, s8, 3
	s_cbranch_execz .LBB0_734
	s_branch .LBB0_735

; #define KP(f) ((decltype(Params::f))karg_ptr<(int)offsetof(Params, f)>())
;     int G = gridDim.x, c = ((int)blockIdx.x - cbase + (int)gridDim.x) % (int)gridDim.x; asm volatile("" : "+s"(G), "+s"(c));
;     const int Kq = Ktot >> 2;
;     pg8::StaticOrder S;
; #pragma unroll 1
;     for (int kq = 0; kq < 4; ++kq) {
;         pg8::Gemm g{A + (size_t)kq * Kq, Bt + (size_t)kq * Kq, 1024, DM, Kq, lda, Ktot};
;         S.init(1024, DM, G, (c - 16 * kq + G) % G);
;         EpiPartial E{part + (size_t)kq * 1024 * DM};
;         pg8::gemm_phase(lds, g, S, E, ready, need, npan);
; __device__ __forceinline__ void run_phase(int type, int l, unsigned char* shm) {
;     ...
;         sample_splitk(lds, KP(z) + (size_t)T_P * DIN, DIN, KP(WoT), DM, l == 0 ? KP(x_sample) : out + (size_t)T_P * DM, out + (size_t)T_P * DM, KP(xb) + (size_t)T_P * DM, KP(ssq) + (size_t)T_P * 16,
;                       (float*)KP(sc_a), KP(bar) + XCD_BAR_WORDS + (l * 2 + 0) * 256, G > 64 ? G - 64 : 0, rdy + 64 * 64, 32u, 4);
.LBB0_800:
	s_load_dwordx2 s[6:7], s[0:1], 0x130
	s_waitcnt lgkmcnt(0)
	s_add_u32 s82, s6, 0x8800000
	s_addc_u32 s83, s7, 0
	s_max_i32 s6, s53, 64
	s_add_u32 s26, s30, 0x10e00
	s_addc_u32 s27, s31, 0
	s_abs_i32 s51, s46
	v_cvt_f32_u32_e32 v0, s51
	s_add_i32 s80, s2, 64
	s_sub_i32 s8, 0, s51
	s_add_i32 s7, s46, s80
	v_rcp_iflag_f32_e32 v0, v0
	s_sub_i32 s6, s7, s6
	v_writelane_b32 v230, s7, 8
	s_ashr_i32 s7, s6, 31
	v_mul_f32_e32 v0, 0x4f7ffffe, v0
	v_cvt_u32_f32_e32 v0, v0
	s_abs_i32 s6, s6
	s_load_dwordx2 s[24:25], s[0:1], 0x108
	s_load_dwordx2 s[14:15], s[0:1], 8
	s_waitcnt lgkmcnt(0)
	v_readfirstlane_b32 s9, v0
	s_mul_i32 s8, s8, s9
	s_mul_hi_u32 s8, s9, s8
	s_add_i32 s8, s9, s8
	v_writelane_b32 v230, s8, 9
	s_mul_hi_u32 s8, s6, s8
	s_mul_i32 s8, s8, s51
	s_sub_i32 s6, s6, s8
	s_sub_i32 s8, s6, s51
	s_cmp_ge_u32 s6, s51
	s_cselect_b32 s6, s8, s6
	s_sub_i32 s8, s6, s51
	s_cmp_ge_u32 s6, s51
	s_load_dwordx2 s[20:21], s[0:1], 0x120
	s_cselect_b32 s6, s8, s6
	s_load_dwordx2 s[18:19], s[0:1], 0x128
	s_xor_b32 s6, s6, s7
	s_load_dwordx2 s[16:17], s[0:1], 0x140
	s_sub_i32 s81, s6, s7
	s_mov_b32 s84, s46
	s_load_dwordx2 s[22:23], s[0:1], 0x158
	s_waitcnt lgkmcnt(0)
	s_abs_i32 s85, s84
	v_cvt_f32_u32_e32 v0, s85
	s_sub_i32 s6, 0, s85
	s_mov_b32 s31, 0
	s_movk_i32 s86, 0x1100
	v_rcp_iflag_f32_e32 v0, v0
	v_mov_b32_e32 v129, 0
	s_add_i32 s87, s84, s81
	s_ashr_i32 s88, s84, 31
	v_mul_f32_e32 v0, 0x4f7ffffe, v0
	v_cvt_u32_f32_e32 v0, v0
	s_mov_b64 s[34:35], 0x80
	v_mov_b32_e32 v138, 1
	s_mov_b32 s90, 0
	v_readfirstlane_b32 s7, v0
	s_mul_i32 s6, s6, s7
	s_mul_hi_u32 s6, s7, s6
	s_add_i32 s89, s7, s6
	s_branch .LBB0_803

; #define KP(f) ((decltype(Params::f))karg_ptr<(int)offsetof(Params, f)>())
;     int tid_ = threadIdx.x; asm volatile("" : "+v"(tid_));
;     const int tid = tid_, ntn = N / 64, ntiles = (K / 64) * ntn, nwg = wgn > 0 ? wgn : (int)gridDim.x - wg0;
;     if ((int)blockIdx.x < wg0 || (int)blockIdx.x >= wg0 + nwg) return;
;     const int r = tid >> 4, c4 = (tid & 15) * 4, n = tid >> 3, k8 = (tid & 7) * 8;
;     int t = (int)blockIdx.x - wg0;
;     f32x4 v0, v1; float g0 = 1.f, g1 = 1.f;
;     if (t < ntiles) { const int k0 = (t / ntn) * 64, n0 = (t % ntn) * 64;
;         v0 = *(const f32x4*)(src + (size_t)(k0 + r) * N + n0 + c4); v1 = *(const f32x4*)(src + (size_t)(k0 + r + 32) * N + n0 + c4);
;         if (gain) { g0 = gain[k0 + r]; g1 = gain[k0 + r + 32]; } }
; __device__ __forceinline__ void run_phase(int type, int l, unsigned char* shm) {
;     ...
;         if (l == 0) { if (G >= 256) transpose_convert(KP(w_ff2), DFF, DM, nullptr, KP(Wff2T), (float*)shm, 64, 128);
;                       else transpose_convert(KP(w_ff2), DFF, DM, nullptr, KP(Wff2T), (float*)shm); }
.LBB0_869:
	s_load_dwordx2 s[10:11], s[0:1], 0xc8
	s_load_dwordx2 s[12:13], s[0:1], 0x118
	s_waitcnt lgkmcnt(0)
	v_readlane_b32 s6, v230, 2
	v_readlane_b32 s7, v230, 3
	v_mov_b32_e32 v10, v166
	s_and_b64 vcc, exec, s[6:7]
	s_cbranch_vccnz .LBB0_877
	s_cmpk_gt_u32 s2, 0x3ff
	s_cbranch_scc1 .LBB0_877
	s_lshl_b32 s6, s2, 2
	v_ashrrev_i32_e32 v12, 4, v10
	v_lshlrev_b32_e32 v0, 2, v10
	s_and_b32 s6, s6, 0xfc0
	v_and_b32_e32 v20, 60, v0
	v_add_u32_e32 v0, s6, v12
	s_waitcnt lgkmcnt(0)
	v_ashrrev_i32_e32 v1, 31, v0
	v_lshlrev_b64 v[0:1], 12, v[0:1]
	s_lshl_b32 s6, s2, 8
	v_lshl_add_u64 v[0:1], s[10:11], 0, v[0:1]
	s_and_b32 s6, s6, 0xf00
	s_mov_b32 s7, 0
	v_lshl_add_u64 v[0:1], v[0:1], 0, s[6:7]
	v_mov_b32_e32 v9, 0
	v_lshlrev_b32_e32 v8, 2, v20
	v_lshl_add_u64 v[14:15], v[0:1], 0, v[8:9]
	s_mov_b32 s6, 0x20000
	v_add_co_u32_e32 v16, vcc, s6, v14
	v_ashrrev_i32_e32 v13, 3, v10
	s_nop 0
	v_addc_co_u32_e32 v17, vcc, 0, v15, vcc
	global_load_dwordx4 v[0:3], v[14:15], off
	global_load_dwordx4 v[4:7], v[16:17], off
	v_lshlrev_b32_e32 v10, 3, v10
	s_movk_i32 s6, 0x104
	v_and_b32_e32 v10, 56, v10
	v_mul_lo_u32 v15, v12, s6
	v_add3_u32 v14, 0, v8, v15
	v_add3_u32 v8, 0, v15, v8
	v_mul_u32_u24_e32 v15, 0x41, v10
	v_lshlrev_b32_e32 v11, 2, v13
	v_lshlrev_b32_e32 v16, 2, v15
	v_add3_u32 v15, 0, v11, v16
	v_add3_u32 v16, 0, v16, v11
	s_lshl_b32 s7, s2, 6
	s_lshl_b32 s6, s46, 6
	v_add_u32_e32 v17, 0x2080, v8
	v_add_u32_e32 v18, 0x2088, v8
	v_lshlrev_b32_e32 v8, 2, v20
	v_lshlrev_b32_e32 v10, 1, v10
	v_add_u32_e32 v19, 0x400, v16
	v_mov_b32_e32 v11, v9
	s_mov_b32 s9, s2
	s_branch .LBB0_873

; #define KP(f) ((decltype(Params::f))karg_ptr<(int)offsetof(Params, f)>())
;     int tid_ = threadIdx.x; asm volatile("" : "+v"(tid_));
;     const int tid = tid_, ntn = N / 64, ntiles = (K / 64) * ntn, nwg = wgn > 0 ? wgn : (int)gridDim.x - wg0;
;     if ((int)blockIdx.x < wg0 || (int)blockIdx.x >= wg0 + nwg) return;
;     const int r = tid >> 4, c4 = (tid & 15) * 4, n = tid >> 3, k8 = (tid & 7) * 8;
;     int t = (int)blockIdx.x - wg0;
;     f32x4 v0, v1; float g0 = 1.f, g1 = 1.f;
;     if (t < ntiles) { const int k0 = (t / ntn) * 64, n0 = (t % ntn) * 64;
;         v0 = *(const f32x4*)(src + (size_t)(k0 + r) * N + n0 + c4); v1 = *(const f32x4*)(src + (size_t)(k0 + r + 32) * N + n0 + c4);
;         if (gain) { g0 = gain[k0 + r]; g1 = gain[k0 + r + 32]; } }
; __device__ __forceinline__ void run_phase(int type, int l, unsigned char* shm) {
;     ...
;         if (l == 0) { if (G >= 256) transpose_convert(KP(w_ff2), DFF, DM, nullptr, KP(Wff2T), (float*)shm, 64, 128);
.LBB0_885:
	s_load_dwordx2 s[10:11], s[0:1], 0xc8
	s_load_dwordx2 s[12:13], s[0:1], 0x118
	s_waitcnt lgkmcnt(0)
	s_sub_i32 s6, s2, 64
	v_mov_b32_e32 v10, v166
	s_cmpk_gt_u32 s6, 0x7f
	s_cbranch_scc1 .LBB0_890
	s_lshl_b32 s7, s6, 2
	v_ashrrev_i32_e32 v12, 4, v10
	s_waitcnt vmcnt(0)
	v_lshlrev_b32_e32 v0, 2, v10
	s_and_b32 s7, s7, 0x1c0
	v_and_b32_e32 v20, 60, v0
	v_add_u32_e32 v0, s7, v12
	s_waitcnt lgkmcnt(0)
	v_ashrrev_i32_e32 v1, 31, v0
	v_lshlrev_b64 v[0:1], 12, v[0:1]
	s_lshl_b32 s7, s2, 8
	v_lshl_add_u64 v[0:1], s[10:11], 0, v[0:1]
	s_and_b32 s14, s7, 0xf00
	s_mov_b32 s15, 0
	v_lshl_add_u64 v[0:1], v[0:1], 0, s[14:15]
	v_mov_b32_e32 v9, 0
	v_lshlrev_b32_e32 v8, 2, v20
	v_lshl_add_u64 v[14:15], v[0:1], 0, v[8:9]
	s_mov_b32 s7, 0x20000
	v_add_co_u32_e32 v16, vcc, s7, v14
	v_ashrrev_i32_e32 v13, 3, v10
	s_nop 0
	v_addc_co_u32_e32 v17, vcc, 0, v15, vcc
	global_load_dwordx4 v[0:3], v[14:15], off
	global_load_dwordx4 v[4:7], v[16:17], off
	v_lshlrev_b32_e32 v10, 3, v10
	s_movk_i32 s7, 0x104
	v_and_b32_e32 v10, 56, v10
	v_mul_lo_u32 v15, v12, s7
	v_add3_u32 v14, 0, v8, v15
	v_add3_u32 v8, 0, v15, v8
	v_mul_u32_u24_e32 v15, 0x41, v10
	v_lshlrev_b32_e32 v11, 2, v13
	v_lshlrev_b32_e32 v16, 2, v15
	s_lshl_b32 s8, s2, 6
	v_add3_u32 v15, 0, v11, v16
	v_add3_u32 v16, 0, v16, v11
	s_lshl_b32 s7, s2, 2
	s_addk_i32 s7, 0x100
	s_addk_i32 s8, 0xf000
	v_add_u32_e32 v17, 0x2080, v8
	v_add_u32_e32 v18, 0x2088, v8
	v_lshlrev_b32_e32 v8, 2, v20
	v_lshlrev_b32_e32 v10, 1, v10
	v_add_u32_e32 v19, 0x400, v16
	v_mov_b32_e32 v11, v9
	s_branch .LBB0_888

; #define KP(f) ((decltype(Params::f))karg_ptr<(int)offsetof(Params, f)>())
;     __device__ bool next(int i, Unit& u) const {
;         const long L = (long)i * G + c; if (L >= nwg) return false;
;         int wgid = (int)L; { const int q = nwg / NXCD, r = nwg % NXCD, xcd = wgid % NXCD, off = wgid / NXCD; wgid = (xcd < r ? xcd * (q + 1) : r * (q + 1) + (xcd - r) * q) + off; }
;         const int nig = WGM * nN, gid = wgid / nig, fm = gid * WGM, gsz = (nM - fm) < WGM ? (nM - fm) : WGM;
;         u.pm = fm + ((wgid % nig) % gsz); u.pn = (wgid % nig) / gsz; return true;
; __device__ __forceinline__ void run_phase(int type, int l, unsigned char* shm) {
;     ...
;         unsigned* rdy = KP(bar) + XCD_BAR_WORDS + 1024 + l * (68 * 64); float* out = KP(out);
;         { pg8::Gemm g{KP(xb), KP(Wff1T), T_P, DFF, DM, DM, DM}; S.init(T_P, DFF, G, c);
;           EpiFF1Pub E{KP(z), KP(ssq), rdy, 0, 0}; pg8::gemm_phase(lds, g, S, E); }
.LBB0_942:
	s_or_b64 exec, exec, s[10:11]
	s_mov_b32 s53, s46
	s_mov_b32 s72, s2
	s_waitcnt lgkmcnt(0)
	s_barrier
	s_load_dwordx2 s[22:23], s[0:1], 0x158
	s_load_dwordx2 s[20:21], s[0:1], 0xd8
	s_load_dwordx2 s[14:15], s[0:1], 0x120
	s_load_dwordx2 s[24:25], s[0:1], 0x110
	s_load_dwordx2 s[16:17], s[0:1], 0x130
	s_waitcnt lgkmcnt(0)
	s_add_u32 s73, s22, 0x4600
	s_load_dwordx2 s[26:27], s[0:1], 0x128
	s_waitcnt lgkmcnt(0)
	s_addc_u32 s74, s23, 0
	v_mov_b32_e32 v8, v166
	s_cmpk_gt_i32 s72, 0x3ff
	v_readfirstlane_b32 s58, v8
	s_cbranch_scc1 .LBB0_965
	s_ashr_i32 s59, s72, 31
	s_lshr_b32 s6, s59, 29
	s_add_i32 s6, s72, s6
	s_and_b32 s7, s6, -8
	s_sub_i32 s7, s72, s7
	s_cmp_gt_i32 s7, -1
	s_cbranch_scc0 .LBB0_945
	s_lshl_b32 s8, s7, 7
	s_cbranch_execz .LBB0_946
	s_branch .LBB0_947

; #define KP(f) ((decltype(Params::f))karg_ptr<(int)offsetof(Params, f)>())
;     __device__ bool next(int i, Unit& u) const {
;         const long L = (long)i * G + c; if (L >= nwg) return false;
;         int wgid = (int)L; { const int q = nwg / NXCD, r = nwg % NXCD, xcd = wgid % NXCD, off = wgid / NXCD; wgid = (xcd < r ? xcd * (q + 1) : r * (q + 1) + (xcd - r) * q) + off; }
;         const int nig = WGM * nN, gid = wgid / nig, fm = gid * WGM, gsz = (nM - fm) < WGM ? (nM - fm) : WGM;
;         u.pm = fm + ((wgid % nig) % gsz); u.pn = (wgid % nig) / gsz; return true;
; __device__ __forceinline__ void run_phase(int type, int l, unsigned char* shm) {
;     ...
;         { pg8::Gemm g{KP(xb) + (size_t)T_P * DM, KP(Wff1T), T_ALL - T_P, DFF, DM, DM, DM}; S.init(T_ALL - T_P, DFF, G, c);
;           EpiFF1Pub E{KP(z), KP(ssq), rdy, T_P, 64}; pg8::gemm_phase(lds, g, S, E); }
.LBB0_965:
	s_load_dwordx2 s[10:11], s[0:1], 0x120
	s_load_dwordx2 s[16:17], s[0:1], 0x110
	s_load_dwordx2 s[12:13], s[0:1], 0x130
	s_load_dwordx2 s[18:19], s[0:1], 0x128
	s_waitcnt lgkmcnt(0)
	v_mov_b32_e32 v8, v166
	s_cmp_gt_i32 s72, 63
	v_readfirstlane_b32 s56, v8
	s_cbranch_scc1 .LBB0_988
	s_ashr_i32 s57, s72, 31
	s_lshr_b32 s6, s57, 29
	s_add_i32 s6, s72, s6
	s_and_b32 s7, s6, -8
	s_sub_i32 s7, s72, s7
	s_cmp_gt_i32 s7, -1
	s_cbranch_scc0 .LBB0_968
	s_lshl_b32 s8, s7, 3
	s_cbranch_execz .LBB0_969
	s_branch .LBB0_970

; #define KP(f) ((decltype(Params::f))karg_ptr<(int)offsetof(Params, f)>())
;     __device__ bool next(int i, Unit& u) const {
;         const long L = (long)i * G + c; if (L >= nwg) return false;
;         int wgid = (int)L; { const int q = nwg / NXCD, r = nwg % NXCD, xcd = wgid % NXCD, off = wgid / NXCD; wgid = (xcd < r ? xcd * (q + 1) : r * (q + 1) + (xcd - r) * q) + off; }
;         const int nig = WGM * nN, gid = wgid / nig, fm = gid * WGM, gsz = (nM - fm) < WGM ? (nM - fm) : WGM;
;         u.pm = fm + ((wgid % nig) % gsz); u.pn = (wgid % nig) / gsz; return true;
; __device__ __forceinline__ void run_phase(int type, int l, unsigned char* shm) {
;     ...
;         { pg8::Gemm g{KP(z), KP(Wff2T), T_P, DM, DFF, DFF, DFF}; S.init(T_P, DM, G, c);
;           EpiRes E{out, nullptr, out, KP(xb), KP(ssq)}; pg8::gemm_phase(lds, g, S, E, rdy, 128u); }
.LBB0_988:
	s_load_dwordx2 s[18:19], s[0:1], 0x130
	s_load_dwordx2 s[24:25], s[0:1], 0x118
	s_load_dwordx2 s[26:27], s[0:1], 0x120
	s_load_dwordx2 s[28:29], s[0:1], 0x128
	s_waitcnt lgkmcnt(0)
	v_mov_b32_e32 v8, v166
	s_cmpk_lt_i32 s72, 0x100
	s_cselect_b64 s[10:11], -1, 0
	s_cmpk_gt_i32 s72, 0xff
	v_readfirstlane_b32 s75, v8
	s_cbranch_scc1 .LBB0_994
	s_ashr_i32 s6, s72, 31
	s_lshr_b32 s6, s6, 29
	s_add_i32 s8, s72, s6
	s_and_b32 s6, s8, -8
	s_sub_i32 s6, s72, s6
	s_cmp_gt_i32 s6, -1
	s_cbranch_scc0 .LBB0_991
	s_lshl_b32 s7, s6, 5
	s_ashr_i32 s8, s8, 3
	s_cbranch_execz .LBB0_992
	s_branch .LBB0_993

; #define KP(f) ((decltype(Params::f))karg_ptr<(int)offsetof(Params, f)>())
;     int G = gridDim.x, c = ((int)blockIdx.x - cbase + (int)gridDim.x) % (int)gridDim.x; asm volatile("" : "+s"(G), "+s"(c));
;     const int Kq = Ktot >> 2;
;     pg8::StaticOrder S;
; #pragma unroll 1
;     for (int kq = 0; kq < 4; ++kq) {
;         pg8::Gemm g{A + (size_t)kq * Kq, Bt + (size_t)kq * Kq, 1024, DM, Kq, lda, Ktot};
;         S.init(1024, DM, G, (c - 16 * kq + G) % G);
;         EpiPartial E{part + (size_t)kq * 1024 * DM};
;         pg8::gemm_phase(lds, g, S, E, ready, need, npan);
; __device__ __forceinline__ void run_phase(int type, int l, unsigned char* shm) {
;     ...
;         sample_splitk(lds, KP(z) + (size_t)T_P * DFF, DFF, KP(Wff2T), DFF, out + (size_t)T_P * DM, out + (size_t)T_P * DM, KP(xb) + (size_t)T_P * DM, KP(ssq) + (size_t)T_P * 16,
;                       (float*)KP(sc_a), KP(bar) + XCD_BAR_WORDS + (l * 2 + 1) * 256, G > 64 ? G - 64 : 0, rdy + 64 * 64, 128u);
.LBB0_1056:
	s_load_dwordx2 s[6:7], s[0:1], 0x130
	s_waitcnt lgkmcnt(0)
	s_add_u32 s71, s6, 0x8000000
	s_addc_u32 s72, s7, 0
	s_max_i32 s6, s53, 64
	s_add_u32 s73, s22, 0x8600
	v_readlane_b32 s7, v230, 8
	s_addc_u32 s74, s23, 0
	s_sub_i32 s6, s7, s6
	s_ashr_i32 s7, s6, 31
	s_abs_i32 s6, s6
	v_readlane_b32 s8, v230, 9
	s_mul_hi_u32 s8, s6, s8
	s_mul_i32 s8, s8, s51
	s_sub_i32 s6, s6, s8
	s_sub_i32 s8, s6, s51
	s_cmp_ge_u32 s6, s51
	s_cselect_b32 s6, s8, s6
	s_sub_i32 s8, s6, s51
	s_load_dwordx2 s[24:25], s[0:1], 0x118
	s_cmp_ge_u32 s6, s51
	s_load_dwordx2 s[16:17], s[0:1], 0x120
	s_cselect_b32 s6, s8, s6
	s_load_dwordx2 s[12:13], s[0:1], 0x128
	s_xor_b32 s6, s6, s7
	s_load_dwordx2 s[14:15], s[0:1], 0x140
	s_sub_i32 s70, s6, s7
	s_mov_b32 s75, s46
	s_load_dwordx2 s[18:19], s[0:1], 0x158
	s_waitcnt lgkmcnt(0)
	s_abs_i32 s76, s75
	v_cvt_f32_u32_e32 v0, s76
	s_sub_i32 s6, 0, s76
	s_add_i32 s77, s75, s70
	s_ashr_i32 s81, s75, 31
	v_rcp_iflag_f32_e32 v0, v0
	s_mov_b32 s23, 0
	v_mov_b32_e32 v129, 0
	s_mov_b64 s[26:27], 0x80
	v_mul_f32_e32 v0, 0x4f7ffffe, v0
	v_cvt_u32_f32_e32 v0, v0
	v_mov_b32_e32 v132, 1
	s_mov_b32 s83, 0
	v_readfirstlane_b32 s7, v0
	s_mul_i32 s6, s6, s7
	s_mul_hi_u32 s6, s7, s6
	s_add_i32 s82, s7, s6
	s_branch .LBB0_1059

; #define KP(f) ((decltype(Params::f))karg_ptr<(int)offsetof(Params, f)>())
;     int tid_ = threadIdx.x; asm volatile("" : "+v"(tid_));
;     const int tid = tid_, ntn = N / 64, ntiles = (K / 64) * ntn, nwg = wgn > 0 ? wgn : (int)gridDim.x - wg0;
;     if ((int)blockIdx.x < wg0 || (int)blockIdx.x >= wg0 + nwg) return;
;     const int r = tid >> 4, c4 = (tid & 15) * 4, n = tid >> 3, k8 = (tid & 7) * 8;
;     int t = (int)blockIdx.x - wg0;
;     f32x4 v0, v1; float g0 = 1.f, g1 = 1.f;
;     if (t < ntiles) { const int k0 = (t / ntn) * 64, n0 = (t % ntn) * 64;
;         v0 = *(const f32x4*)(src + (size_t)(k0 + r) * N + n0 + c4); v1 = *(const f32x4*)(src + (size_t)(k0 + r + 32) * N + n0 + c4);
;         if (gain) { g0 = gain[k0 + r]; g1 = gain[k0 + r + 32]; } }
; __device__ __forceinline__ void run_phase(int type, int l, unsigned char* shm) {
;     ...
;         } else if (l == 0) {
;             transpose_convert(KP(w_in) + (size_t)DM * DIN, DM, DIN, KP(norm1_g) + DM, KP(WinT), (float*)shm);
.LBB0_1121:
	s_load_dwordx2 s[14:15], s[0:1], 48
	s_load_dwordx2 s[12:13], s[0:1], 40
	s_load_dwordx2 s[10:11], s[0:1], 0xe0
	s_waitcnt lgkmcnt(0)
	v_readlane_b32 s6, v230, 2
	v_readlane_b32 s7, v230, 3
	v_mov_b32_e32 v12, v166
	s_and_b64 vcc, exec, s[6:7]
	s_cbranch_vccnz .LBB0_1129
	s_cmpk_gt_u32 s2, 0x43f
	s_cbranch_scc1 .LBB0_1129
	s_add_u32 s8, s14, 0x1100000
	s_addc_u32 s9, s15, 0
	s_add_u32 s12, s12, 0x1000
	s_mul_i32 s6, s2, 0xf0f1
	s_addc_u32 s13, s13, 0
	s_lshr_b32 s7, s6, 22
	s_lshr_b32 s6, s6, 16
	v_ashrrev_i32_e32 v15, 4, v12
	s_and_b32 s6, s6, 0xffc0
	s_mulk_i32 s7, 0x44
	v_lshlrev_b32_e32 v0, 2, v12
	s_sub_i32 s7, s2, s7
	v_add_u32_e32 v16, s6, v15
	s_movk_i32 s6, 0x4400
	v_mov_b64_e32 v[8:9], s[8:9]
	v_and_b32_e32 v24, 60, v0
	s_waitcnt lgkmcnt(0)
	v_mad_i64_i32 v[0:1], s[8:9], v16, s6, v[8:9]
	s_lshl_b32 s7, s7, 8
	s_and_b32 s8, s7, 0x3ff00
	s_mov_b32 s9, 0
	v_lshl_add_u64 v[0:1], v[0:1], 0, s[8:9]
	v_mov_b32_e32 v11, 0
	v_lshlrev_b32_e32 v10, 2, v24
	v_add_u32_e32 v20, 32, v16
	v_lshl_add_u64 v[18:19], v[0:1], 0, v[10:11]
	v_mad_i64_i32 v[0:1], s[14:15], v20, s6, v[8:9]
	v_ashrrev_i32_e32 v17, 31, v16
	v_ashrrev_i32_e32 v21, 31, v20
	v_lshl_add_u64 v[0:1], v[0:1], 0, s[8:9]
	v_lshl_add_u64 v[22:23], v[0:1], 0, v[10:11]
	global_load_dwordx4 v[0:3], v[18:19], off
	global_load_dwordx4 v[4:7], v[22:23], off
	v_lshl_add_u64 v[18:19], v[20:21], 2, s[12:13]
	v_lshl_add_u64 v[20:21], v[16:17], 2, s[12:13]
	global_load_dword v14, v[20:21], off
	global_load_dword v16, v[18:19], off
	v_ashrrev_i32_e32 v17, 3, v12
	v_lshlrev_b32_e32 v12, 3, v12
	s_movk_i32 s7, 0x104
	v_and_b32_e32 v26, 56, v12
	v_mul_lo_u32 v13, v15, s7
	v_add3_u32 v18, 0, v10, v13
	v_add3_u32 v10, 0, v13, v10
	v_mul_u32_u24_e32 v13, 0x41, v26
	v_lshlrev_b32_e32 v12, 2, v17
	v_lshlrev_b32_e32 v13, 2, v13
	v_add3_u32 v19, 0, v12, v13
	v_add3_u32 v20, 0, v13, v12
	s_lshl_b32 s8, s2, 6
	s_lshl_b32 s7, s46, 6
	v_add_u32_e32 v21, 0x2080, v10
	v_add_u32_e32 v22, 0x2088, v10
	v_lshlrev_b32_e32 v12, 2, v24
	v_lshlrev_b32_e32 v10, 1, v26
	s_mov_b32 s18, s2
	s_branch .LBB0_1125

; #define KP(f) ((decltype(Params::f))karg_ptr<(int)offsetof(Params, f)>())
;     int tid_ = threadIdx.x; asm volatile("" : "+v"(tid_));
;     const int tid = tid_, ntn = N / 64, ntiles = (K / 64) * ntn, nwg = wgn > 0 ? wgn : (int)gridDim.x - wg0;
;     if ((int)blockIdx.x < wg0 || (int)blockIdx.x >= wg0 + nwg) return;
;     const int r = tid >> 4, c4 = (tid & 15) * 4, n = tid >> 3, k8 = (tid & 7) * 8;
;     int t = (int)blockIdx.x - wg0;
;     f32x4 v0, v1; float g0 = 1.f, g1 = 1.f;
;     if (t < ntiles) { const int k0 = (t / ntn) * 64, n0 = (t % ntn) * 64;
;         v0 = *(const f32x4*)(src + (size_t)(k0 + r) * N + n0 + c4); v1 = *(const f32x4*)(src + (size_t)(k0 + r + 32) * N + n0 + c4);
;         if (gain) { g0 = gain[k0 + r]; g1 = gain[k0 + r + 32]; } }
; __device__ __forceinline__ void run_phase(int type, int l, unsigned char* shm) {
;     ...
;             transpose_convert(KP(w_b_up) + (size_t)512 * DM, 512, DM, nullptr, KP(BupT), (float*)shm);
.LBB0_1129:
	s_load_dwordx2 s[12:13], s[0:1], 0xa8
	s_load_dwordx2 s[10:11], s[0:1], 0xf8
	s_waitcnt lgkmcnt(0)
	v_readlane_b32 s6, v230, 2
	v_readlane_b32 s7, v230, 3
	v_mov_b32_e32 v10, v166
	s_and_b64 vcc, exec, s[6:7]
	s_cbranch_vccnz .LBB0_1137
	s_cmpk_gt_u32 s2, 0x7f
	s_cbranch_scc1 .LBB0_1137
	s_add_u32 s12, s12, 0x200000
	s_addc_u32 s13, s13, 0
	s_lshl_b32 s6, s2, 2
	v_ashrrev_i32_e32 v12, 4, v10
	s_waitcnt vmcnt(0)
	v_lshlrev_b32_e32 v0, 2, v10
	s_and_b32 s6, s6, 0x1c0
	v_and_b32_e32 v20, 60, v0
	v_add_u32_e32 v0, s6, v12
	s_waitcnt lgkmcnt(0)
	v_ashrrev_i32_e32 v1, 31, v0
	v_lshlrev_b64 v[0:1], 12, v[0:1]
	s_lshl_b32 s6, s2, 8
	v_lshl_add_u64 v[0:1], s[12:13], 0, v[0:1]
	s_and_b32 s6, s6, 0xf00
	s_mov_b32 s7, 0
	v_lshl_add_u64 v[0:1], v[0:1], 0, s[6:7]
	v_mov_b32_e32 v9, 0
	v_lshlrev_b32_e32 v8, 2, v20
	v_lshl_add_u64 v[14:15], v[0:1], 0, v[8:9]
	s_mov_b32 s6, 0x20000
	v_add_co_u32_e32 v16, vcc, s6, v14
	v_ashrrev_i32_e32 v13, 3, v10
	s_nop 0
	v_addc_co_u32_e32 v17, vcc, 0, v15, vcc
	global_load_dwordx4 v[0:3], v[14:15], off
	global_load_dwordx4 v[4:7], v[16:17], off
	v_lshlrev_b32_e32 v10, 3, v10
	s_movk_i32 s6, 0x104
	v_and_b32_e32 v10, 56, v10
	v_mul_lo_u32 v15, v12, s6
	v_add3_u32 v14, 0, v8, v15
	v_add3_u32 v8, 0, v15, v8
	v_mul_u32_u24_e32 v15, 0x41, v10
	v_lshlrev_b32_e32 v11, 2, v13
	v_lshlrev_b32_e32 v16, 2, v15
	v_add3_u32 v15, 0, v11, v16
	v_add3_u32 v16, 0, v16, v11
	s_lshl_b32 s7, s2, 6
	s_lshl_b32 s6, s46, 6
	v_add_u32_e32 v17, 0x2080, v8
	v_add_u32_e32 v18, 0x2088, v8
	v_lshlrev_b32_e32 v8, 2, v20
	v_lshlrev_b32_e32 v10, 1, v10
	v_add_u32_e32 v19, 0x400, v16
	v_mov_b32_e32 v11, v9
	s_mov_b32 s9, s2
	s_branch .LBB0_1133

; #define KP(f) ((decltype(Params::f))karg_ptr<(int)offsetof(Params, f)>())
;     int tid_ = threadIdx.x; asm volatile("" : "+v"(tid_));
;     const int tid = tid_, ntn = N / 64, ntiles = (K / 64) * ntn, nwg = wgn > 0 ? wgn : (int)gridDim.x - wg0;
;     if ((int)blockIdx.x < wg0 || (int)blockIdx.x >= wg0 + nwg) return;
;     const int r = tid >> 4, c4 = (tid & 15) * 4, n = tid >> 3, k8 = (tid & 7) * 8;
;     int t = (int)blockIdx.x - wg0;
;     f32x4 v0, v1; float g0 = 1.f, g1 = 1.f;
;     if (t < ntiles) { const int k0 = (t / ntn) * 64, n0 = (t % ntn) * 64;
;         v0 = *(const f32x4*)(src + (size_t)(k0 + r) * N + n0 + c4); v1 = *(const f32x4*)(src + (size_t)(k0 + r + 32) * N + n0 + c4);
;         if (gain) { g0 = gain[k0 + r]; g1 = gain[k0 + r + 32]; } }
; __device__ __forceinline__ void run_phase(int type, int l, unsigned char* shm) {
;     ...
;             transpose_convert(KP(w_a_up) + (size_t)512 * DM, 512, DM, nullptr, KP(AupT), (float*)shm);
.LBB0_1137:
	s_load_dwordx2 s[12:13], s[0:1], 0x90
	s_load_dwordx2 s[10:11], s[0:1], 0x100
	s_waitcnt lgkmcnt(0)
	v_readlane_b32 s6, v230, 2
	v_readlane_b32 s7, v230, 3
	v_mov_b32_e32 v10, v166
	s_and_b64 vcc, exec, s[6:7]
	s_cbranch_vccnz .LBB0_1145
	s_cmpk_gt_u32 s2, 0x7f
	s_cbranch_scc1 .LBB0_1145
	s_add_u32 s12, s12, 0x200000
	s_addc_u32 s13, s13, 0
	s_lshl_b32 s6, s2, 2
	v_ashrrev_i32_e32 v12, 4, v10
	s_waitcnt vmcnt(0)
	v_lshlrev_b32_e32 v0, 2, v10
	s_and_b32 s6, s6, 0x1c0
	v_and_b32_e32 v20, 60, v0
	v_add_u32_e32 v0, s6, v12
	s_waitcnt lgkmcnt(0)
	v_ashrrev_i32_e32 v1, 31, v0
	v_lshlrev_b64 v[0:1], 12, v[0:1]
	s_lshl_b32 s6, s2, 8
	v_lshl_add_u64 v[0:1], s[12:13], 0, v[0:1]
	s_and_b32 s6, s6, 0xf00
	s_mov_b32 s7, 0
	v_lshl_add_u64 v[0:1], v[0:1], 0, s[6:7]
	v_mov_b32_e32 v9, 0
	v_lshlrev_b32_e32 v8, 2, v20
	v_lshl_add_u64 v[14:15], v[0:1], 0, v[8:9]
	s_mov_b32 s6, 0x20000
	v_add_co_u32_e32 v16, vcc, s6, v14
	v_ashrrev_i32_e32 v13, 3, v10
	s_nop 0
	v_addc_co_u32_e32 v17, vcc, 0, v15, vcc
	global_load_dwordx4 v[0:3], v[14:15], off
	global_load_dwordx4 v[4:7], v[16:17], off
	v_lshlrev_b32_e32 v10, 3, v10
	s_movk_i32 s6, 0x104
	v_and_b32_e32 v10, 56, v10
	v_mul_lo_u32 v15, v12, s6
	v_add3_u32 v14, 0, v8, v15
	v_add3_u32 v8, 0, v15, v8
	v_mul_u32_u24_e32 v15, 0x41, v10
	v_lshlrev_b32_e32 v11, 2, v13
	v_lshlrev_b32_e32 v16, 2, v15
	v_add3_u32 v15, 0, v11, v16
	v_add3_u32 v16, 0, v16, v11
	s_lshl_b32 s7, s2, 6
	s_lshl_b32 s6, s46, 6
	v_add_u32_e32 v17, 0x2080, v8
	v_add_u32_e32 v18, 0x2088, v8
	v_lshlrev_b32_e32 v8, 2, v20
	v_lshlrev_b32_e32 v10, 1, v10
	v_add_u32_e32 v19, 0x400, v16
	v_mov_b32_e32 v11, v9
	s_mov_b32 s9, s2
	s_branch .LBB0_1141

; #define KP(f) ((decltype(Params::f))karg_ptr<(int)offsetof(Params, f)>())
;     int tid_ = threadIdx.x; asm volatile("" : "+v"(tid_));
;     const int tid = tid_, ntn = N / 64, ntiles = (K / 64) * ntn, nwg = wgn > 0 ? wgn : (int)gridDim.x - wg0;
;     if ((int)blockIdx.x < wg0 || (int)blockIdx.x >= wg0 + nwg) return;
;     const int r = tid >> 4, c4 = (tid & 15) * 4, n = tid >> 3, k8 = (tid & 7) * 8;
;     int t = (int)blockIdx.x - wg0;
;     f32x4 v0, v1; float g0 = 1.f, g1 = 1.f;
;     if (t < ntiles) { const int k0 = (t / ntn) * 64, n0 = (t % ntn) * 64;
;         v0 = *(const f32x4*)(src + (size_t)(k0 + r) * N + n0 + c4); v1 = *(const f32x4*)(src + (size_t)(k0 + r + 32) * N + n0 + c4);
;         if (gain) { g0 = gain[k0 + r]; g1 = gain[k0 + r + 32]; } }
; __device__ __forceinline__ void run_phase(int type, int l, unsigned char* shm) {
;     ...
;             transpose_convert(KP(w_o) + (size_t)DM * DM, DM, DM, nullptr, KP(WoT), (float*)shm);
.LBB0_1145:
	s_load_dwordx2 s[12:13], s[0:1], 0xb0
	s_load_dwordx2 s[10:11], s[0:1], 0x108
	s_waitcnt lgkmcnt(0)
	v_readlane_b32 s6, v230, 2
	v_readlane_b32 s7, v230, 3
	v_mov_b32_e32 v10, v166
	s_and_b64 vcc, exec, s[6:7]
	s_cbranch_vccnz .LBB0_1183
	s_cmpk_gt_u32 s2, 0xff
	s_cbranch_scc1 .LBB0_1160
	s_add_u32 s12, s12, 0x400000
	s_addc_u32 s13, s13, 0
	s_lshl_b32 s6, s2, 2
	v_ashrrev_i32_e32 v12, 4, v10
	s_waitcnt vmcnt(0)
	v_lshlrev_b32_e32 v0, 2, v10
	s_and_b32 s6, s6, 0x3c0
	v_and_b32_e32 v20, 60, v0
	v_add_u32_e32 v0, s6, v12
	s_waitcnt lgkmcnt(0)
	v_ashrrev_i32_e32 v1, 31, v0
	v_lshlrev_b64 v[0:1], 12, v[0:1]
	s_lshl_b32 s6, s2, 8
	v_lshl_add_u64 v[0:1], s[12:13], 0, v[0:1]
	s_and_b32 s6, s6, 0xf00
	s_mov_b32 s7, 0
	v_lshl_add_u64 v[0:1], v[0:1], 0, s[6:7]
	v_mov_b32_e32 v9, 0
	v_lshlrev_b32_e32 v8, 2, v20
	v_lshl_add_u64 v[14:15], v[0:1], 0, v[8:9]
	s_mov_b32 s6, 0x20000
	v_add_co_u32_e32 v16, vcc, s6, v14
	v_ashrrev_i32_e32 v13, 3, v10
	s_nop 0
	v_addc_co_u32_e32 v17, vcc, 0, v15, vcc
	global_load_dwordx4 v[0:3], v[14:15], off
	global_load_dwordx4 v[4:7], v[16:17], off
	v_lshlrev_b32_e32 v10, 3, v10
	s_movk_i32 s6, 0x104
	v_and_b32_e32 v10, 56, v10
	v_mul_lo_u32 v15, v12, s6
	v_add3_u32 v14, 0, v8, v15
	v_add3_u32 v8, 0, v15, v8
	v_mul_u32_u24_e32 v15, 0x41, v10
	v_lshlrev_b32_e32 v11, 2, v13
	v_lshlrev_b32_e32 v16, 2, v15
	v_add3_u32 v15, 0, v11, v16
	v_add3_u32 v16, 0, v16, v11
	s_lshl_b32 s7, s2, 6
	s_lshl_b32 s6, s46, 6
	v_add_u32_e32 v17, 0x2080, v8
	v_add_u32_e32 v18, 0x2088, v8
	v_lshlrev_b32_e32 v8, 2, v20
	v_lshlrev_b32_e32 v10, 1, v10
	v_add_u32_e32 v19, 0x400, v16
	v_mov_b32_e32 v11, v9
	s_mov_b32 s9, s2
	s_branch .LBB0_1149

; __device__ __forceinline__ bf16_t f2bf(float f) { return (bf16_t)(pk2(f, 0.f) & 0xffffu); }
; #define KP(f) ((decltype(Params::f))karg_ptr<(int)offsetof(Params, f)>())
;     const int nwg_ = wgn > 0 ? wgn : (int)gridDim.x - wg0;
;     if ((int)blockIdx.x < wg0 || (int)blockIdx.x >= wg0 + nwg_) return;
;     const int gtid = ((int)blockIdx.x - wg0) * 512 + threadIdx.x, nth = nwg_ * 512;
;     { const float* wd = KP(w_decay2) + (size_t)l * 64 * 512; const float* wa = KP(w_a2) + (size_t)l * 64 * 512; const float* wg = KP(w_g2) + (size_t)l * 128 * 512;
;       bf16_t* LoraT = KP(LoraT);
;       for (int i = gtid; i < 1536 * 256; i += nth) { const int n = i >> 8, k = i & 255; float v = 0.f;
;         if (n < 512) { if (k < 64) v = wd[k * 512 + n]; }
;         else if (n < 1024) { if (k >= 64 && k < 128) v = wa[(k - 64) * 512 + (n - 512)]; }
;         else { if (k >= 128) v = wg[(k - 128) * 512 + (n - 1024)]; }
;         LoraT[i] = f2bf(v); } }
.LBB0_1160:
	s_load_dwordx2 s[16:17], s[0:1], 0x48
	s_load_dwordx2 s[10:11], s[0:1], 0x58
	s_load_dwordx2 s[12:13], s[0:1], 0x60
	s_load_dwordx2 s[22:23], s[0:1], 0xe8
	s_waitcnt lgkmcnt(0)
	s_waitcnt vmcnt(0)
	v_lshl_add_u32 v0, s2, 9, v166
	s_mov_b32 s6, 0x60000
	v_cmp_gt_i32_e32 vcc, s6, v0
	s_waitcnt lgkmcnt(0)
	v_ashrrev_i32_e32 v1, 31, v0
	s_and_saveexec_b64 s[14:15], vcc
	s_cbranch_execz .LBB0_1177
	s_add_u32 s16, s16, 0x20000
	v_mov_b32_e32 v2, 9
	s_addc_u32 s17, s17, 0
	s_movk_i32 s6, 0x7f
	v_lshlrev_b32_sdwa v6, v2, v166 dst_sel:DWORD dst_unused:UNUSED_PAD src0_sel:DWORD src1_sel:BYTE_0
	v_mov_b32_e32 v2, 64
	s_ashr_i32 s53, s52, 31
	v_cmp_gt_u32_sdwa s[18:19], v166, s6 src0_sel:BYTE_0 src1_sel:DWORD
	v_cmp_lt_u32_sdwa s[20:21], v166, v2 src0_sel:BYTE_0 src1_sel:DWORD
	v_lshl_add_u64 v[2:3], v[0:1], 1, s[22:23]
	s_lshl_b64 s[22:23], s[52:53], 1
	s_mov_b64 s[24:25], 0
	s_movk_i32 s6, 0x1ff
	s_movk_i32 s7, 0x3ff
	v_mov_b32_e32 v5, 0
	s_mov_b32 s8, 0x5ffff
	v_mov_b32_e32 v7, v0
	s_branch .LBB0_1164

; __device__ __forceinline__ bf16_t f2bf(float f) { return (bf16_t)(pk2(f, 0.f) & 0xffffu); }
; #define KP(f) ((decltype(Params::f))karg_ptr<(int)offsetof(Params, f)>())
;     ...
;     { const float* wp = KP(w_pool) + (size_t)l * 4 * 128 * 128; bf16_t* PoolT = KP(PoolT);
;       for (int i = gtid; i < 512 * 512; i += nth) { const int n = i >> 9, k = i & 511; const int g = n >> 7, d = n & 127; float v = 0.f;
;         if ((k >> 7) == g) v = wp[(g * 128 + (k & 127)) * 128 + d];
;         PoolT[i] = f2bf(v); } }
.LBB0_1177:
	s_or_b64 exec, exec, s[14:15]
	s_load_dwordx2 s[12:13], s[0:1], 0x98
	s_load_dwordx2 s[14:15], s[0:1], 0xf0
	s_waitcnt lgkmcnt(0)
	s_mov_b32 s6, 0x40000
	v_cmp_gt_i32_e32 vcc, s6, v0
	s_and_saveexec_b64 s[10:11], vcc
	s_cbranch_execz .LBB0_1182
	s_add_u32 s12, s12, 0x40000
	s_addc_u32 s13, s13, 0
	v_lshlrev_b32_e32 v2, 7, v166
	s_ashr_i32 s53, s52, 31
	v_lshl_add_u32 v6, s2, 16, v2
	s_lshl_b32 s6, s46, 16
	v_lshl_add_u64 v[2:3], v[0:1], 1, s[14:15]
	s_lshl_b64 s[14:15], s[52:53], 1
	s_mov_b64 s[16:17], 0
	v_mov_b32_e32 v5, 0
	s_mov_b32 s7, 0x3ffff
	v_mov_b32_e32 v1, 14
	s_branch .LBB0_1180

; #define KP(f) ((decltype(Params::f))karg_ptr<(int)offsetof(Params, f)>())
;     int tid_ = threadIdx.x; asm volatile("" : "+v"(tid_));
;     const int tid = tid_, ntn = N / 64, ntiles = (K / 64) * ntn, nwg = wgn > 0 ? wgn : (int)gridDim.x - wg0;
;     if ((int)blockIdx.x < wg0 || (int)blockIdx.x >= wg0 + nwg) return;
;     const int r = tid >> 4, c4 = (tid & 15) * 4, n = tid >> 3, k8 = (tid & 7) * 8;
;     int t = (int)blockIdx.x - wg0;
;     f32x4 v0, v1; float g0 = 1.f, g1 = 1.f;
;     if (t < ntiles) { const int k0 = (t / ntn) * 64, n0 = (t % ntn) * 64;
;         v0 = *(const f32x4*)(src + (size_t)(k0 + r) * N + n0 + c4); v1 = *(const f32x4*)(src + (size_t)(k0 + r + 32) * N + n0 + c4);
;         if (gain) { g0 = gain[k0 + r]; g1 = gain[k0 + r + 32]; } }
; __device__ __forceinline__ void run_phase(int type, int l, unsigned char* shm) {
;     ...
;             transpose_convert(KP(w_in) + (size_t)DM * DIN, DM, DIN, KP(norm1_g) + DM, KP(WinT), (float*)shm, 64, 128);
.LBB0_1184:
	s_load_dwordx2 s[14:15], s[0:1], 48
	s_load_dwordx2 s[16:17], s[0:1], 40
	s_load_dwordx2 s[10:11], s[0:1], 0xe0
	s_waitcnt lgkmcnt(0)
	s_sub_i32 s6, s2, 64
	s_cmpk_lt_u32 s6, 0x80
	v_mov_b32_e32 v10, v166
	s_cselect_b64 s[12:13], -1, 0
	s_cmpk_gt_u32 s6, 0x7f
	s_cbranch_scc1 .LBB0_1189
	s_add_u32 s14, s14, 0x1100000
	s_addc_u32 s15, s15, 0
	s_add_u32 s16, s16, 0x1000
	s_addc_u32 s17, s17, 0
	s_cmpk_gt_u32 s6, 0x43
	v_ashrrev_i32_e32 v13, 4, v10
	s_waitcnt vmcnt(0)
	v_lshlrev_b32_e32 v0, 2, v10
	s_cselect_b32 s7, 64, 0
	s_add_i32 s8, s2, 0xff7c
	v_and_b32_e32 v22, 60, v0
	s_cmpk_lt_u32 s6, 0x44
	v_add_u32_e32 v14, s7, v13
	s_movk_i32 s7, 0x4400
	s_waitcnt lgkmcnt(0)
	v_mov_b64_e32 v[0:1], s[14:15]
	s_cselect_b32 s18, s6, s8
	v_mad_i64_i32 v[2:3], s[8:9], v14, s7, v[0:1]
	s_lshl_b32 s8, s18, 8
	s_mov_b32 s19, 0
	s_and_b32 s18, s8, 0xffff00
	v_add_u32_e32 v18, 32, v14
	v_lshl_add_u64 v[2:3], v[2:3], 0, s[18:19]
	v_mov_b32_e32 v9, 0
	v_lshlrev_b32_e32 v8, 2, v22
	v_mad_i64_i32 v[0:1], s[8:9], v18, s7, v[0:1]
	v_ashrrev_i32_e32 v15, 31, v14
	v_lshl_add_u64 v[16:17], v[2:3], 0, v[8:9]
	v_ashrrev_i32_e32 v19, 31, v18
	v_lshl_add_u64 v[0:1], v[0:1], 0, s[18:19]
	v_lshl_add_u64 v[20:21], v[0:1], 0, v[8:9]
	global_load_dwordx4 v[0:3], v[16:17], off
	global_load_dwordx4 v[4:7], v[20:21], off
	v_lshl_add_u64 v[16:17], v[18:19], 2, s[16:17]
	v_lshl_add_u64 v[18:19], v[14:15], 2, s[16:17]
	global_load_dword v12, v[18:19], off
	global_load_dword v14, v[16:17], off
	v_ashrrev_i32_e32 v11, 3, v10
	v_lshlrev_b32_e32 v10, 3, v10
	s_movk_i32 s8, 0x104
	v_and_b32_e32 v24, 56, v10
	v_mul_lo_u32 v16, v13, s8
	v_add3_u32 v15, 0, v8, v16
	v_add3_u32 v8, 0, v16, v8
	v_mul_u32_u24_e32 v16, 0x41, v24
	v_lshlrev_b32_e32 v10, 2, v11
	v_lshlrev_b32_e32 v17, 2, v16
	s_lshl_b32 s8, s2, 6
	v_add3_u32 v16, 0, v10, v17
	v_add3_u32 v17, 0, v17, v10
	v_add_u32_e32 v10, s8, v11
	v_add_u32_e32 v18, 0xfffff000, v10
	s_addk_i32 s8, 0x1000
	v_add_u32_e32 v19, 0x2080, v8
	v_add_u32_e32 v20, 0x2088, v8
	v_lshlrev_b32_e32 v10, 2, v22
	v_lshlrev_b32_e32 v8, 1, v24
	s_mov_b32 s22, s6
	s_branch .LBB0_1187

; #define KP(f) ((decltype(Params::f))karg_ptr<(int)offsetof(Params, f)>())
;     int tid_ = threadIdx.x; asm volatile("" : "+v"(tid_));
;     const int tid = tid_, ntn = N / 64, ntiles = (K / 64) * ntn, nwg = wgn > 0 ? wgn : (int)gridDim.x - wg0;
;     if ((int)blockIdx.x < wg0 || (int)blockIdx.x >= wg0 + nwg) return;
;     const int r = tid >> 4, c4 = (tid & 15) * 4, n = tid >> 3, k8 = (tid & 7) * 8;
;     int t = (int)blockIdx.x - wg0;
;     f32x4 v0, v1; float g0 = 1.f, g1 = 1.f;
;     if (t < ntiles) { const int k0 = (t / ntn) * 64, n0 = (t % ntn) * 64;
;         v0 = *(const f32x4*)(src + (size_t)(k0 + r) * N + n0 + c4); v1 = *(const f32x4*)(src + (size_t)(k0 + r + 32) * N + n0 + c4);
;         if (gain) { g0 = gain[k0 + r]; g1 = gain[k0 + r + 32]; } }
;     for (; t < ntiles; t += nwg) {
;         const int k0 = (t / ntn) * 64, n0 = (t % ntn) * 64;
;         tile[r * 65 + c4 + 0] = v0[0] * g0; tile[r * 65 + c4 + 1] = v0[1] * g0; tile[r * 65 + c4 + 2] = v0[2] * g0; tile[r * 65 + c4 + 3] = v0[3] * g0;
;         tile[(r + 32) * 65 + c4 + 0] = v1[0] * g1; tile[(r + 32) * 65 + c4 + 1] = v1[1] * g1; tile[(r + 32) * 65 + c4 + 2] = v1[2] * g1; tile[(r + 32) * 65 + c4 + 3] = v1[3] * g1;
;         const int tn = t + nwg;
;         if (tn < ntiles) { const int k1 = (tn / ntn) * 64, n1 = (tn % ntn) * 64;
;             v0 = *(const f32x4*)(src + (size_t)(k1 + r) * N + n1 + c4); v1 = *(const f32x4*)(src + (size_t)(k1 + r + 32) * N + n1 + c4);
;             if (gain) { g0 = gain[k1 + r]; g1 = gain[k1 + r + 32]; } }
;         RAW_BARRIER();
;         { u32x4 w;
;           w.x = pk2(tile[(k8 + 0) * 65 + n], tile[(k8 + 1) * 65 + n]); w.y = pk2(tile[(k8 + 2) * 65 + n], tile[(k8 + 3) * 65 + n]);
;           w.z = pk2(tile[(k8 + 4) * 65 + n], tile[(k8 + 5) * 65 + n]); w.w = pk2(tile[(k8 + 6) * 65 + n], tile[(k8 + 7) * 65 + n]);
;           *(u32x4*)(dst + (size_t)(n0 + n) * K + k0 + k8) = w; }
;         RAW_BARRIER();
;     }
; __device__ __forceinline__ void run_phase(int type, int l, unsigned char* shm) {
;     ...
;             transpose_convert(KP(w_b_up) + (size_t)512 * DM, 512, DM, nullptr, KP(BupT), (float*)shm, 64, 128);
;             transpose_convert(KP(w_a_up) + (size_t)512 * DM, 512, DM, nullptr, KP(AupT), (float*)shm, 64, 128);
;             transpose_convert(KP(w_o) + (size_t)DM * DM, DM, DM, nullptr, KP(WoT), (float*)shm, 64, 128);
.LBB0_1189:
	s_load_dwordx2 s[16:17], s[0:1], 0xa8
	s_load_dwordx2 s[14:15], s[0:1], 0xf8
	s_waitcnt lgkmcnt(0)
	s_waitcnt vmcnt(0) lgkmcnt(0)
	v_cndmask_b32_e64 v1, 0, 1, s[12:13]
	v_mov_b32_e32 v0, v166
	v_cmp_ne_u32_e64 s[10:11], 1, v1
	s_andn2_b64 vcc, exec, s[12:13]
	s_cbranch_vccnz .LBB0_1191
	s_lshl_b32 s7, s6, 2
	v_ashrrev_i32_e32 v1, 4, v0
	v_lshlrev_b32_e32 v2, 4, v0
	s_and_b32 s7, s7, 0x1c0
	v_and_b32_e32 v10, 0xf0, v2
	v_add_u32_e32 v2, s7, v1
	s_lshl_b32 s8, s2, 6
	v_ashrrev_i32_e32 v3, 31, v2
	s_and_b32 s8, s8, 0x3c0
	v_lshlrev_b64 v[2:3], 12, v[2:3]
	s_mov_b32 s13, 0
	s_lshl_b32 s12, s8, 2
	v_lshl_add_u64 v[2:3], s[16:17], 0, v[2:3]
	v_mov_b32_e32 v11, 0
	v_lshl_add_u64 v[2:3], v[2:3], 0, s[12:13]
	v_lshl_add_u64 v[6:7], v[2:3], 0, v[10:11]
	s_mov_b32 s12, 0x200000
	v_add_co_u32_e32 v2, vcc, s12, v6
	s_mov_b32 s9, 0x220000
	s_nop 0
	v_addc_co_u32_e32 v3, vcc, 0, v7, vcc
	global_load_dwordx4 v[2:5], v[2:3], off
	v_add_co_u32_e32 v6, vcc, s9, v6
	v_ashrrev_i32_e32 v12, 3, v0
	s_nop 0
	v_addc_co_u32_e32 v7, vcc, 0, v7, vcc
	global_load_dwordx4 v[6:9], v[6:7], off
	v_lshlrev_b32_e32 v0, 3, v0
	s_movk_i32 s9, 0x104
	v_and_b32_e32 v13, 56, v0
	v_mul_lo_u32 v1, v1, s9
	v_mul_u32_u24_e32 v14, 0x41, v13
	v_add3_u32 v15, 0, v1, v10
	v_add3_u32 v1, 0, v10, v1
	v_lshlrev_b32_e32 v0, 2, v12
	v_lshlrev_b32_e32 v10, 2, v14
	v_add_u32_e32 v14, 0x2080, v15
	v_add_u32_e32 v15, 0x2088, v15
	v_add3_u32 v16, 0, v0, v10
	v_add3_u32 v10, 0, v10, v0
	s_lshl_b32 s12, s7, 1
	s_waitcnt vmcnt(1)
	ds_write2_b32 v1, v2, v3 offset1:1
	ds_write2_b32 v1, v4, v5 offset0:2 offset1:3
	s_waitcnt vmcnt(0)
	ds_write2_b32 v14, v6, v7 offset1:1
	ds_write2_b32 v15, v8, v9 offset1:1
	s_waitcnt lgkmcnt(0)
	s_barrier
	ds_read_b32 v0, v10 offset:260
	ds_read_b32 v1, v16
	v_add_u32_e32 v4, s8, v12
	v_ashrrev_i32_e32 v5, 31, v4
	v_lshlrev_b64 v[4:5], 10, v[4:5]
	v_lshl_add_u64 v[4:5], s[14:15], 0, v[4:5]
	s_waitcnt lgkmcnt(0)
	v_cvt_pk_bf16_f32 v0, v1, v0
	ds_read2_b32 v[2:3], v10 offset0:130 offset1:195
	v_add_u32_e32 v6, 0x400, v10
	v_lshl_add_u64 v[4:5], v[4:5], 0, s[12:13]
	v_lshlrev_b32_e32 v10, 1, v13
	s_waitcnt lgkmcnt(0)
	v_cvt_pk_bf16_f32 v1, v2, v3
	ds_read2_b32 v[2:3], v6 offset0:4 offset1:69
	v_lshl_add_u64 v[4:5], v[4:5], 0, v[10:11]
	s_waitcnt lgkmcnt(0)
	v_cvt_pk_bf16_f32 v2, v2, v3
	ds_read2_b32 v[6:7], v6 offset0:134 offset1:199
	s_waitcnt lgkmcnt(0)
	v_cvt_pk_bf16_f32 v3, v6, v7
	global_store_dwordx4 v[4:5], v[0:3], off
	s_waitcnt lgkmcnt(0)
	s_barrier
.LBB0_1191:
	s_load_dwordx2 s[16:17], s[0:1], 0x90
	s_load_dwordx2 s[12:13], s[0:1], 0x100
	s_waitcnt lgkmcnt(0)
	s_nop 0
	v_mov_b32_e32 v0, v166
	s_and_b64 vcc, exec, s[10:11]
	s_cbranch_vccnz .LBB0_1193
	s_lshl_b32 s7, s6, 2
	v_ashrrev_i32_e32 v1, 4, v0
	v_lshlrev_b32_e32 v2, 4, v0
	s_and_b32 s7, s7, 0x1c0
	v_and_b32_e32 v10, 0xf0, v2
	v_add_u32_e32 v2, s7, v1
	s_lshl_b32 s8, s2, 6
	v_ashrrev_i32_e32 v3, 31, v2
	s_and_b32 s8, s8, 0x3c0
	v_lshlrev_b64 v[2:3], 12, v[2:3]
	s_mov_b32 s15, 0
	s_lshl_b32 s14, s8, 2
	v_lshl_add_u64 v[2:3], s[16:17], 0, v[2:3]
	v_mov_b32_e32 v11, 0
	v_lshl_add_u64 v[2:3], v[2:3], 0, s[14:15]
	v_lshl_add_u64 v[6:7], v[2:3], 0, v[10:11]
	s_mov_b32 s14, 0x200000
	v_add_co_u32_e32 v2, vcc, s14, v6
	s_mov_b32 s9, 0x220000
	s_nop 0
	v_addc_co_u32_e32 v3, vcc, 0, v7, vcc
	global_load_dwordx4 v[2:5], v[2:3], off
	v_add_co_u32_e32 v6, vcc, s9, v6
	v_ashrrev_i32_e32 v12, 3, v0
	s_nop 0
	v_addc_co_u32_e32 v7, vcc, 0, v7, vcc
	global_load_dwordx4 v[6:9], v[6:7], off
	v_lshlrev_b32_e32 v0, 3, v0
	s_movk_i32 s9, 0x104
	v_and_b32_e32 v13, 56, v0
	v_mul_lo_u32 v1, v1, s9
	v_mul_u32_u24_e32 v14, 0x41, v13
	v_add3_u32 v15, 0, v1, v10
	v_add3_u32 v1, 0, v10, v1
	v_lshlrev_b32_e32 v0, 2, v12
	v_lshlrev_b32_e32 v10, 2, v14
	v_add_u32_e32 v14, 0x2080, v15
	v_add_u32_e32 v15, 0x2088, v15
	v_add3_u32 v16, 0, v0, v10
	v_add3_u32 v10, 0, v10, v0
	s_lshl_b32 s14, s7, 1
	s_waitcnt vmcnt(1)
	ds_write2_b32 v1, v2, v3 offset1:1
	ds_write2_b32 v1, v4, v5 offset0:2 offset1:3
	s_waitcnt vmcnt(0)
	ds_write2_b32 v14, v6, v7 offset1:1
	ds_write2_b32 v15, v8, v9 offset1:1
	s_waitcnt lgkmcnt(0)
	s_barrier
	ds_read_b32 v0, v10 offset:260
	ds_read_b32 v1, v16
	v_add_u32_e32 v4, s8, v12
	v_ashrrev_i32_e32 v5, 31, v4
	v_lshlrev_b64 v[4:5], 10, v[4:5]
	v_lshl_add_u64 v[4:5], s[12:13], 0, v[4:5]
	s_waitcnt lgkmcnt(0)
	v_cvt_pk_bf16_f32 v0, v1, v0
	ds_read2_b32 v[2:3], v10 offset0:130 offset1:195
	v_add_u32_e32 v6, 0x400, v10
	v_lshl_add_u64 v[4:5], v[4:5], 0, s[14:15]
	v_lshlrev_b32_e32 v10, 1, v13
	s_waitcnt lgkmcnt(0)
	v_cvt_pk_bf16_f32 v1, v2, v3
	ds_read2_b32 v[2:3], v6 offset0:4 offset1:69
	v_lshl_add_u64 v[4:5], v[4:5], 0, v[10:11]
	s_waitcnt lgkmcnt(0)
	v_cvt_pk_bf16_f32 v2, v2, v3
	ds_read2_b32 v[6:7], v6 offset0:134 offset1:199
	s_waitcnt lgkmcnt(0)
	v_cvt_pk_bf16_f32 v3, v6, v7
	global_store_dwordx4 v[4:5], v[0:3], off
	s_waitcnt lgkmcnt(0)
	s_barrier
.LBB0_1193:
	s_load_dwordx2 s[14:15], s[0:1], 0xb0
	s_load_dwordx2 s[12:13], s[0:1], 0x108
	s_waitcnt lgkmcnt(0)
	v_mov_b32_e32 v10, v166
	s_and_b64 vcc, exec, s[10:11]
	s_cbranch_vccnz .LBB0_1221
	s_add_u32 s10, s14, 0x400000
	s_addc_u32 s11, s15, 0
	s_lshl_b32 s7, s6, 2
	v_ashrrev_i32_e32 v12, 4, v10
	v_lshlrev_b32_e32 v0, 2, v10
	s_and_b32 s7, s7, 0x1c0
	v_and_b32_e32 v20, 60, v0
	v_add_u32_e32 v0, s7, v12
	v_ashrrev_i32_e32 v1, 31, v0
	v_lshlrev_b64 v[0:1], 12, v[0:1]
	s_lshl_b32 s7, s2, 8
	v_lshl_add_u64 v[0:1], s[10:11], 0, v[0:1]
	s_and_b32 s14, s7, 0xf00
	s_mov_b32 s15, 0
	v_lshl_add_u64 v[0:1], v[0:1], 0, s[14:15]
	v_mov_b32_e32 v9, 0
	v_lshlrev_b32_e32 v8, 2, v20
	v_lshl_add_u64 v[14:15], v[0:1], 0, v[8:9]
	s_mov_b32 s7, 0x20000
	v_add_co_u32_e32 v16, vcc, s7, v14
	v_ashrrev_i32_e32 v13, 3, v10
	s_nop 0
	v_addc_co_u32_e32 v17, vcc, 0, v15, vcc
	global_load_dwordx4 v[0:3], v[14:15], off
	global_load_dwordx4 v[4:7], v[16:17], off
	v_lshlrev_b32_e32 v10, 3, v10
	s_movk_i32 s7, 0x104
	v_and_b32_e32 v10, 56, v10
	v_mul_lo_u32 v15, v12, s7
	v_add3_u32 v14, 0, v8, v15
	v_add3_u32 v8, 0, v15, v8
	v_mul_u32_u24_e32 v15, 0x41, v10
	v_lshlrev_b32_e32 v11, 2, v13
	v_lshlrev_b32_e32 v16, 2, v15
	s_lshl_b32 s8, s2, 6
	v_add3_u32 v15, 0, v11, v16
	v_add3_u32 v16, 0, v16, v11
	s_lshl_b32 s7, s2, 2
	s_addk_i32 s7, 0x100
	s_addk_i32 s8, 0xf000
	v_add_u32_e32 v17, 0x2080, v8
	v_add_u32_e32 v18, 0x2088, v8
	v_lshlrev_b32_e32 v8, 2, v20
	v_lshlrev_b32_e32 v10, 1, v10
	v_add_u32_e32 v19, 0x400, v16
	v_mov_b32_e32 v11, v9
	s_branch .LBB0_1196

; __device__ __forceinline__ bf16_t f2bf(float f) { return (bf16_t)(pk2(f, 0.f) & 0xffffu); }
; #define KP(f) ((decltype(Params::f))karg_ptr<(int)offsetof(Params, f)>())
;     const int nwg_ = wgn > 0 ? wgn : (int)gridDim.x - wg0;
;     if ((int)blockIdx.x < wg0 || (int)blockIdx.x >= wg0 + nwg_) return;
;     const int gtid = ((int)blockIdx.x - wg0) * 512 + threadIdx.x, nth = nwg_ * 512;
;     { const float* wd = KP(w_decay2) + (size_t)l * 64 * 512; const float* wa = KP(w_a2) + (size_t)l * 64 * 512; const float* wg = KP(w_g2) + (size_t)l * 128 * 512;
;       bf16_t* LoraT = KP(LoraT);
;       for (int i = gtid; i < 1536 * 256; i += nth) { const int n = i >> 8, k = i & 255; float v = 0.f;
;         if (n < 512) { if (k < 64) v = wd[k * 512 + n]; }
;         else if (n < 1024) { if (k >= 64 && k < 128) v = wa[(k - 64) * 512 + (n - 512)]; }
;         else { if (k >= 128) v = wg[(k - 128) * 512 + (n - 1024)]; }
;         LoraT[i] = f2bf(v); } }
.LBB0_1198:
	s_load_dwordx2 s[18:19], s[0:1], 0x48
	s_load_dwordx2 s[10:11], s[0:1], 0x58
	s_lshl_b32 s6, s2, 9
	s_load_dwordx2 s[12:13], s[0:1], 0x60
	s_waitcnt lgkmcnt(0)
	s_waitcnt vmcnt(1)
	v_add_u32_e32 v5, s6, v166
	s_load_dwordx2 s[24:25], s[0:1], 0xe8
	s_waitcnt lgkmcnt(0)
	v_add_u32_e32 v4, 0xffff8000, v5
	s_mov_b32 s6, 0x60000
	v_cmp_gt_i32_e32 vcc, s6, v4
	s_and_saveexec_b64 s[14:15], vcc
	s_cbranch_execz .LBB0_1215
	v_mov_b32_e32 v0, 9
	v_lshlrev_b32_sdwa v6, v0, v166 dst_sel:DWORD dst_unused:UNUSED_PAD src0_sel:DWORD src1_sel:BYTE_0
	v_mov_b32_e32 v0, 64
	v_cmp_lt_u32_sdwa s[22:23], v166, v0 src0_sel:BYTE_0 src1_sel:DWORD
	v_add_u32_e32 v0, 0xffff8000, v5
	s_add_u32 s18, s18, 0x20000
	s_movk_i32 s6, 0x7f
	v_ashrrev_i32_e32 v1, 31, v0
	s_mov_b64 s[16:17], 0x20000
	s_addc_u32 s19, s19, 0
	v_cmp_gt_u32_sdwa s[20:21], v166, s6 src0_sel:BYTE_0 src1_sel:DWORD
	v_lshl_add_u64 v[0:1], v[0:1], 1, s[24:25]
	s_mov_b64 s[24:25], 0
	s_movk_i32 s6, 0x1ff
	s_movk_i32 s7, 0x3ff
	v_mov_b32_e32 v3, 0
	s_mov_b32 s8, 0x4ffff
	v_mov_b32_e32 v7, v4
	s_branch .LBB0_1202

; __device__ __forceinline__ bf16_t f2bf(float f) { return (bf16_t)(pk2(f, 0.f) & 0xffffu); }
; #define KP(f) ((decltype(Params::f))karg_ptr<(int)offsetof(Params, f)>())
;     ...
;     { const float* wp = KP(w_pool) + (size_t)l * 4 * 128 * 128; bf16_t* PoolT = KP(PoolT);
;       for (int i = gtid; i < 512 * 512; i += nth) { const int n = i >> 9, k = i & 511; const int g = n >> 7, d = n & 127; float v = 0.f;
;         if ((k >> 7) == g) v = wp[(g * 128 + (k & 127)) * 128 + d];
;         PoolT[i] = f2bf(v); } }
.LBB0_1215:
	s_or_b64 exec, exec, s[14:15]
	s_load_dwordx2 s[12:13], s[0:1], 0x98
	s_load_dwordx2 s[14:15], s[0:1], 0xf0
	s_waitcnt lgkmcnt(0)
	s_mov_b32 s6, 0x40000
	v_cmp_gt_i32_e32 vcc, s6, v4
	s_and_saveexec_b64 s[10:11], vcc
	s_cbranch_execz .LBB0_1220
	v_add_u32_e32 v0, 0xffff8000, v5
	s_add_u32 s12, s12, 0x40000
	v_ashrrev_i32_e32 v1, 31, v0
	s_addc_u32 s13, s13, 0
	v_lshlrev_b32_e32 v5, 7, v0
	v_lshl_add_u64 v[0:1], v[0:1], 1, s[14:15]
	s_mov_b64 s[14:15], 0
	v_mov_b32_e32 v3, 0
	s_mov_b64 s[16:17], 0x20000
	s_mov_b32 s6, 0x2ffff
	v_mov_b32_e32 v6, 14
	s_branch .LBB0_1218

; #define KP(f) ((decltype(Params::f))karg_ptr<(int)offsetof(Params, f)>())
;     __device__ bool next(int i, Unit& u) const {
;         const long L = (long)i * G + c; if (L >= nwg) return false;
;         int wgid = (int)L; { const int q = nwg / NXCD, r = nwg % NXCD, xcd = wgid % NXCD, off = wgid / NXCD; wgid = (xcd < r ? xcd * (q + 1) : r * (q + 1) + (xcd - r) * q) + off; }
;         const int nig = WGM * nN, gid = wgid / nig, fm = gid * WGM, gsz = (nM - fm) < WGM ? (nM - fm) : WGM;
;         u.pm = fm + ((wgid % nig) % gsz); u.pn = (wgid % nig) / gsz; return true;
; __device__ __forceinline__ void run_phase(int type, int l, unsigned char* shm) {
;     ...
;         pg8::Gemm g{KP(xb), KP(WinT), T_ALL, DIN, DM, DM, DM}; S.init(T_ALL, DIN, G, c);
;         EpiNormBf16<0> E{KP(z), DIN, KP(ssq)}; pg8::gemm_phase(lds, g, S, E);
.LBB0_1273:
	s_or_b64 exec, exec, s[10:11]
	s_mov_b32 s40, s46
	s_mov_b32 s41, s2
	s_waitcnt lgkmcnt(0)
	s_barrier
	s_load_dwordx2 s[12:13], s[0:1], 0x120
	s_load_dwordx2 s[14:15], s[0:1], 0xe0
	s_load_dwordx2 s[16:17], s[0:1], 0x130
	s_load_dwordx2 s[18:19], s[0:1], 0x128
	s_waitcnt lgkmcnt(0)
	v_mov_b32_e32 v8, v166
	s_cmpk_gt_i32 s41, 0x483
	v_readfirstlane_b32 s53, v8
	s_cbranch_scc1 .LBB0_1293
	s_ashr_i32 s54, s41, 31
	s_lshr_b32 s6, s54, 29
	s_add_i32 s7, s41, s6
	s_and_b32 s6, s7, -8
	s_sub_i32 s6, s41, s6
	s_cmp_gt_i32 s6, 3
	s_cbranch_scc0 .LBB0_1276
	s_mul_i32 s8, s6, 0x90
	s_or_b32 s8, s8, 4
	s_ashr_i32 s9, s7, 3
	s_cbranch_execz .LBB0_1277
	s_branch .LBB0_1278

; #define KP(f) ((decltype(Params::f))karg_ptr<(int)offsetof(Params, f)>())
;     int tid_ = threadIdx.x; asm volatile("" : "+v"(tid_));
;     const int tid = tid_, ntn = N / 64, ntiles = (K / 64) * ntn, nwg = wgn > 0 ? wgn : (int)gridDim.x - wg0;
;     if ((int)blockIdx.x < wg0 || (int)blockIdx.x >= wg0 + nwg) return;
;     const int r = tid >> 4, c4 = (tid & 15) * 4, n = tid >> 3, k8 = (tid & 7) * 8;
;     int t = (int)blockIdx.x - wg0;
;     f32x4 v0, v1; float g0 = 1.f, g1 = 1.f;
;     if (t < ntiles) { const int k0 = (t / ntn) * 64, n0 = (t % ntn) * 64;
;         v0 = *(const f32x4*)(src + (size_t)(k0 + r) * N + n0 + c4); v1 = *(const f32x4*)(src + (size_t)(k0 + r + 32) * N + n0 + c4);
;         if (gain) { g0 = gain[k0 + r]; g1 = gain[k0 + r + 32]; } }
; __device__ __forceinline__ void run_phase(int type, int l, unsigned char* shm) {
;     ...
;         { const int w0 = (68 * 17) % G;
;           if (l == 1) transpose_convert(KP(w_ff2) + (size_t)DFF * DM, DFF, DM, nullptr, KP(Wff2T), (float*)shm, w0);
.LBB0_1293:
	s_abs_i32 s6, s40
	v_cvt_f32_u32_e32 v0, s6
	s_sub_i32 s7, 0, s6
	s_load_dwordx2 s[12:13], s[0:1], 0xc8
	v_readlane_b32 s14, v230, 0
	v_rcp_iflag_f32_e32 v0, v0
	s_load_dwordx2 s[10:11], s[0:1], 0x118
	s_waitcnt lgkmcnt(0)
	v_readlane_b32 s15, v230, 1
	v_mov_b32_e32 v10, v166
	v_mul_f32_e32 v0, 0x4f7ffffe, v0
	v_cvt_u32_f32_e32 v0, v0
	s_nop 0
	v_readfirstlane_b32 s8, v0
	s_mul_i32 s7, s7, s8
	s_mul_hi_u32 s7, s8, s7
	s_add_i32 s8, s8, s7
	s_mul_hi_u32 s7, s8, 0x484
	s_mul_i32 s7, s7, s6
	s_sub_i32 s7, 0x484, s7
	s_sub_i32 s8, s7, s6
	s_cmp_ge_u32 s7, s6
	s_cselect_b32 s7, s8, s7
	s_sub_i32 s8, s7, s6
	s_cmp_ge_u32 s7, s6
	s_cselect_b32 s7, s8, s7
	s_cmp_ge_i32 s2, s7
	s_cselect_b64 s[8:9], -1, 0
	s_and_b64 s[8:9], s[8:9], s[14:15]
	s_andn2_b64 vcc, exec, s[8:9]
	s_cbranch_vccnz .LBB0_1301
	s_sub_i32 s6, s2, s7
	s_cmpk_gt_i32 s6, 0x3ff
	s_cbranch_scc1 .LBB0_1301
	s_add_u32 s12, s12, 0x1000000
	s_sext_i32_i16 s8, s6
	s_addc_u32 s13, s13, 0
	s_bfe_u32 s8, s8, 0x4001b
	s_add_i32 s8, s6, s8
	s_sext_i32_i16 s9, s8
	s_lshl_b32 s9, s9, 2
	v_ashrrev_i32_e32 v12, 4, v10
	v_lshlrev_b32_e32 v0, 2, v10
	s_andn2_b32 s9, s9, 63
	s_and_b32 s8, s8, 0xfff0
	v_and_b32_e32 v20, 60, v0
	s_sub_i32 s8, s6, s8
	v_add_u32_e32 v0, s9, v12
	s_sext_i32_i16 s8, s8
	v_ashrrev_i32_e32 v1, 31, v0
	s_lshl_b32 s8, s8, 6
	v_lshlrev_b64 v[0:1], 12, v[0:1]
	v_lshl_add_u64 v[0:1], s[12:13], 0, v[0:1]
	s_ashr_i32 s9, s8, 31
	v_lshl_add_u64 v[0:1], s[8:9], 2, v[0:1]
	v_mov_b32_e32 v9, 0
	v_lshlrev_b32_e32 v8, 2, v20
	v_lshl_add_u64 v[14:15], v[0:1], 0, v[8:9]
	s_mov_b32 s8, 0x20000
	v_add_co_u32_e32 v16, vcc, s8, v14
	v_ashrrev_i32_e32 v13, 3, v10
	s_nop 0
	v_addc_co_u32_e32 v17, vcc, 0, v15, vcc
	global_load_dwordx4 v[0:3], v[14:15], off
	global_load_dwordx4 v[4:7], v[16:17], off
	v_lshlrev_b32_e32 v10, 3, v10
	s_movk_i32 s8, 0x104
	v_and_b32_e32 v10, 56, v10
	v_mul_lo_u32 v15, v12, s8
	v_add3_u32 v14, 0, v8, v15
	v_add3_u32 v8, 0, v15, v8
	v_mul_u32_u24_e32 v15, 0x41, v10
	v_lshlrev_b32_e32 v11, 2, v13
	v_lshlrev_b32_e32 v16, 2, v15
	v_add3_u32 v15, 0, v11, v16
	v_add3_u32 v16, 0, v16, v11
	s_sub_i32 s7, s46, s7
	s_lshl_b32 s18, s6, 6
	s_lshl_b32 s8, s7, 6
	v_add_u32_e32 v17, 0x2080, v8
	v_add_u32_e32 v18, 0x2088, v8
	v_lshlrev_b32_e32 v8, 2, v20
	v_lshlrev_b32_e32 v10, 1, v10
	v_add_u32_e32 v19, 0x400, v16
	v_mov_b32_e32 v11, v9
	s_branch .LBB0_1297

; #define KP(f) ((decltype(Params::f))karg_ptr<(int)offsetof(Params, f)>())
; __device__ __forceinline__ void unpack8(const u32x4 w, f32x4& v0, f32x4& v1) { v0 = (f32x4){bflo(w.x), bfhi(w.x), bflo(w.y), bfhi(w.y)}; v1 = (f32x4){bflo(w.z), bfhi(w.z), bflo(w.w), bfhi(w.w)}; }
; __device__ __forceinline__ Tok tok_decode(int tok) { Tok r; if (tok < T_P) { r.is_s = 0; r.seq = tok >> 11; r.t = tok & 2047; } else { r.is_s = 1; r.seq = (tok - T_P) >> 3; r.t = (tok - T_P) & 7; } return r; }
; __device__ void phase_e1(int l) {
;     ...
;     const bf16_t* z = KP(z); bf16_t* pbuf = KP(xb);
;     bf16_t* Lb = KP(L);
;     const float* mu = KP(mu_shift) + (size_t)l * DSH;
;     const float* st_shift = KP(state_shift) + (size_t)l * NSB * DSH;
;     const float* st_pool = KP(state_pool) + (size_t)l * NSB * 15 * 512;
;     float* out = KP(out);
;     for (int it = gtid; it < T_ALL * 32; it += nth) {
;         const int tok = it >> 5, v = it & 31; const Tok tk = tok_decode(tok);
;         const int c = O_LORA + v * 8; const bf16_t* zr = z + (size_t)tok * DIN + c;
;         f32x4 x0, x1, p0, p1; unpack8(*(const u32x4*)zr, x0, x1);
;         if (tk.t > 0) unpack8(*(const u32x4*)(zr - DIN), p0, p1);
;         else if (tk.is_s) { const float* sp = st_shift + (size_t)tk.seq * DSH + c; p0 = *(const f32x4*)sp; p1 = *(const f32x4*)(sp + 4); }
;         else { p0 = (f32x4){0.f, 0.f, 0.f, 0.f}; p1 = p0; }
;         const f32x4 m0 = *(const f32x4*)(mu + c), m1 = *(const f32x4*)(mu + c + 4);
;         x0 = x0 + (p0 - x0) * m0; x1 = x1 + (p1 - x1) * m1;
.LBB0_1355:
	s_load_dwordx2 s[56:57], s[0:1], 0x130
	s_load_dwordx2 s[58:59], s[0:1], 0x120
	s_load_dwordx2 s[14:15], s[0:1], 0x138
	s_load_dwordx2 s[10:11], s[0:1], 56
	s_load_dwordx2 s[12:13], s[0:1], 16
	s_load_dwordx2 s[16:17], s[0:1], 24
	s_load_dwordx2 s[54:55], s[0:1], 0xd8
	s_waitcnt lgkmcnt(0)
	v_lshl_add_u32 v12, s6, 9, v166
	s_mov_b32 s6, 0x88000
	v_cmp_gt_i32_e32 vcc, s6, v12
	s_and_saveexec_b64 s[18:19], vcc
	s_cbranch_execz .LBB0_1370
	s_waitcnt vmcnt(2)
	v_mov_b32_e32 v1, 0
	v_mov_b32_e32 v2, 0x1800
	v_lshl_or_b32 v2, v169, 5, v2
	v_mov_b32_e32 v3, v1
	s_waitcnt vmcnt(1)
	v_lshl_add_u64 v[4:5], s[12:13], 0, v[2:3]
	s_mov_b64 s[6:7], 0xe0000
	v_lshlrev_b32_e32 v0, 4, v169
	v_lshl_add_u64 v[16:17], v[4:5], 0, s[6:7]
	v_lshl_add_u64 v[2:3], s[10:11], 0, v[2:3]
	s_mov_b64 s[6:7], 0x1c00
	v_lshl_add_u64 v[14:15], s[56:57], 0, v[0:1]
	v_lshl_add_u64 v[18:19], v[2:3], 0, s[6:7]
	v_cmp_lt_u32_e64 s[10:11], 7, v169
	v_cmp_lt_u32_e64 s[12:13], 15, v169
	v_lshl_add_u64 v[20:21], s[14:15], 0, v[0:1]
	s_mov_b64 s[20:21], 0
	s_movk_i32 s6, 0x3fff
	s_movk_i32 s7, 0x4000
	v_mov_b32_e32 v13, 0x7ff
	s_movk_i32 s8, 0x2200
	s_mov_b64 s[22:23], 0xc00
	s_movk_i32 s9, 0x1c00
	s_mov_b32 s28, 0x87fff
	v_mov_b32_e32 v24, v12
	s_branch .LBB0_1358

; #define KP(f) ((decltype(Params::f))karg_ptr<(int)offsetof(Params, f)>())
; #define PG8_WAIT_V(n) asm volatile("s_waitcnt vmcnt(" #n ")" ::: "memory")
; #define PG8_BAR __builtin_amdgcn_s_barrier()
;     ...
;     const int tid = tid_, wid = __builtin_amdgcn_readfirstlane(tid >> 6), lane = tid & 63, wr = wid >> 2, wc = wid & 3, fr = lane & 15, fq = lane >> 4;
;     const int K = g.K, nt = K / BK, lda = g.lda, ldb = g.ldb;
;     unsigned voffA[2], voffB[2];
; #pragma unroll
;     for (int i = 0; i < 2; ++i) { int R, C; stage_rc(tid * 16 + i * 8192, R, C); const int Rb = Epi::PERM ? ((R & ~31) + perm32(R & 31)) : R;
;         voffA[i] = (unsigned)(R * lda + C) * 2u; voffB[i] = (unsigned)(Rb * ldb + C) * 2u; }
;     const size_t kstep = (size_t)(BK * 2);
;     const size_t hA = (size_t)HALF * lda * 2, hB = (size_t)HALF * ldb * 2;
;     const size_t tA = 2 * hA, tB = 2 * hB;
;     const unsigned ldsw = (unsigned)wid * 1024u;
;     const int aoff = lds_byte(wr * 64 + fr, fq * 8), boff = lds_byte(wc * 32 + fr, fq * 8);
;     ...
;     Unit cur, nxt; int ui = 0;
;     if (!S.next(0, cur)) return;
;     ...
;     f32x4 acc[2][2][4][2];
; #pragma unroll
;     for (int a = 0; a < 2; ++a)
; #pragma unroll
;         for (int b = 0; b < 2; ++b)
; #pragma unroll
;             for (int m = 0; m < 4; ++m)
; #pragma unroll
;                 for (int n = 0; n < 2; ++n) acc[a][b][m][n] = (f32x4){0.f, 0.f, 0.f, 0.f};
;     bf16x8 At[4][2], B0[2][2], B1[2][2];
;     const char* cA = (const char*)g.A + (size_t)cur.pm * tA; const char* cB = (const char*)g.Bt + (size_t)cur.pn * tB;
;     PG8_A_READY(cur);
;     PG8_STAGE(PG8_SB(0, 0), cB, voffB); PG8_STAGE(PG8_SA(0, 0), cA, voffA); PG8_STAGE(PG8_SB(0, 1), cB + hB, voffB); PG8_STAGE(PG8_SA(0, 1), cA + hA, voffA);
;     if (wr == 1) PG8_BAR;
;     PG8_WAIT_V(4); PG8_BAR;
;     PG8_STAGE(PG8_SB(1, 0), cB + kstep, voffB); PG8_STAGE(PG8_SA(1, 0), cA + kstep, voffA); PG8_STAGE(PG8_SB(1, 1), cB + hB + kstep, voffB);
;     PG8_WAIT_V(6); PG8_BAR;
; __device__ __forceinline__ void run_phase(int type, int l, unsigned char* shm) {
;     ...
;         { pg8::Gemm g{KP(L), KP(LoraT), T_ALL, 1536, 256, 256, 256}; S.init(T_ALL, 1536, G, c);
;           EpiLora E{KP(xb) + (size_t)T_ALL * 512, KP(sc_a), KP(sc_g)}; pg8::gemm_phase(lds, g, S, E); }
.LBB0_1466:
	s_or_b64 exec, exec, s[10:11]
	s_mov_b32 s53, s46
	s_mov_b32 s68, s2
	s_waitcnt lgkmcnt(0)
	s_barrier
	s_load_dwordx2 s[12:13], s[0:1], 0x138
	s_load_dwordx2 s[14:15], s[0:1], 0xe8
	s_load_dwordx2 s[10:11], s[0:1], 0x120
	s_load_dwordx2 s[16:17], s[0:1], 0x140
	s_load_dwordx2 s[18:19], s[0:1], 0x148
	s_waitcnt lgkmcnt(0)
	v_mov_b32_e32 v8, v166
	s_cmpk_gt_i32 s68, 0x197
	v_readfirstlane_b32 s69, v8
	s_cbranch_scc1 .LBB0_1478
	s_waitcnt vmcnt(2)
	v_lshlrev_b32_e32 v0, 4, v8
	v_add_u32_e32 v1, 0x2000, v0
	v_ashrrev_i32_e32 v2, 31, v1
	v_lshrrev_b32_e32 v2, 22, v2
	v_add_u32_e32 v2, v1, v2
	v_ashrrev_i32_e32 v2, 10, v2
	v_mul_i32_i24_e32 v3, 0x400, v2
	v_sub_u32_e32 v1, v1, v3
	v_lshrrev_b32_e32 v3, 4, v1
	v_bitop3_b32 v1, v3, v1, 32 bitop3:0x6c
	v_ashrrev_i32_e32 v3, 31, v1
	v_lshrrev_b32_e32 v3, 26, v3
	v_add_u32_e32 v3, v1, v3
	s_waitcnt vmcnt(1)
	v_lshlrev_b32_e32 v5, 3, v2
	v_ashrrev_i32_e32 v4, 6, v3
	v_and_b32_e32 v5, -16, v5
	v_and_b32_e32 v3, 0xc0, v3
	v_add_u32_e32 v5, v4, v5
	v_sub_u32_e32 v1, v1, v3
	v_mov_b32_e32 v3, 1
	v_and_b32_e32 v4, 3, v4
	s_mov_b32 s8, 0x7fffe0
	v_lshrrev_b32_e32 v6, 2, v5
	v_lshlrev_b32_e32 v7, 1, v5
	v_lshlrev_b32_e32 v2, 5, v2
	v_ashrrev_i16_sdwa v1, v3, sext(v1) dst_sel:DWORD dst_unused:UNUSED_PAD src0_sel:DWORD src1_sel:BYTE_0
	v_and_or_b32 v4, v5, s8, v4
	v_and_b32_e32 v6, 4, v6
	v_and_b32_e32 v7, 24, v7
	v_and_b32_e32 v2, 32, v2
	v_bfe_i32 v1, v1, 0, 16
	v_or3_b32 v4, v4, v6, v7
	v_add_lshl_u32 v1, v2, v1, 1
	v_lshl_add_u32 v128, v4, 9, v1
	v_lshl_add_u32 v130, v5, 9, v1
	v_bfe_i32 v1, v8, 27, 1
	v_lshrrev_b32_e32 v1, 22, v1
	v_add_u32_e32 v1, v0, v1
	v_and_b32_e32 v1, 0xfffffc00, v1
	v_sub_u32_e32 v0, v0, v1
	v_lshrrev_b32_e32 v1, 4, v0
	v_ashrrev_i32_e32 v4, 31, v8
	v_bitop3_b32 v0, v1, v0, 32 bitop3:0x6c
	v_lshrrev_b32_e32 v4, 26, v4
	v_ashrrev_i32_e32 v1, 31, v0
	v_add_u32_e32 v4, v8, v4
	v_lshrrev_b32_e32 v1, 26, v1
	v_ashrrev_i32_e32 v4, 6, v4
	v_add_u32_e32 v1, v0, v1
	v_lshlrev_b32_e32 v5, 3, v4
	v_ashrrev_i32_e32 v2, 6, v1
	v_and_b32_e32 v5, -16, v5
	v_add_u32_e32 v5, v2, v5
	v_and_b32_e32 v2, 3, v2
	s_ashr_i32 s71, s68, 31
	v_and_or_b32 v2, v5, s8, v2
	s_lshr_b32 s8, s71, 29
	s_add_i32 s8, s68, s8
	s_ashr_i32 s6, s69, 6
	s_ashr_i32 s9, s8, 3
	s_and_b32 s8, s8, -8
	s_ashr_i32 s7, s69, 8
	s_lshl_b32 s70, s6, 10
	s_sub_i32 s8, s68, s8
	s_cmp_lt_i32 s8, 0
	s_cselect_b32 s20, 52, 51
	s_mul_i32 s8, s20, s8
	s_add_i32 s8, s8, s9
	s_mul_hi_i32 s9, s8, 0x2aaaaaab
	v_and_b32_e32 v1, 0xc0, v1
	s_lshr_b32 s20, s9, 31
	s_ashr_i32 s9, s9, 3
	v_sub_u32_e32 v0, v0, v1
	s_add_i32 s9, s9, s20
	v_lshrrev_b32_e32 v6, 2, v5
	v_lshlrev_b32_e32 v7, 1, v5
	v_lshlrev_b32_e32 v4, 5, v4
	v_ashrrev_i16_sdwa v0, v3, sext(v0) dst_sel:DWORD dst_unused:UNUSED_PAD src0_sel:DWORD src1_sel:BYTE_0
	s_lshl_b32 s20, s9, 3
	v_and_b32_e32 v6, 4, v6
	v_and_b32_e32 v7, 24, v7
	v_and_b32_e32 v4, 32, v4
	v_bfe_i32 v0, v0, 0, 16
	s_sub_i32 s21, 0x44, s20
	v_or3_b32 v2, v2, v6, v7
	v_add_lshl_u32 v0, v4, v0, 1
	s_min_u32 s21, s21, 8
	s_mul_i32 s9, s9, 48
	v_lshl_add_u32 v132, v2, 9, v0
	s_sub_i32 s23, s8, s9
	v_cvt_f32_ubyte0_e32 v2, s21
	v_cvt_f32_i32_e32 v1, s23
	v_rcp_iflag_f32_e32 v3, v2
	v_lshl_add_u32 v134, v5, 9, v0
	s_ashr_i32 s8, s23, 30
	s_or_b32 s22, s8, 1
	v_mul_f32_e32 v0, v1, v3
	v_trunc_f32_e32 v0, v0
	v_fma_f32 v1, -v0, v2, v1
	v_cvt_i32_f32_e32 v0, v0
	v_cmp_ge_f32_e64 s[8:9], |v1|, v2
	s_and_b64 s[8:9], s[8:9], exec
	s_cselect_b32 s8, s22, 0
	v_readfirstlane_b32 s9, v0
	s_add_i32 s22, s9, s8
	s_mul_i32 s8, s22, s21
	s_sub_i32 s8, s23, s8
	s_sext_i32_i8 s8, s8
	s_add_i32 s38, s20, s8
	s_ashr_i32 s39, s38, 31
	s_bfe_i64 s[20:21], s[22:23], 0x80000
	s_lshl_b64 s[8:9], s[38:39], 17
	s_lshl_b64 s[20:21], s[20:21], 17
	s_add_u32 s40, s14, s20
	s_addc_u32 s41, s15, s21
	s_add_i32 s39, s70, 0
	s_add_i32 m0, s39, 0x10000
	v_mov_b32_e32 v137, 0
	global_load_lds_dwordx4 v132, s[40:41]
	s_add_i32 m0, s39, 0x12000
	s_add_u32 s42, s12, s8
	global_load_lds_dwordx4 v128, s[40:41]
	s_addc_u32 s43, s13, s9
	s_mov_b32 m0, s39
	s_add_i32 s72, s39, 0x2000
	global_load_lds_dwordx4 v134, s[42:43]
	s_mov_b32 m0, s72
	s_add_u32 s8, s40, 0x10000
	global_load_lds_dwordx4 v130, s[42:43]
	s_addc_u32 s9, s41, 0
	s_add_i32 m0, s39, 0x14000
	v_mov_b32_e32 v133, v137
	global_load_lds_dwordx4 v132, s[8:9]
	s_add_i32 m0, s39, 0x16000
	v_mov_b32_e32 v129, v137
	global_load_lds_dwordx4 v128, s[8:9]
	s_add_u32 s8, s42, 0x10000
	s_addc_u32 s9, s43, 0
	s_add_i32 s73, s39, 0x4000
	s_mov_b32 m0, s73
	s_add_i32 s74, s39, 0x6000
	global_load_lds_dwordx4 v134, s[8:9]
	s_mov_b32 m0, s74
	v_mov_b32_e32 v135, v137
	global_load_lds_dwordx4 v130, s[8:9]
	v_mov_b32_e32 v131, v137
	s_mov_b32 s75, 0
	v_lshl_add_u64 v[6:7], s[40:41], 0, v[132:133]
	v_lshl_add_u64 v[4:5], s[40:41], 0, v[128:129]
	v_lshl_add_u64 v[2:3], s[42:43], 0, v[134:135]
	s_cmp_lg_u32 s7, 1
	v_lshl_add_u64 v[0:1], s[42:43], 0, v[130:131]
	s_cbranch_scc1 .LBB0_1469
	s_barrier

; #define KP(f) ((decltype(Params::f))karg_ptr<(int)offsetof(Params, f)>())
; #define PG8_WAIT_V(n) asm volatile("s_waitcnt vmcnt(" #n ")" ::: "memory")
; #define PG8_BAR __builtin_amdgcn_s_barrier()
;     ...
;     const int tid = tid_, wid = __builtin_amdgcn_readfirstlane(tid >> 6), lane = tid & 63, wr = wid >> 2, wc = wid & 3, fr = lane & 15, fq = lane >> 4;
;     const int K = g.K, nt = K / BK, lda = g.lda, ldb = g.ldb;
;     unsigned voffA[2], voffB[2];
; #pragma unroll
;     for (int i = 0; i < 2; ++i) { int R, C; stage_rc(tid * 16 + i * 8192, R, C); const int Rb = Epi::PERM ? ((R & ~31) + perm32(R & 31)) : R;
;         voffA[i] = (unsigned)(R * lda + C) * 2u; voffB[i] = (unsigned)(Rb * ldb + C) * 2u; }
;     const size_t kstep = (size_t)(BK * 2);
;     const size_t hA = (size_t)HALF * lda * 2, hB = (size_t)HALF * ldb * 2;
;     const size_t tA = 2 * hA, tB = 2 * hB;
;     const unsigned ldsw = (unsigned)wid * 1024u;
;     const int aoff = lds_byte(wr * 64 + fr, fq * 8), boff = lds_byte(wc * 32 + fr, fq * 8);
;     ...
;     Unit cur, nxt; int ui = 0;
;     if (!S.next(0, cur)) return;
;     ...
;     f32x4 acc[2][2][4][2];
; #pragma unroll
;     for (int a = 0; a < 2; ++a)
; #pragma unroll
;         for (int b = 0; b < 2; ++b)
; #pragma unroll
;             for (int m = 0; m < 4; ++m)
; #pragma unroll
;                 for (int n = 0; n < 2; ++n) acc[a][b][m][n] = (f32x4){0.f, 0.f, 0.f, 0.f};
;     bf16x8 At[4][2], B0[2][2], B1[2][2];
;     const char* cA = (const char*)g.A + (size_t)cur.pm * tA; const char* cB = (const char*)g.Bt + (size_t)cur.pn * tB;
;     PG8_A_READY(cur);
;     PG8_STAGE(PG8_SB(0, 0), cB, voffB); PG8_STAGE(PG8_SA(0, 0), cA, voffA); PG8_STAGE(PG8_SB(0, 1), cB + hB, voffB); PG8_STAGE(PG8_SA(0, 1), cA + hA, voffA);
;     if (wr == 1) PG8_BAR;
;     PG8_WAIT_V(4); PG8_BAR;
;     PG8_STAGE(PG8_SB(1, 0), cB + kstep, voffB); PG8_STAGE(PG8_SA(1, 0), cA + kstep, voffA); PG8_STAGE(PG8_SB(1, 1), cB + hB + kstep, voffB);
;     PG8_WAIT_V(6); PG8_BAR;
; __device__ __forceinline__ void run_phase(int type, int l, unsigned char* shm) {
;     ...
;         { pg8::Gemm g{KP(xb), KP(PoolT), T_ALL, 512, 512, 512, 512}; S.init(T_ALL, 512, G, (c + 136) % G);
;           EpiPool E{KP(z), KP(pool_scale) + (size_t)l * 512}; pg8::gemm_phase(lds, g, S, E); }
.LBB0_1478:
	s_abs_i32 s6, s53
	s_waitcnt vmcnt(0)
	v_cvt_f32_u32_e32 v0, s6
	s_sub_i32 s9, 0, s6
	s_add_i32 s7, s68, 0x88
	s_ashr_i32 s8, s7, 31
	v_rcp_iflag_f32_e32 v0, v0
	s_abs_i32 s7, s7
	s_load_dwordx2 s[12:13], s[0:1], 0x120
	s_load_dwordx2 s[14:15], s[0:1], 0xf0
	v_mul_f32_e32 v0, 0x4f7ffffe, v0
	v_cvt_u32_f32_e32 v0, v0
	s_load_dwordx2 s[16:17], s[0:1], 0x130
	s_load_dwordx2 s[18:19], s[0:1], 0xa0
	s_waitcnt lgkmcnt(0)
	v_mov_b32_e32 v8, v166
	v_readfirstlane_b32 s10, v0
	s_mul_i32 s9, s9, s10
	s_mul_hi_u32 s9, s10, s9
	s_add_i32 s10, s10, s9
	s_mul_hi_u32 s9, s7, s10
	s_mul_i32 s9, s9, s6
	s_sub_i32 s7, s7, s9
	s_sub_i32 s9, s7, s6
	s_cmp_ge_u32 s7, s6
	s_cselect_b32 s7, s9, s7
	s_sub_i32 s9, s7, s6
	s_cmp_ge_u32 s7, s6
	s_cselect_b32 s6, s9, s7
	s_xor_b32 s6, s6, s8
	s_sub_i32 s40, s6, s8
	s_cmpk_gt_i32 s40, 0x87
	v_readfirstlane_b32 s41, v8
	s_cbranch_scc1 .LBB0_1490
	v_lshlrev_b32_e32 v0, 4, v8
	v_add_u32_e32 v1, 0x2000, v0
	v_ashrrev_i32_e32 v2, 31, v1
	v_lshrrev_b32_e32 v2, 22, v2
	v_add_u32_e32 v2, v1, v2
	v_ashrrev_i32_e32 v9, 10, v2
	v_mul_i32_i24_e32 v2, 0x400, v9
	v_sub_u32_e32 v1, v1, v2
	v_lshrrev_b32_e32 v2, 4, v1
	v_bitop3_b32 v1, v2, v1, 32 bitop3:0x6c
	v_ashrrev_i32_e32 v2, 31, v1
	v_lshrrev_b32_e32 v2, 26, v2
	v_add_u32_e32 v2, v1, v2
	v_lshlrev_b32_e32 v3, 3, v9
	v_ashrrev_i32_e32 v10, 6, v2
	v_and_b32_e32 v3, -16, v3
	v_add_u32_e32 v3, v10, v3
	v_and_b32_e32 v4, 3, v10
	s_mov_b32 s8, 0x3fffe0
	v_lshrrev_b32_e32 v5, 2, v3
	v_lshlrev_b32_e32 v6, 1, v3
	v_and_b32_e32 v2, 0xc0, v2
	v_and_or_b32 v4, v3, s8, v4
	v_and_b32_e32 v5, 4, v5
	v_and_b32_e32 v6, 24, v6
	v_sub_u32_e32 v1, v1, v2
	v_mov_b32_e32 v2, 1
	v_or3_b32 v4, v4, v5, v6
	v_lshlrev_b32_e32 v5, 5, v9
	v_ashrrev_i16_sdwa v1, v2, sext(v1) dst_sel:DWORD dst_unused:UNUSED_PAD src0_sel:DWORD src1_sel:BYTE_0
	v_and_b32_e32 v5, 32, v5
	v_bfe_i32 v11, v1, 0, 16
	v_add_lshl_u32 v1, v5, v11, 1
	v_lshl_add_u32 v146, v4, 10, v1
	v_lshl_add_u32 v148, v3, 10, v1
	v_bfe_i32 v1, v8, 27, 1
	v_lshrrev_b32_e32 v1, 22, v1
	v_add_u32_e32 v1, v0, v1
	v_and_b32_e32 v1, 0xfffffc00, v1
	v_sub_u32_e32 v0, v0, v1
	v_lshrrev_b32_e32 v1, 4, v0
	v_ashrrev_i32_e32 v3, 31, v8
	v_bitop3_b32 v0, v1, v0, 32 bitop3:0x6c
	v_lshrrev_b32_e32 v3, 26, v3
	v_ashrrev_i32_e32 v1, 31, v0
	v_add_u32_e32 v3, v8, v3
	v_lshrrev_b32_e32 v1, 26, v1
	v_ashrrev_i32_e32 v13, 6, v3
	v_add_u32_e32 v1, v0, v1
	v_lshlrev_b32_e32 v3, 3, v13
	v_ashrrev_i32_e32 v12, 6, v1
	v_and_b32_e32 v3, -16, v3
	v_add_u32_e32 v3, v12, v3
	v_and_b32_e32 v4, 3, v12
	s_ashr_i32 s43, s40, 31
	v_and_or_b32 v4, v3, s8, v4
	s_lshr_b32 s8, s43, 29
	s_add_i32 s8, s40, s8
	s_ashr_i32 s6, s41, 6
	s_ashr_i32 s9, s8, 3
	s_and_b32 s8, s8, -8
	s_ashr_i32 s7, s41, 8
	s_lshl_b32 s42, s6, 10
	s_sub_i32 s8, s40, s8
	s_cmp_lt_i32 s8, 0
	s_cselect_b32 s10, 18, 17
	s_mul_i32 s8, s10, s8
	s_add_i32 s8, s8, s9
	s_ashr_i32 s9, s8, 31
	s_lshr_b32 s9, s9, 28
	s_add_i32 s9, s8, s9
	v_lshrrev_b32_e32 v5, 2, v3
	v_lshlrev_b32_e32 v6, 1, v3
	v_and_b32_e32 v1, 0xc0, v1
	s_ashr_i32 s10, s9, 4
	v_and_b32_e32 v5, 4, v5
	v_and_b32_e32 v6, 24, v6
	v_sub_u32_e32 v0, v0, v1
	s_lshl_b32 s11, s10, 3
	v_or3_b32 v4, v4, v5, v6
	v_lshlrev_b32_e32 v5, 5, v13
	v_ashrrev_i16_sdwa v0, v2, sext(v0) dst_sel:DWORD dst_unused:UNUSED_PAD src0_sel:DWORD src1_sel:BYTE_0
	s_sub_i32 s10, 0x44, s11
	v_and_b32_e32 v5, 32, v5
	v_bfe_i32 v14, v0, 0, 16
	s_min_u32 s20, s10, 8
	s_and_b32 s9, s9, -16
	v_add_lshl_u32 v0, v5, v14, 1
	s_sub_i32 s21, s8, s9
	v_cvt_f32_ubyte0_e32 v2, s20
	v_lshl_add_u32 v150, v4, 10, v0
	v_cvt_f32_i32_e32 v1, s21
	v_rcp_iflag_f32_e32 v4, v2
	v_lshl_add_u32 v152, v3, 10, v0
	s_ashr_i32 s8, s21, 30
	s_or_b32 s10, s8, 1
	v_mul_f32_e32 v0, v1, v4
	v_trunc_f32_e32 v0, v0
	v_fma_f32 v1, -v0, v2, v1
	v_cvt_i32_f32_e32 v0, v0
	v_cmp_ge_f32_e64 s[8:9], |v1|, v2
	s_and_b64 s[8:9], s[8:9], exec
	s_cselect_b32 s8, s10, 0
	v_readfirstlane_b32 s9, v0
	s_add_i32 s10, s9, s8
	s_mul_i32 s8, s10, s20
	s_sub_i32 s8, s21, s8
	s_sext_i32_i8 s8, s8
	s_add_i32 s30, s11, s8
	s_ashr_i32 s31, s30, 31
	s_bfe_i64 s[20:21], s[10:11], 0x80000
	s_lshl_b64 s[8:9], s[30:31], 18
	s_lshl_b64 s[20:21], s[20:21], 18
	s_add_u32 s34, s14, s20
	s_addc_u32 s35, s15, s21
	s_add_i32 s31, s42, 0
	s_add_i32 m0, s31, 0x10000
	v_mov_b32_e32 v151, 0
	global_load_lds_dwordx4 v150, s[34:35]
	s_add_i32 m0, s31, 0x12000
	s_add_u32 s36, s12, s8
	global_load_lds_dwordx4 v146, s[34:35]
	s_addc_u32 s37, s13, s9
	s_mov_b32 m0, s31
	s_add_i32 s54, s31, 0x2000
	global_load_lds_dwordx4 v152, s[36:37]
	s_mov_b32 m0, s54
	s_add_u32 s8, s34, 0x20000
	global_load_lds_dwordx4 v148, s[36:37]
	s_addc_u32 s9, s35, 0
	s_add_i32 m0, s31, 0x14000
	v_mov_b32_e32 v147, v151
	global_load_lds_dwordx4 v150, s[8:9]
	s_add_i32 m0, s31, 0x16000
	v_mov_b32_e32 v153, v151
	global_load_lds_dwordx4 v146, s[8:9]
	s_add_u32 s8, s36, 0x20000
	s_addc_u32 s9, s37, 0
	s_add_i32 s55, s31, 0x4000
	s_mov_b32 m0, s55
	s_add_i32 s56, s31, 0x6000
	global_load_lds_dwordx4 v152, s[8:9]
	s_mov_b32 m0, s56
	v_mov_b32_e32 v149, v151
	global_load_lds_dwordx4 v148, s[8:9]
	v_lshl_add_u64 v[6:7], s[34:35], 0, v[150:151]
	v_lshl_add_u64 v[4:5], s[34:35], 0, v[146:147]
	v_lshl_add_u64 v[2:3], s[36:37], 0, v[152:153]
	s_cmp_lg_u32 s7, 1
	v_lshl_add_u64 v[0:1], s[36:37], 0, v[148:149]
	s_cbranch_scc1 .LBB0_1481
	s_barrier

; #define KP(f) ((decltype(Params::f))karg_ptr<(int)offsetof(Params, f)>())
; __device__ void phase_scan(int l, unsigned char* lds) {
;     int tid_ = threadIdx.x; asm volatile("" : "+v"(tid_));
;     const int tid = tid_, wid = tid >> 6, lane = tid & 63, G = gridDim.x;
;     const bool loader = wid >= 4;
;     if (!loader) __builtin_amdgcn_s_setprio(3);
;     ScanPtrs Q;
;     Q.z = KP(z); Q.sw = KP(xb) + (size_t)T_ALL * 512; Q.sa = KP(sc_a); Q.st_shift = KP(state_shift) + (size_t)l * NSB * DSH; Q.mu = KP(mu_shift) + (size_t)l * DSH;
;     Q.k_k = KP(k_k) + (size_t)l * 512; Q.k_a = KP(k_a) + (size_t)l * 512; Q.r_k = KP(r_k) + (size_t)l * 512; Q.decay0 = KP(decay0) + (size_t)l * 512; Q.a0 = KP(a0) + (size_t)l * 512; Q.rk = KP(rk);
;     bf16_t* ybuf = KP(xb);
;     const float* st_wkv = KP(state_wkv); float* out = KP(out);
;     int J = (G % 8 == 0) ? (int)(blockIdx.x % 8) * (G / 8) + (int)(blockIdx.x / 8) : (int)blockIdx.x, ci = 0, it = 0;
;     int Ji = J, cis = 0;
;     int Jg = J, cg_ = 0;
;     LStage L, L2;
;     f32x2 s01 = (f32x2){0.f, 0.f}, s23 = s01;
;     f32x4 s_pref = (f32x4){0.f, 0.f, 0.f, 0.f};
;     if (!loader && J >= 256 && J < NJOBS) { const Job j0 = job_decode(J, 0); s_pref = *(const f32x4*)(st_wkv + (((((size_t)l * NSB + j0.seq) * 8 + j0.h) * 64 + j0.rs * 16 + (wid * 4 + (lane >> 4))) * 64 + (lane & 15) * 4)); }
.LBB0_1542:
	s_or_b64 exec, exec, s[10:11]
	s_mov_b32 s6, s2
	s_mov_b32 s7, s46
	v_mov_b32_e32 v53, v166
	s_waitcnt lgkmcnt(0)
	s_barrier
	s_nop 0
	v_ashrrev_i32_e32 v52, 6, v53
	s_mov_b32 s98, -1
	v_mov_b32_e32 v252, 0xbfb8aa3b
	v_mov_b32_e32 v254, 0xbf1b4598
	v_mov_b32_e32 v226, 0x3fb8aa3b
	v_cmp_lt_i32_e64 s[10:11], 3, v52
	v_cmp_gt_i32_e64 s[12:13], 4, v52
	s_and_saveexec_b64 s[14:15], s[12:13]
	s_setprio 3
	s_or_b64 exec, exec, s[14:15]
	s_load_dwordx2 s[22:23], s[0:1], 0x130
	s_load_dwordx2 s[16:17], s[0:1], 0x120
	s_load_dwordx2 s[24:25], s[0:1], 0x140
	s_load_dwordx2 s[18:19], s[0:1], 16
	s_load_dwordx2 s[14:15], s[0:1], 56
	s_load_dwordx2 s[26:27], s[0:1], 0x68
	s_load_dwordx2 s[28:29], s[0:1], 0x70
	s_load_dwordx2 s[30:31], s[0:1], 0x78
	s_load_dwordx2 s[34:35], s[0:1], 64
	s_load_dwordx2 s[36:37], s[0:1], 0x50
	s_load_dwordx2 s[38:39], s[0:1], 0x150
	s_load_dwordx2 s[40:41], s[0:1], 0x120
	s_load_dwordx2 s[20:21], s[0:1], 32
	s_load_dwordx2 s[42:43], s[0:1], 0xd8
	s_waitcnt lgkmcnt(0)
	v_readlane_b32 s6, v230, 6
	v_readlane_b32 s7, v230, 7
	s_and_b64 vcc, exec, s[6:7]
	s_mov_b32 s53, s2
	s_cbranch_vccnz .LBB0_1546
	s_and_b32 s6, s2, 7
	s_ashr_i32 s7, s46, 3
	s_mul_i32 s6, s7, s6
	s_lshr_b32 s7, s2, 3
	s_add_i32 s53, s6, s7

; #define KP(f) ((decltype(Params::f))karg_ptr<(int)offsetof(Params, f)>())
; __device__ __forceinline__ Tok tok_decode(int tok) { Tok r; if (tok < T_P) { r.is_s = 0; r.seq = tok >> 11; r.t = tok & 2047; } else { r.is_s = 1; r.seq = (tok - T_P) >> 3; r.t = (tok - T_P) & 7; } return r; }
; __device__ void phase_e2(int l, int wg0) {
;     if ((int)blockIdx.x < wg0) return;
;     const int gtid = ((int)blockIdx.x - wg0) * 512 + threadIdx.x, nth = ((int)gridDim.x - wg0) * 512;
;     const bf16_t* ybuf = KP(xb); bf16_t* ya = KP(xb) + (size_t)T_ALL * 512;
;     const bf16_t* z = KP(z); const bf16_t* sc_g = KP(sc_g); const float* rkb = KP(rk);
;     const float* mu = KP(mu_shift) + (size_t)l * DSH + 1024;
;     const float* st_shift = KP(state_shift) + (size_t)l * NSB * DSH;
;     const float* lng = KP(ln_x_g) + (size_t)l * 512; const float* lnb = KP(ln_x_b) + (size_t)l * 512;
;     for (int it0 = gtid; it0 < T_ALL * 128; it0 += 2 * nth) {
;         f32x4 y[2], v[2], vp[2], g[2], m4[2], lg[2], lb[2]; float rk[2]; int tokv[2], cv[2]; bool ok[2];
; #pragma unroll
;         for (int q = 0; q < 2; ++q) {
;             const int it = it0 + q * nth; ok[q] = it < T_ALL * 128; const int itc = ok[q] ? it : it0;
;             const int tok = itc >> 7, c = (itc & 127) * 4, h = c >> 6; const Tok tk = tok_decode(tok); tokv[q] = tok; cv[q] = c;
.LBB0_1736:
	s_or_b64 exec, exec, s[8:9]
	s_mov_b32 s38, s46
	s_mov_b32 s39, s2
	s_waitcnt lgkmcnt(0)
	s_barrier
	s_abs_i32 s6, s38
	v_cvt_f32_u32_e32 v0, s6
	s_sub_i32 s7, 0, s6
	v_rcp_iflag_f32_e32 v0, v0
	s_nop 0
	v_mul_f32_e32 v0, 0x4f7ffffe, v0
	v_cvt_u32_f32_e32 v0, v0
	s_nop 0
	v_readfirstlane_b32 s8, v0
	s_mul_i32 s7, s7, s8
	s_mul_hi_u32 s7, s8, s7
	s_add_i32 s8, s8, s7
	s_mul_hi_u32 s7, s8, 0x110
	s_mul_i32 s7, s7, s6
	s_sub_i32 s7, 0x110, s7
	s_sub_i32 s8, s7, s6
	s_cmp_ge_u32 s7, s6
	s_cselect_b32 s7, s8, s7
	s_sub_i32 s8, s7, s6
	s_cmp_ge_u32 s7, s6
	s_cselect_b32 s30, s8, s7
	s_cmp_lt_i32 s2, s30
	s_cbranch_scc1 .LBB0_1759
	s_load_dwordx2 s[12:13], s[0:1], 0x120
	s_load_dwordx2 s[10:11], s[0:1], 0x120
	s_load_dwordx2 s[8:9], s[0:1], 0x130
	s_load_dwordx2 s[14:15], s[0:1], 0x148
	s_load_dwordx2 s[16:17], s[0:1], 0x150
	s_load_dwordx2 s[26:27], s[0:1], 56
	s_load_dwordx2 s[28:29], s[0:1], 16
	s_load_dwordx2 s[18:19], s[0:1], 0x80
	s_sub_i32 s6, s2, s30
	s_load_dwordx2 s[20:21], s[0:1], 0x88
	s_waitcnt lgkmcnt(0)
	v_lshl_add_u32 v0, s6, 9, v166
	s_mov_b32 s6, 0x220000
	v_cmp_gt_i32_e32 vcc, s6, v0
	s_and_saveexec_b64 s[22:23], vcc
	s_cbranch_execz .LBB0_1758
	s_add_u32 s24, s10, 0x1100000
	s_addc_u32 s25, s11, 0
	s_add_u32 s26, s26, 0x2c00
	s_addc_u32 s27, s27, 0
	s_add_u32 s28, s28, 0xe0000
	s_addc_u32 s29, s29, 0
	s_lshl_b32 s10, s46, 10
	s_lshl_b32 s11, s30, 10
	s_lshl_b32 s7, s30, 9
	s_sub_i32 s33, s10, s11
	s_sub_i32 s40, s52, s11
	s_lshl_b32 s10, s46, 12
	s_lshl_b32 s11, s30, 12
	s_sub_i32 s7, 0, s7
	v_lshl_add_u32 v35, s2, 9, v166
	v_lshlrev_b32_e32 v44, 2, v0
	s_sub_i32 s41, s10, s11
	s_mov_b64 s[30:31], 0
	s_movk_i32 s42, 0x3fff
	s_movk_i32 s43, 0x4000
	v_mov_b32_e32 v45, 0x7ff
	v_mov_b32_e32 v21, 0
	s_movk_i32 s44, 0x2200
	v_mov_b64_e32 v[22:23], s[8:9]
	s_mov_b64 s[34:35], 0x800
	s_movk_i32 s45, 0x1c00
	v_mov_b32_e32 v46, 0x3a27c5ac
	s_mov_b32 s52, 0x800000
	s_mov_b32 s53, 0x21ffff
	s_branch .LBB0_1740

; #define KP(f) ((decltype(Params::f))karg_ptr<(int)offsetof(Params, f)>())
; #define PG8_STAGE(bufoff, gbase, voff) do { _Pragma("unroll") for (int _i = 0; _i < 2; ++_i) \
;         __builtin_amdgcn_global_load_lds((const unsigned*)((const char*)(gbase) + (voff)[_i]), (LAS unsigned*)(lds + (bufoff) + ldsw + _i * 8192), 16, 0, 0); } while (0)
;     ...
;     const int tid = tid_, wid = __builtin_amdgcn_readfirstlane(tid >> 6), lane = tid & 63, wr = wid >> 2, wc = wid & 3, fr = lane & 15, fq = lane >> 4;
;     const int K = g.K, nt = K / BK, lda = g.lda, ldb = g.ldb;
;     unsigned voffA[2], voffB[2];
; #pragma unroll
;     for (int i = 0; i < 2; ++i) { int R, C; stage_rc(tid * 16 + i * 8192, R, C); const int Rb = Epi::PERM ? ((R & ~31) + perm32(R & 31)) : R;
;         voffA[i] = (unsigned)(R * lda + C) * 2u; voffB[i] = (unsigned)(Rb * ldb + C) * 2u; }
;     const size_t kstep = (size_t)(BK * 2);
;     const size_t hA = (size_t)HALF * lda * 2, hB = (size_t)HALF * ldb * 2;
;     const size_t tA = 2 * hA, tB = 2 * hB;
;     const unsigned ldsw = (unsigned)wid * 1024u;
;     const int aoff = lds_byte(wr * 64 + fr, fq * 8), boff = lds_byte(wc * 32 + fr, fq * 8);
;     ...
;     Unit cur, nxt; int ui = 0;
;     if (!S.next(0, cur)) return;
;     ...
;     f32x4 acc[2][2][4][2];
; #pragma unroll
;     for (int a = 0; a < 2; ++a)
; #pragma unroll
;         for (int b = 0; b < 2; ++b)
; #pragma unroll
;             for (int m = 0; m < 4; ++m)
; #pragma unroll
;                 for (int n = 0; n < 2; ++n) acc[a][b][m][n] = (f32x4){0.f, 0.f, 0.f, 0.f};
;     bf16x8 At[4][2], B0[2][2], B1[2][2];
;     const char* cA = (const char*)g.A + (size_t)cur.pm * tA; const char* cB = (const char*)g.Bt + (size_t)cur.pn * tB;
;     PG8_A_READY(cur);
;     PG8_STAGE(PG8_SB(0, 0), cB, voffB); PG8_STAGE(PG8_SA(0, 0), cA, voffA); PG8_STAGE(PG8_SB(0, 1), cB + hB, voffB); PG8_STAGE(PG8_SA(0, 1), cA + hA, voffA);
;     if (wr == 1) PG8_BAR;
;     PG8_WAIT_V(4); PG8_BAR;
;     PG8_STAGE(PG8_SB(1, 0), cB + kstep, voffB); PG8_STAGE(PG8_SA(1, 0), cA + kstep, voffA); PG8_STAGE(PG8_SB(1, 1), cB + hB + kstep, voffB);
;     PG8_WAIT_V(6); PG8_BAR;
; __device__ __forceinline__ void run_phase(int type, int l, unsigned char* shm) {
;     ...
;         pg8::Gemm g{KP(z) + O_U, KP(BupT), T_ALL, DM, 512, DIN, 512}; S.init(T_ALL, DM, G, c);
;         EpiGate<0> E{KP(z)}; pg8::gemm_phase(lds, g, S, E);
.LBB0_1759:
	s_load_dwordx2 s[18:19], s[0:1], 0x130
	s_load_dwordx2 s[20:21], s[0:1], 0xf8
	s_load_dwordx2 s[22:23], s[0:1], 0x130
	s_waitcnt lgkmcnt(0)
	s_waitcnt vmcnt(4)
	v_mov_b32_e32 v8, v166
	s_cmpk_gt_i32 s39, 0x10f
	v_readfirstlane_b32 s34, v8
	s_cbranch_scc1 .LBB0_1773
	v_lshlrev_b32_e32 v0, 4, v8
	v_add_u32_e32 v1, 0x2000, v0
	s_waitcnt vmcnt(0)
	v_ashrrev_i32_e32 v2, 31, v1
	v_lshrrev_b32_e32 v2, 22, v2
	v_add_u32_e32 v2, v1, v2
	v_ashrrev_i32_e32 v9, 10, v2
	v_mul_i32_i24_e32 v2, 0x400, v9
	v_sub_u32_e32 v1, v1, v2
	v_lshrrev_b32_e32 v2, 4, v1
	v_bitop3_b32 v1, v2, v1, 32 bitop3:0x6c
	v_ashrrev_i32_e32 v2, 31, v1
	v_lshrrev_b32_e32 v2, 26, v2
	v_add_u32_e32 v2, v1, v2
	v_lshlrev_b32_e32 v3, 3, v9
	v_ashrrev_i32_e32 v10, 6, v2
	v_and_b32_e32 v3, -16, v3
	v_add_u32_e32 v3, v10, v3
	v_and_b32_e32 v4, 3, v10
	s_mov_b32 s6, 0x3fffe0
	v_lshrrev_b32_e32 v5, 2, v3
	v_lshlrev_b32_e32 v6, 1, v3
	v_and_b32_e32 v2, 0xc0, v2
	v_and_or_b32 v4, v3, s6, v4
	v_and_b32_e32 v5, 4, v5
	v_and_b32_e32 v6, 24, v6
	v_sub_u32_e32 v1, v1, v2
	v_mov_b32_e32 v2, 1
	v_or3_b32 v4, v4, v5, v6
	v_lshlrev_b32_e32 v5, 5, v9
	v_ashrrev_i16_sdwa v1, v2, sext(v1) dst_sel:DWORD dst_unused:UNUSED_PAD src0_sel:DWORD src1_sel:BYTE_0
	v_and_b32_e32 v11, 32, v5
	v_bfe_i32 v12, v1, 0, 16
	s_movk_i32 s10, 0x1100
	v_add_u32_e32 v1, v11, v12
	v_mul_lo_u32 v3, v3, s10
	v_lshlrev_b32_e32 v5, 1, v1
	v_add_lshl_u32 v130, v1, v3, 1
	v_bfe_i32 v1, v8, 27, 1
	v_lshrrev_b32_e32 v1, 22, v1
	v_add_u32_e32 v1, v0, v1
	v_and_b32_e32 v1, 0xfffffc00, v1
	v_sub_u32_e32 v0, v0, v1
	v_lshrrev_b32_e32 v1, 4, v0
	v_ashrrev_i32_e32 v3, 31, v8
	v_bitop3_b32 v0, v1, v0, 32 bitop3:0x6c
	v_lshrrev_b32_e32 v3, 26, v3
	v_ashrrev_i32_e32 v1, 31, v0
	v_add_u32_e32 v3, v8, v3
	v_lshrrev_b32_e32 v1, 26, v1
	v_ashrrev_i32_e32 v14, 6, v3
	v_add_u32_e32 v1, v0, v1
	v_lshlrev_b32_e32 v3, 3, v14
	v_ashrrev_i32_e32 v13, 6, v1
	v_and_b32_e32 v3, -16, v3
	v_lshl_add_u32 v128, v4, 10, v5
	v_add_u32_e32 v3, v13, v3
	v_and_b32_e32 v4, 3, v13
	s_ashr_i32 s36, s39, 31
	v_and_or_b32 v4, v3, s6, v4
	s_lshr_b32 s6, s36, 29
	s_add_i32 s6, s39, s6
	s_ashr_i32 s7, s34, 6
	s_ashr_i32 s8, s6, 3
	s_and_b32 s6, s6, -8
	s_ashr_i32 s9, s34, 8
	s_lshl_b32 s35, s7, 10
	s_sub_i32 s6, s39, s6
	s_cmp_lt_i32 s6, 0
	s_cselect_b32 s11, 35, 34
	s_mul_i32 s6, s11, s6
	s_add_i32 s6, s6, s8
	s_ashr_i32 s8, s6, 31
	v_lshrrev_b32_e32 v5, 2, v3
	v_lshlrev_b32_e32 v6, 1, v3
	v_and_b32_e32 v1, 0xc0, v1
	s_lshr_b32 s8, s8, 27
	v_and_b32_e32 v5, 4, v5
	v_and_b32_e32 v6, 24, v6
	v_sub_u32_e32 v0, v0, v1
	s_add_i32 s8, s6, s8
	v_or3_b32 v4, v4, v5, v6
	v_lshlrev_b32_e32 v5, 5, v14
	v_ashrrev_i16_sdwa v0, v2, sext(v0) dst_sel:DWORD dst_unused:UNUSED_PAD src0_sel:DWORD src1_sel:BYTE_0
	s_ashr_i32 s11, s8, 5
	v_and_b32_e32 v15, 32, v5
	v_bfe_i32 v16, v0, 0, 16
	s_lshl_b32 s11, s11, 3
	v_add_u32_e32 v0, v15, v16
	s_sub_i32 s12, 0x44, s11
	v_lshlrev_b32_e32 v1, 1, v0
	s_min_u32 s14, s12, 8
	s_andn2_b32 s8, s8, 31
	v_lshl_add_u32 v132, v4, 10, v1
	v_mul_lo_u32 v1, v3, s10
	s_sub_i32 s6, s6, s8
	v_cvt_f32_ubyte0_e32 v3, s14
	v_cvt_f32_i32_e32 v2, s6
	v_rcp_iflag_f32_e32 v4, v3
	v_add_lshl_u32 v134, v0, v1, 1
	s_ashr_i32 s8, s6, 30
	s_or_b32 s8, s8, 1
	v_mul_f32_e32 v0, v2, v4
	v_trunc_f32_e32 v0, v0
	v_fma_f32 v1, -v0, v3, v2
	v_cvt_i32_f32_e32 v0, v0
	v_cmp_ge_f32_e64 s[12:13], |v1|, v3
	s_and_b64 s[12:13], s[12:13], exec
	s_cselect_b32 s8, s8, 0
	v_readfirstlane_b32 s12, v0
	s_add_i32 s8, s12, s8
	s_mul_i32 s12, s8, s14
	s_sub_i32 s6, s6, s12
	s_sext_i32_i8 s6, s6
	s_bfe_i64 s[12:13], s[8:9], 0x80000
	s_add_i32 s6, s11, s6
	s_lshl_b64 s[12:13], s[12:13], 18
	s_add_u32 s14, s20, s12
	s_addc_u32 s15, s21, s13
	s_add_i32 s37, s35, 0
	s_add_i32 m0, s37, 0x10000
	s_mul_i32 s16, s6, 0x220000
	global_load_lds_dwordx4 v132, s[14:15]
	s_add_i32 m0, s37, 0x12000
	s_mul_hi_i32 s11, s6, 0x220000
	v_mov_b32_e32 v133, 0
	s_add_u32 s16, s18, s16
	s_addc_u32 s17, s19, s11
	v_mov_b32_e32 v135, v133
	s_mov_b64 s[24:25], 0xe00
	v_lshl_add_u64 v[0:1], s[16:17], 0, v[134:135]
	global_load_lds_dwordx4 v128, s[14:15]
	s_add_u32 s12, s16, 0xe00
	v_lshl_add_u64 v[2:3], v[0:1], 0, s[24:25]
	s_mov_b32 m0, s37
	v_mov_b32_e32 v131, v133
	s_addc_u32 s13, s17, 0
	global_load_lds_dwordx4 v[2:3], off
	v_lshl_add_u64 v[2:3], s[16:17], 0, v[130:131]
	s_add_i32 s40, s37, 0x2000
	v_lshl_add_u64 v[4:5], v[2:3], 0, s[24:25]
	s_mov_b32 m0, s40
	s_add_u32 s24, s14, 0x20000
	global_load_lds_dwordx4 v[4:5], off
	s_addc_u32 s25, s15, 0
	s_add_i32 m0, s37, 0x14000
	v_mov_b32_e32 v129, v133
	global_load_lds_dwordx4 v132, s[24:25]
	s_add_i32 m0, s37, 0x16000
	s_add_u32 s16, s16, 0x110e00
	s_addc_u32 s17, s17, 0
	s_add_i32 s41, s37, 0x4000
	global_load_lds_dwordx4 v128, s[24:25]
	s_mov_b32 m0, s41
	s_add_i32 s42, s37, 0x6000
	global_load_lds_dwordx4 v134, s[16:17]
	s_mov_b32 m0, s42
	s_mov_b32 s43, 0
	global_load_lds_dwordx4 v130, s[16:17]
	v_lshl_add_u64 v[4:5], s[14:15], 0, v[132:133]
	s_cmp_lg_u32 s9, 1
	v_lshl_add_u64 v[6:7], s[14:15], 0, v[128:129]
	s_cbranch_scc1 .LBB0_1762
	s_barrier

; #define KP(f) ((decltype(Params::f))karg_ptr<(int)offsetof(Params, f)>())
;     __device__ bool next(int i, Unit& u) const {
;         const long L = (long)i * G + c; if (L >= nwg) return false;
;         int wgid = (int)L; { const int q = nwg / NXCD, r = nwg % NXCD, xcd = wgid % NXCD, off = wgid / NXCD; wgid = (xcd < r ? xcd * (q + 1) : r * (q + 1) + (xcd - r) * q) + off; }
;         const int nig = WGM * nN, gid = wgid / nig, fm = gid * WGM, gsz = (nM - fm) < WGM ? (nM - fm) : WGM;
;         u.pm = fm + ((wgid % nig) % gsz); u.pn = (wgid % nig) / gsz; return true;
; __device__ __forceinline__ void run_phase(int type, int l, unsigned char* shm) {
;     ...
;         unsigned* rdy = KP(bar) + XCD_BAR_WORDS + 1024 + (2 + l) * (68 * 64); float* out = KP(out);
;         { pg8::Gemm g{KP(xb) + (size_t)T_ALL * 512, KP(AupT), T_P, DM, 512, 512, 512}; S.init(T_P, DM, G, c);
;           EpiMergePub E{KP(z), rdy, 0, 0}; pg8::gemm_phase(lds, g, S, E); }
.LBB0_1825:
	s_or_b64 exec, exec, s[8:9]
	s_mov_b32 s70, s46
	s_mov_b32 s60, s2
	s_waitcnt lgkmcnt(0)
	s_barrier
	s_load_dwordx2 s[26:27], s[0:1], 0x158
	s_load_dwordx2 s[24:25], s[0:1], 0xd8
	s_load_dwordx2 s[8:9], s[0:1], 0x120
	s_waitcnt lgkmcnt(0)
	s_add_u32 s28, s26, 0x11200
	s_load_dwordx2 s[34:35], s[0:1], 0x100
	s_addc_u32 s29, s27, 0
	s_load_dwordx2 s[36:37], s[0:1], 0x130
	s_waitcnt lgkmcnt(0)
	v_mov_b32_e32 v8, v166
	s_cmpk_lt_i32 s60, 0x100
	s_cselect_b64 s[30:31], -1, 0
	s_cmpk_gt_i32 s60, 0xff
	v_readfirstlane_b32 s56, v8
	s_cbranch_scc1 .LBB0_1848
	s_ashr_i32 s57, s60, 31
	s_lshr_b32 s6, s57, 29
	s_add_i32 s6, s60, s6
	s_and_b32 s7, s6, -8
	s_sub_i32 s7, s60, s7
	s_cmp_gt_i32 s7, -1
	s_cbranch_scc0 .LBB0_1828
	s_lshl_b32 s12, s7, 5
	s_cbranch_execz .LBB0_1829
	s_branch .LBB0_1830

; #define KP(f) ((decltype(Params::f))karg_ptr<(int)offsetof(Params, f)>())
;     __device__ bool next(int i, Unit& u) const {
;         const long L = (long)i * G + c; if (L >= nwg) return false;
;         int wgid = (int)L; { const int q = nwg / NXCD, r = nwg % NXCD, xcd = wgid % NXCD, off = wgid / NXCD; wgid = (xcd < r ? xcd * (q + 1) : r * (q + 1) + (xcd - r) * q) + off; }
;         const int nig = WGM * nN, gid = wgid / nig, fm = gid * WGM, gsz = (nM - fm) < WGM ? (nM - fm) : WGM;
;         u.pm = fm + ((wgid % nig) % gsz); u.pn = (wgid % nig) / gsz; return true;
; __device__ __forceinline__ void run_phase(int type, int l, unsigned char* shm) {
;     ...
;         { pg8::Gemm g{KP(xb) + (size_t)T_ALL * 512 + (size_t)T_P * 512, KP(AupT), T_ALL - T_P, DM, 512, 512, 512}; S.init(T_ALL - T_P, DM, G, c);
;           EpiMergePub E{KP(z), rdy, T_P, 64}; pg8::gemm_phase(lds, g, S, E); }
.LBB0_1848:
	s_load_dwordx2 s[8:9], s[0:1], 0x120
	s_load_dwordx2 s[18:19], s[0:1], 0x100
	s_load_dwordx2 s[34:35], s[0:1], 0x130
	s_waitcnt lgkmcnt(0)
	v_mov_b32_e32 v8, v166
	s_cmp_gt_i32 s60, 15
	v_readfirstlane_b32 s56, v8
	s_cbranch_scc1 .LBB0_1871
	s_ashr_i32 s57, s60, 31
	s_lshr_b32 s6, s57, 29
	s_add_i32 s6, s60, s6
	s_and_b32 s7, s6, -8
	s_sub_i32 s7, s60, s7
	s_cmp_gt_i32 s7, -1
	s_cbranch_scc0 .LBB0_1851
	s_lshl_b32 s12, s7, 1
	s_cbranch_execz .LBB0_1852
	s_branch .LBB0_1853

; #define KP(f) ((decltype(Params::f))karg_ptr<(int)offsetof(Params, f)>())
;     __device__ bool next(int i, Unit& u) const {
;         const long L = (long)i * G + c; if (L >= nwg) return false;
;         int wgid = (int)L; { const int q = nwg / NXCD, r = nwg % NXCD, xcd = wgid % NXCD, off = wgid / NXCD; wgid = (xcd < r ? xcd * (q + 1) : r * (q + 1) + (xcd - r) * q) + off; }
;         const int nig = WGM * nN, gid = wgid / nig, fm = gid * WGM, gsz = (nM - fm) < WGM ? (nM - fm) : WGM;
;         u.pm = fm + ((wgid % nig) % gsz); u.pn = (wgid % nig) / gsz; return true;
; __device__ __forceinline__ void run_phase(int type, int l, unsigned char* shm) {
;     ...
;         { pg8::Gemm g{KP(z), KP(WoT), T_P, DM, DM, DIN, DM}; S.init(T_P, DM, G, c);
;           EpiRes E{l == 0 ? KP(x_prompt) : out, nullptr, out, KP(xb), KP(ssq)}; pg8::gemm_phase(lds, g, S, E, rdy, 32u, 64); }
.LBB0_1871:
	s_load_dwordx2 s[16:17], s[0:1], 0x130
	s_load_dwordx2 s[18:19], s[0:1], 0x108
	s_load_dwordx2 s[20:21], s[0:1], 0x120
	s_load_dwordx2 s[22:23], s[0:1], 0x128
	s_waitcnt lgkmcnt(0)
	s_waitcnt vmcnt(0)
	v_mov_b32_e32 v10, v166
	v_cndmask_b32_e64 v0, 0, 1, s[30:31]
	v_cmp_ne_u32_e64 s[8:9], 1, v0
	s_andn2_b64 vcc, exec, s[30:31]
	v_readfirstlane_b32 s61, v10
	s_cbranch_vccnz .LBB0_1877
	s_ashr_i32 s6, s60, 31
	s_lshr_b32 s6, s6, 29
	s_add_i32 s12, s60, s6
	s_and_b32 s6, s12, -8
	s_sub_i32 s6, s60, s6
	s_cmp_gt_i32 s6, -1
	s_cbranch_scc0 .LBB0_1874
	s_lshl_b32 s7, s6, 5
	s_ashr_i32 s10, s12, 3
	s_cbranch_execz .LBB0_1875
	s_branch .LBB0_1876

; #define KP(f) ((decltype(Params::f))karg_ptr<(int)offsetof(Params, f)>())
;     int G = gridDim.x, c = ((int)blockIdx.x - cbase + (int)gridDim.x) % (int)gridDim.x; asm volatile("" : "+s"(G), "+s"(c));
;     const int Kq = Ktot >> 2;
;     pg8::StaticOrder S;
; #pragma unroll 1
;     for (int kq = 0; kq < 4; ++kq) {
;         pg8::Gemm g{A + (size_t)kq * Kq, Bt + (size_t)kq * Kq, 1024, DM, Kq, lda, Ktot};
;         S.init(1024, DM, G, (c - 16 * kq + G) % G);
;         EpiPartial E{part + (size_t)kq * 1024 * DM};
;         pg8::gemm_phase(lds, g, S, E, ready, need, npan);
; __device__ __forceinline__ void run_phase(int type, int l, unsigned char* shm) {
;     ...
;         sample_splitk(lds, KP(z) + (size_t)T_P * DIN, DIN, KP(WoT), DM, l == 0 ? KP(x_sample) : out + (size_t)T_P * DM, out + (size_t)T_P * DM, KP(xb) + (size_t)T_P * DM, KP(ssq) + (size_t)T_P * 16,
;                       (float*)KP(sc_a), KP(bar) + XCD_BAR_WORDS + (l * 2 + 0) * 256, G > 64 ? G - 64 : 0, rdy + 64 * 64, 32u, 4);
.LBB0_1941:
	s_load_dwordx2 s[6:7], s[0:1], 0x130
	s_waitcnt lgkmcnt(0)
	s_add_u32 s72, s6, 0x8800000
	s_addc_u32 s73, s7, 0
	s_max_i32 s6, s70, 64
	s_add_u32 s22, s26, 0x15200
	v_readlane_b32 s7, v230, 8
	s_addc_u32 s23, s27, 0
	s_sub_i32 s6, s7, s6
	s_ashr_i32 s7, s6, 31
	s_abs_i32 s6, s6
	v_readlane_b32 s8, v230, 9
	s_mul_hi_u32 s8, s6, s8
	s_mul_i32 s8, s8, s51
	s_sub_i32 s6, s6, s8
	s_sub_i32 s8, s6, s51
	s_cmp_ge_u32 s6, s51
	s_cselect_b32 s6, s8, s6
	s_sub_i32 s8, s6, s51
	s_load_dwordx2 s[20:21], s[0:1], 0x108
	s_cmp_ge_u32 s6, s51
	s_load_dwordx2 s[16:17], s[0:1], 0x120
	s_cselect_b32 s6, s8, s6
	s_load_dwordx2 s[14:15], s[0:1], 0x128
	s_xor_b32 s6, s6, s7
	s_load_dwordx2 s[12:13], s[0:1], 0x140
	s_sub_i32 s71, s6, s7
	s_mov_b32 s74, s46
	s_load_dwordx2 s[18:19], s[0:1], 0x158
	s_waitcnt lgkmcnt(0)
	s_abs_i32 s75, s74
	v_cvt_f32_u32_e32 v0, s75
	s_sub_i32 s6, 0, s75
	s_add_i32 s76, s74, s71
	s_ashr_i32 s77, s74, 31
	v_rcp_iflag_f32_e32 v0, v0
	s_mov_b32 s27, 0
	s_movk_i32 s81, 0x1100
	v_mov_b32_e32 v129, 0
	v_mul_f32_e32 v0, 0x4f7ffffe, v0
	v_cvt_u32_f32_e32 v0, v0
	s_mov_b64 s[28:29], 0x80
	v_mov_b32_e32 v138, 1
	s_mov_b32 s82, 0
	v_readfirstlane_b32 s7, v0
	s_mul_i32 s6, s6, s7
	s_mul_hi_u32 s6, s7, s6
	s_add_i32 s80, s7, s6
	s_branch .LBB0_1944

; #define KP(f) ((decltype(Params::f))karg_ptr<(int)offsetof(Params, f)>())
;     int tid_ = threadIdx.x; asm volatile("" : "+v"(tid_));
;     const int tid = tid_, ntn = N / 64, ntiles = (K / 64) * ntn, nwg = wgn > 0 ? wgn : (int)gridDim.x - wg0;
;     if ((int)blockIdx.x < wg0 || (int)blockIdx.x >= wg0 + nwg) return;
;     const int r = tid >> 4, c4 = (tid & 15) * 4, n = tid >> 3, k8 = (tid & 7) * 8;
;     int t = (int)blockIdx.x - wg0;
;     f32x4 v0, v1; float g0 = 1.f, g1 = 1.f;
;     if (t < ntiles) { const int k0 = (t / ntn) * 64, n0 = (t % ntn) * 64;
;         v0 = *(const f32x4*)(src + (size_t)(k0 + r) * N + n0 + c4); v1 = *(const f32x4*)(src + (size_t)(k0 + r + 32) * N + n0 + c4);
;         if (gain) { g0 = gain[k0 + r]; g1 = gain[k0 + r + 32]; } }
; __device__ __forceinline__ void run_phase(int type, int l, unsigned char* shm) {
;     ...
;         else { if (G >= 256) transpose_convert(KP(w_ff1) + (size_t)DM * DFF, DM, DFF, KP(norm2_g) + DM, KP(Wff1T), (float*)shm, 64, 128);
;                else transpose_convert(KP(w_ff1) + (size_t)DM * DFF, DM, DFF, KP(norm2_g) + DM, KP(Wff1T), (float*)shm); }
.LBB0_2010:
	s_load_dwordx2 s[12:13], s[0:1], 0xc0
	s_load_dwordx2 s[10:11], s[0:1], 0xb8
	s_load_dwordx2 s[8:9], s[0:1], 0x110
	s_waitcnt lgkmcnt(0)
	v_readlane_b32 s6, v230, 2
	v_readlane_b32 s7, v230, 3
	v_mov_b32_e32 v10, v166
	s_and_b64 vcc, exec, s[6:7]
	s_cbranch_vccnz .LBB0_2018
	s_cmpk_gt_u32 s2, 0x3ff
	s_cbranch_scc1 .LBB0_2018
	s_add_u32 s6, s12, 0x1000000
	s_addc_u32 s7, s13, 0
	s_add_u32 s10, s10, 0x1000
	v_ashrrev_i32_e32 v13, 4, v10
	s_addc_u32 s11, s11, 0
	s_and_b32 s12, s2, 0x3c0
	v_add_u32_e32 v14, s12, v13
	v_lshlrev_b32_e32 v0, 2, v10
	v_ashrrev_i32_e32 v15, 31, v14
	v_and_b32_e32 v22, 60, v0
	s_waitcnt lgkmcnt(0)
	v_lshlrev_b64 v[0:1], 14, v[14:15]
	s_lshl_b32 s12, s2, 8
	v_lshl_add_u64 v[0:1], s[6:7], 0, v[0:1]
	s_and_b32 s12, s12, 0x3f00
	s_mov_b32 s13, 0
	v_add_u32_e32 v18, 32, v14
	v_lshl_add_u64 v[0:1], v[0:1], 0, s[12:13]
	v_mov_b32_e32 v9, 0
	v_lshlrev_b32_e32 v8, 2, v22
	v_ashrrev_i32_e32 v19, 31, v18
	v_lshl_add_u64 v[16:17], v[0:1], 0, v[8:9]
	v_lshlrev_b64 v[0:1], 14, v[18:19]
	v_lshl_add_u64 v[0:1], s[6:7], 0, v[0:1]
	v_lshl_add_u64 v[0:1], v[0:1], 0, s[12:13]
	v_lshl_add_u64 v[20:21], v[0:1], 0, v[8:9]
	global_load_dwordx4 v[0:3], v[16:17], off
	global_load_dwordx4 v[4:7], v[20:21], off
	v_lshl_add_u64 v[16:17], v[18:19], 2, s[10:11]
	v_lshl_add_u64 v[18:19], v[14:15], 2, s[10:11]
	global_load_dword v12, v[18:19], off
	global_load_dword v14, v[16:17], off
	v_ashrrev_i32_e32 v15, 3, v10
	v_lshlrev_b32_e32 v10, 3, v10
	s_movk_i32 s12, 0x104
	v_and_b32_e32 v24, 56, v10
	v_mul_lo_u32 v11, v13, s12
	v_add3_u32 v16, 0, v8, v11
	v_add3_u32 v8, 0, v11, v8
	v_mul_u32_u24_e32 v11, 0x41, v24
	v_lshlrev_b32_e32 v10, 2, v15
	v_lshlrev_b32_e32 v11, 2, v11
	s_lshl_b32 s17, s2, 6
	v_add3_u32 v17, 0, v10, v11
	v_add3_u32 v18, 0, v11, v10
	s_lshl_b32 s16, s46, 6
	v_add_u32_e32 v19, 0x2080, v8
	v_add_u32_e32 v20, 0x2088, v8
	v_lshlrev_b32_e32 v10, 2, v22
	v_lshlrev_b32_e32 v8, 1, v24
	s_mov_b32 s18, s2
	s_branch .LBB0_2014

; #define KP(f) ((decltype(Params::f))karg_ptr<(int)offsetof(Params, f)>())
;     int tid_ = threadIdx.x; asm volatile("" : "+v"(tid_));
;     const int tid = tid_, ntn = N / 64, ntiles = (K / 64) * ntn, nwg = wgn > 0 ? wgn : (int)gridDim.x - wg0;
;     if ((int)blockIdx.x < wg0 || (int)blockIdx.x >= wg0 + nwg) return;
;     const int r = tid >> 4, c4 = (tid & 15) * 4, n = tid >> 3, k8 = (tid & 7) * 8;
;     int t = (int)blockIdx.x - wg0;
;     f32x4 v0, v1; float g0 = 1.f, g1 = 1.f;
;     if (t < ntiles) { const int k0 = (t / ntn) * 64, n0 = (t % ntn) * 64;
;         v0 = *(const f32x4*)(src + (size_t)(k0 + r) * N + n0 + c4); v1 = *(const f32x4*)(src + (size_t)(k0 + r + 32) * N + n0 + c4);
;         if (gain) { g0 = gain[k0 + r]; g1 = gain[k0 + r + 32]; } }
; __device__ __forceinline__ void run_phase(int type, int l, unsigned char* shm) {
;     ...
;         else { if (G >= 256) transpose_convert(KP(w_ff1) + (size_t)DM * DFF, DM, DFF, KP(norm2_g) + DM, KP(Wff1T), (float*)shm, 64, 128);
.LBB0_2026:
	s_load_dwordx2 s[8:9], s[0:1], 0xc0
	s_load_dwordx2 s[10:11], s[0:1], 0xb8
	s_load_dwordx2 s[6:7], s[0:1], 0x110
	s_waitcnt lgkmcnt(0)
	s_sub_i32 s16, s2, 64
	v_mov_b32_e32 v10, v166
	s_cmpk_gt_u32 s16, 0x7f
	s_cbranch_scc1 .LBB0_2031
	s_add_u32 s8, s8, 0x1000000
	s_addc_u32 s9, s9, 0
	s_add_u32 s10, s10, 0x1000
	s_addc_u32 s11, s11, 0
	v_ashrrev_i32_e32 v13, 4, v10
	s_and_b32 s12, s16, 64
	s_add_i32 s13, s2, 0xff80
	s_cmp_lt_u32 s16, 64
	s_waitcnt vmcnt(0)
	v_add_u32_e32 v14, s12, v13
	v_lshlrev_b32_e32 v0, 2, v10
	s_cselect_b32 s13, s16, s13
	v_ashrrev_i32_e32 v15, 31, v14
	v_and_b32_e32 v22, 60, v0
	s_waitcnt lgkmcnt(0)
	v_lshlrev_b64 v[0:1], 14, v[14:15]
	s_lshl_b32 s12, s13, 8
	v_lshl_add_u64 v[0:1], s[8:9], 0, v[0:1]
	s_and_b32 s12, s12, 0xffff00
	s_mov_b32 s13, 0
	v_add_u32_e32 v18, 32, v14
	v_lshl_add_u64 v[0:1], v[0:1], 0, s[12:13]
	v_mov_b32_e32 v9, 0
	v_lshlrev_b32_e32 v8, 2, v22
	v_ashrrev_i32_e32 v19, 31, v18
	v_lshl_add_u64 v[16:17], v[0:1], 0, v[8:9]
	v_lshlrev_b64 v[0:1], 14, v[18:19]
	v_lshl_add_u64 v[0:1], s[8:9], 0, v[0:1]
	v_lshl_add_u64 v[0:1], v[0:1], 0, s[12:13]
	v_lshl_add_u64 v[20:21], v[0:1], 0, v[8:9]
	global_load_dwordx4 v[0:3], v[16:17], off
	global_load_dwordx4 v[4:7], v[20:21], off
	v_lshl_add_u64 v[16:17], v[18:19], 2, s[10:11]
	v_lshl_add_u64 v[18:19], v[14:15], 2, s[10:11]
	global_load_dword v12, v[18:19], off
	global_load_dword v14, v[16:17], off
	v_ashrrev_i32_e32 v15, 3, v10
	v_lshlrev_b32_e32 v10, 3, v10
	s_movk_i32 s12, 0x104
	v_and_b32_e32 v24, 56, v10
	v_mul_lo_u32 v11, v13, s12
	v_add3_u32 v16, 0, v8, v11
	v_add3_u32 v8, 0, v11, v8
	v_mul_u32_u24_e32 v11, 0x41, v24
	v_lshlrev_b32_e32 v10, 2, v15
	v_lshlrev_b32_e32 v11, 2, v11
	s_lshl_b32 s12, s2, 6
	v_add3_u32 v17, 0, v10, v11
	v_add3_u32 v18, 0, v11, v10
	s_add_i32 s17, s12, 0xfffff000
	v_add_u32_e32 v19, 0x2080, v8
	v_add_u32_e32 v20, 0x2088, v8
	v_lshlrev_b32_e32 v10, 2, v22
	v_lshlrev_b32_e32 v8, 1, v24
	s_branch .LBB0_2029

; #define KP(f) ((decltype(Params::f))karg_ptr<(int)offsetof(Params, f)>())
;     __device__ bool next(int i, Unit& u) const {
;         const long L = (long)i * G + c; if (L >= nwg) return false;
;         int wgid = (int)L; { const int q = nwg / NXCD, r = nwg % NXCD, xcd = wgid % NXCD, off = wgid / NXCD; wgid = (xcd < r ? xcd * (q + 1) : r * (q + 1) + (xcd - r) * q) + off; }
;         const int nig = WGM * nN, gid = wgid / nig, fm = gid * WGM, gsz = (nM - fm) < WGM ? (nM - fm) : WGM;
;         u.pm = fm + ((wgid % nig) % gsz); u.pn = (wgid % nig) / gsz; return true;
; __device__ __forceinline__ void run_phase(int type, int l, unsigned char* shm) {
;     ...
;         unsigned* rdy = KP(bar) + XCD_BAR_WORDS + 1024 + l * (68 * 64); float* out = KP(out);
;         { pg8::Gemm g{KP(xb), KP(Wff1T), T_P, DFF, DM, DM, DM}; S.init(T_P, DFF, G, c);
;           EpiFF1Pub E{KP(z), KP(ssq), rdy, 0, 0}; pg8::gemm_phase(lds, g, S, E); }
.LBB0_2083:
	s_or_b64 exec, exec, s[6:7]
	s_mov_b32 s64, s46
	s_mov_b32 s65, s2
	s_waitcnt lgkmcnt(0)
	s_barrier
	s_load_dwordx2 s[18:19], s[0:1], 0x158
	s_load_dwordx2 s[16:17], s[0:1], 0xd8
	s_load_dwordx2 s[10:11], s[0:1], 0x120
	s_load_dwordx2 s[20:21], s[0:1], 0x110
	s_load_dwordx2 s[12:13], s[0:1], 0x130
	s_waitcnt lgkmcnt(0)
	s_add_u32 s66, s18, 0x8a00
	s_load_dwordx2 s[22:23], s[0:1], 0x128
	s_waitcnt lgkmcnt(0)
	s_addc_u32 s67, s19, 0
	v_mov_b32_e32 v8, v166
	s_cmpk_gt_i32 s65, 0x3ff
	v_readfirstlane_b32 s42, v8
	s_cbranch_scc1 .LBB0_2106
	s_ashr_i32 s43, s65, 31
	s_lshr_b32 s6, s43, 29
	s_add_i32 s8, s65, s6
	s_and_b32 s6, s8, -8
	s_sub_i32 s14, s65, s6
	s_cmp_gt_i32 s14, -1
	s_cbranch_scc0 .LBB0_2086
	s_lshl_b32 s9, s14, 7
	s_cbranch_execz .LBB0_2087
	s_branch .LBB0_2088

; #define KP(f) ((decltype(Params::f))karg_ptr<(int)offsetof(Params, f)>())
;     __device__ bool next(int i, Unit& u) const {
;         const long L = (long)i * G + c; if (L >= nwg) return false;
;         int wgid = (int)L; { const int q = nwg / NXCD, r = nwg % NXCD, xcd = wgid % NXCD, off = wgid / NXCD; wgid = (xcd < r ? xcd * (q + 1) : r * (q + 1) + (xcd - r) * q) + off; }
;         const int nig = WGM * nN, gid = wgid / nig, fm = gid * WGM, gsz = (nM - fm) < WGM ? (nM - fm) : WGM;
;         u.pm = fm + ((wgid % nig) % gsz); u.pn = (wgid % nig) / gsz; return true;
; __device__ __forceinline__ void run_phase(int type, int l, unsigned char* shm) {
;     ...
;         { pg8::Gemm g{KP(xb) + (size_t)T_P * DM, KP(Wff1T), T_ALL - T_P, DFF, DM, DM, DM}; S.init(T_ALL - T_P, DFF, G, c);
;           EpiFF1Pub E{KP(z), KP(ssq), rdy, T_P, 64}; pg8::gemm_phase(lds, g, S, E); }
.LBB0_2106:
	s_load_dwordx2 s[6:7], s[0:1], 0x120
	s_load_dwordx2 s[12:13], s[0:1], 0x110
	s_load_dwordx2 s[8:9], s[0:1], 0x130
	s_load_dwordx2 s[14:15], s[0:1], 0x128
	s_waitcnt lgkmcnt(0)
	v_mov_b32_e32 v8, v166
	s_cmp_gt_i32 s65, 63
	v_readfirstlane_b32 s40, v8
	s_cbranch_scc1 .LBB0_2129
	s_ashr_i32 s41, s65, 31
	s_lshr_b32 s10, s41, 29
	s_add_i32 s21, s65, s10
	s_and_b32 s10, s21, -8
	s_sub_i32 s22, s65, s10
	s_cmp_gt_i32 s22, -1
	s_cbranch_scc0 .LBB0_2109
	s_lshl_b32 s20, s22, 3
	s_cbranch_execz .LBB0_2110
	s_branch .LBB0_2111

; #define KP(f) ((decltype(Params::f))karg_ptr<(int)offsetof(Params, f)>())
;     __device__ bool next(int i, Unit& u) const {
;         const long L = (long)i * G + c; if (L >= nwg) return false;
;         int wgid = (int)L; { const int q = nwg / NXCD, r = nwg % NXCD, xcd = wgid % NXCD, off = wgid / NXCD; wgid = (xcd < r ? xcd * (q + 1) : r * (q + 1) + (xcd - r) * q) + off; }
;         const int nig = WGM * nN, gid = wgid / nig, fm = gid * WGM, gsz = (nM - fm) < WGM ? (nM - fm) : WGM;
;         u.pm = fm + ((wgid % nig) % gsz); u.pn = (wgid % nig) / gsz; return true;
; __device__ __forceinline__ void run_phase(int type, int l, unsigned char* shm) {
;     ...
;         { pg8::Gemm g{KP(z), KP(Wff2T), T_P, DM, DFF, DFF, DFF}; S.init(T_P, DM, G, c);
;           EpiRes E{out, nullptr, out, KP(xb), KP(ssq)}; pg8::gemm_phase(lds, g, S, E, rdy, 128u); }
.LBB0_2129:
	s_load_dwordx2 s[14:15], s[0:1], 0x130
	s_load_dwordx2 s[20:21], s[0:1], 0x118
	s_load_dwordx2 s[22:23], s[0:1], 0x120
	s_load_dwordx2 s[24:25], s[0:1], 0x128
	s_waitcnt lgkmcnt(0)
	v_mov_b32_e32 v8, v166
	s_cmpk_lt_i32 s65, 0x100
	s_cselect_b64 s[6:7], -1, 0
	s_cmpk_gt_i32 s65, 0xff
	v_readfirstlane_b32 s68, v8
	s_cbranch_scc1 .LBB0_2135
	s_ashr_i32 s8, s65, 31
	s_lshr_b32 s8, s8, 29
	s_add_i32 s12, s65, s8
	s_and_b32 s8, s12, -8
	s_sub_i32 s10, s65, s8
	s_cmp_gt_i32 s10, -1
	s_cbranch_scc0 .LBB0_2132
	s_lshl_b32 s11, s10, 5
	s_ashr_i32 s8, s12, 3
	s_cbranch_execz .LBB0_2133
	s_branch .LBB0_2134

; #define KP(f) ((decltype(Params::f))karg_ptr<(int)offsetof(Params, f)>())
;     int G = gridDim.x, c = ((int)blockIdx.x - cbase + (int)gridDim.x) % (int)gridDim.x; asm volatile("" : "+s"(G), "+s"(c));
;     const int Kq = Ktot >> 2;
;     pg8::StaticOrder S;
; #pragma unroll 1
;     for (int kq = 0; kq < 4; ++kq) {
;         pg8::Gemm g{A + (size_t)kq * Kq, Bt + (size_t)kq * Kq, 1024, DM, Kq, lda, Ktot};
;         S.init(1024, DM, G, (c - 16 * kq + G) % G);
;         EpiPartial E{part + (size_t)kq * 1024 * DM};
;         pg8::gemm_phase(lds, g, S, E, ready, need, npan);
; __device__ __forceinline__ void run_phase(int type, int l, unsigned char* shm) {
;     ...
;         sample_splitk(lds, KP(z) + (size_t)T_P * DFF, DFF, KP(Wff2T), DFF, out + (size_t)T_P * DM, out + (size_t)T_P * DM, KP(xb) + (size_t)T_P * DM, KP(ssq) + (size_t)T_P * 16,
;                       (float*)KP(sc_a), KP(bar) + XCD_BAR_WORDS + (l * 2 + 1) * 256, G > 64 ? G - 64 : 0, rdy + 64 * 64, 128u);
.LBB0_2197:
	s_load_dwordx2 s[6:7], s[0:1], 0x130
	s_waitcnt lgkmcnt(0)
	s_add_u32 s66, s6, 0x8000000
	s_addc_u32 s67, s7, 0
	s_max_i32 s6, s64, 64
	s_add_u32 s68, s18, 0xca00
	v_readlane_b32 s7, v230, 8
	s_addc_u32 s69, s19, 0
	s_sub_i32 s6, s7, s6
	s_ashr_i32 s7, s6, 31
	s_abs_i32 s6, s6
	v_readlane_b32 s18, v230, 9
	s_mul_hi_u32 s18, s6, s18
	s_mul_i32 s18, s18, s51
	s_sub_i32 s6, s6, s18
	s_sub_i32 s18, s6, s51
	s_cmp_ge_u32 s6, s51
	s_cselect_b32 s6, s18, s6
	s_sub_i32 s18, s6, s51
	s_load_dwordx2 s[20:21], s[0:1], 0x118
	s_cmp_ge_u32 s6, s51
	s_load_dwordx2 s[12:13], s[0:1], 0x120
	s_cselect_b32 s6, s18, s6
	s_load_dwordx2 s[8:9], s[0:1], 0x128
	s_xor_b32 s6, s6, s7
	s_load_dwordx2 s[10:11], s[0:1], 0x140
	s_sub_i32 s51, s6, s7
	s_mov_b32 s70, s46
	s_load_dwordx2 s[14:15], s[0:1], 0x158
	s_waitcnt lgkmcnt(0)
	s_abs_i32 s71, s70
	v_cvt_f32_u32_e32 v0, s71
	s_sub_i32 s6, 0, s71
	s_add_i32 s72, s70, s51
	s_ashr_i32 s73, s70, 31
	v_rcp_iflag_f32_e32 v0, v0
	s_mov_b32 s19, 0
	v_mov_b32_e32 v129, 0
	s_mov_b64 s[22:23], 0x80
	v_mul_f32_e32 v0, 0x4f7ffffe, v0
	v_cvt_u32_f32_e32 v0, v0
	s_mov_b32 s75, 0x90000
	s_mov_b64 s[24:25], 0xa0000
	s_mov_b32 s76, 0xa0000
	v_readfirstlane_b32 s7, v0
	s_mul_i32 s6, s6, s7
	s_mul_hi_u32 s6, s7, s6
	s_add_i32 s74, s7, s6
	s_mov_b64 s[26:27], 0xb0000
	v_mov_b32_e32 v132, 1
	s_mov_b32 s77, 0
	s_branch .LBB0_2200

; #define KP(f) ((decltype(Params::f))karg_ptr<(int)offsetof(Params, f)>())
; __device__ __forceinline__ float row_rstd(const float* ssq, int row) {
;     const f32x4* p = (const f32x4*)(ssq + (size_t)row * 16);
;     const f32x4 a = p[0], b = p[1], c = p[2], d = p[3];
;     const float s = ((a[0] + a[1]) + (a[2] + a[3])) + ((b[0] + b[1]) + (b[2] + b[3])) + ((c[0] + c[1]) + (c[2] + c[3])) + ((d[0] + d[1]) + (d[2] + d[3]));
;     return rsqrtf(s * (1.0f / 1024.0f) + 1e-6f);
; }
; __device__ void phase_final() {
;     float* out = KP(out); const float* ssq = KP(ssq); const float* fg = KP(final_g);
;     const int lane = threadIdx.x & 63, gw = blockIdx.x * 8 + (threadIdx.x >> 6), nw = gridDim.x * 8;
;     for (int row = gw; row < T_ALL; row += nw) {
;         const float rs = row_rstd(ssq, row);
;         float* xr = out + (size_t)row * DM;
; #pragma unroll
;         for (int i = 0; i < 4; ++i) { const int c = i * 256 + lane * 4; const f32x4 v = *(const f32x4*)(xr + c); const f32x4 g = *(const f32x4*)(fg + c);
;             *(f32x4*)(xr + c) = v * rs * g; }
;     }
.LBB0_2319:
	s_or_b64 exec, exec, s[6:7]
	s_waitcnt lgkmcnt(0)
	s_barrier
	v_readlane_b32 s8, v230, 4
	s_load_dwordx2 s[2:3], s[0:1], 0xd8
	s_load_dwordx2 s[4:5], s[0:1], 0x128
	s_load_dwordx2 s[0:1], s[0:1], 0xd0
	s_waitcnt lgkmcnt(0)
	v_readlane_b32 s9, v230, 5
	s_and_saveexec_b64 s[6:7], s[8:9]
	s_cbranch_execz .LBB0_2322
	v_lshlrev_b32_e32 v0, 4, v166
	v_lshlrev_b64 v[2:3], 6, v[144:145]
	v_lshlrev_b64 v[4:5], 12, v[144:145]
	v_and_b32_e32 v0, 0x3f0, v0
	v_mov_b32_e32 v1, 0
	v_lshl_add_u64 v[2:3], s[4:5], 0, v[2:3]
	s_ashr_i32 s51, s50, 31
	v_lshl_or_b32 v4, v167, 4, v4
	v_lshl_add_u64 v[0:1], s[0:1], 0, v[0:1]
	v_lshl_add_u64 v[2:3], v[2:3], 0, 32
	s_lshl_b64 s[0:1], s[50:51], 6
	v_lshl_add_u64 v[4:5], s[2:3], 0, v[4:5]
	s_lshl_b64 s[2:3], s[50:51], 12
	s_mov_b64 s[4:5], 0
	v_mov_b32_e32 v6, 0x358637bd
	s_mov_b32 s6, 0x800000
	s_movk_i32 s7, 0x43ff
	global_load_dwordx4 v[40:43], v[0:1], off
	global_load_dwordx4 v[44:47], v[0:1], off offset:1024
	global_load_dwordx4 v[48:51], v[0:1], off offset:2048
	global_load_dwordx4 v[52:55], v[0:1], off offset:3072
	v_mov_b64_e32 v[92:93], v[4:5]
	global_load_dwordx4 v[8:11], v[2:3], off offset:-32
	global_load_dwordx4 v[12:15], v[2:3], off offset:-16
	global_load_dwordx4 v[16:19], v[2:3], off
	global_load_dwordx4 v[20:23], v[2:3], off offset:16
	global_load_dwordx4 v[24:27], v[4:5], off
	global_load_dwordx4 v[28:31], v[4:5], off offset:1024
	global_load_dwordx4 v[32:35], v[4:5], off offset:2048
	global_load_dwordx4 v[36:39], v[4:5], off offset:3072
	v_add_u32_e32 v144, s50, v144
	v_lshl_add_u64 v[2:3], v[2:3], 0, s[0:1]
	v_lshl_add_u64 v[4:5], v[4:5], 0, s[2:3]
	v_cmp_ge_i32_e32 vcc, s7, v144
	s_cbranch_vccz .Lfin_lastA
	v_mov_b64_e32 v[94:95], v[4:5]
	global_load_dwordx4 v[56:59], v[2:3], off offset:-32
	global_load_dwordx4 v[60:63], v[2:3], off offset:-16
	global_load_dwordx4 v[64:67], v[2:3], off
	global_load_dwordx4 v[68:71], v[2:3], off offset:16
	global_load_dwordx4 v[72:75], v[4:5], off
	global_load_dwordx4 v[76:79], v[4:5], off offset:1024
	global_load_dwordx4 v[80:83], v[4:5], off offset:2048
	global_load_dwordx4 v[84:87], v[4:5], off offset:3072
	s_waitcnt vmcnt(8)
	v_add_f32_e32 v96, v8, v9
	v_add_f32_e32 v97, v10, v11
	v_add_f32_e32 v98, v12, v13
	v_add_f32_e32 v99, v14, v15
	v_add_f32_e32 v100, v16, v17
	v_add_f32_e32 v101, v18, v19
	v_add_f32_e32 v102, v20, v21
	v_add_f32_e32 v103, v22, v23
	v_add_f32_e32 v96, v96, v97
	v_add_f32_e32 v98, v98, v99
	v_add_f32_e32 v100, v100, v101
	v_add_f32_e32 v102, v102, v103
	v_add_f32_e32 v96, v96, v98
	v_add_f32_e32 v96, v96, v100
	v_add_f32_e32 v96, v96, v102
	v_fmamk_f32 v96, v96, 0x3a800000, v6
	v_mul_f32_e32 v97, 0x4b800000, v96
	v_cmp_gt_f32_e32 vcc, s6, v96
	s_nop 1
	v_cndmask_b32_e32 v96, v96, v97, vcc
	v_rsq_f32_e32 v96, v96
	s_nop 0
	v_mul_f32_e32 v97, 0x45800000, v96
	v_cndmask_b32_e32 v90, v96, v97, vcc
	v_pk_mul_f32 v[24:25], v[24:25], v[90:91] op_sel_hi:[1,0]
	v_pk_mul_f32 v[26:27], v[26:27], v[90:91] op_sel_hi:[1,0]
	v_pk_mul_f32 v[24:25], v[40:41], v[24:25]
	v_pk_mul_f32 v[26:27], v[42:43], v[26:27]
	global_store_dwordx4 v[92:93], v[24:27], off
	v_pk_mul_f32 v[28:29], v[28:29], v[90:91] op_sel_hi:[1,0]
	v_pk_mul_f32 v[30:31], v[30:31], v[90:91] op_sel_hi:[1,0]
	v_pk_mul_f32 v[28:29], v[44:45], v[28:29]
	v_pk_mul_f32 v[30:31], v[46:47], v[30:31]
	global_store_dwordx4 v[92:93], v[28:31], off offset:1024
	v_pk_mul_f32 v[32:33], v[32:33], v[90:91] op_sel_hi:[1,0]
	v_pk_mul_f32 v[34:35], v[34:35], v[90:91] op_sel_hi:[1,0]
	v_pk_mul_f32 v[32:33], v[48:49], v[32:33]
	v_pk_mul_f32 v[34:35], v[50:51], v[34:35]
	global_store_dwordx4 v[92:93], v[32:35], off offset:2048
	v_pk_mul_f32 v[36:37], v[36:37], v[90:91] op_sel_hi:[1,0]
	v_pk_mul_f32 v[38:39], v[38:39], v[90:91] op_sel_hi:[1,0]
	v_pk_mul_f32 v[36:37], v[52:53], v[36:37]
	v_pk_mul_f32 v[38:39], v[54:55], v[38:39]
	global_store_dwordx4 v[92:93], v[36:39], off offset:3072
